# cmlp in-proj epilogue row-scale loads hoisted; out-proj fused epilogue second-pass residual reloads software-pipelined (8 in flight) on top of previous version
# speedup vs baseline: 1.0048x; 1.0048x over previous
;     DI void operator()(const f32x4 (&acc)[2][2][4][2], const Unit& u, int wr, int wc, int fr, int fq) const {
;         asm volatile("" : "+v"(fr), "+v"(fq));
;         const int pn = u.pn; const bool isv = pn >= 8;
;         bf16* base = isv ? VB : U; const int colt = (isv ? pn - 8 : pn) * 256 + 32 * wc + 8 * fq;
; #pragma unroll
;         for (int ai = 0; ai < 2; ++ai)
; #pragma unroll
;             for (int m = 0; m < 4; ++m) {
;                 const int r = u.pm * BM + ai * HALF + wr * 64 + m * 16 + fr; float s = 0.f, q = 0.f; const float rs = RS[r];
; #pragma unroll
;                 for (int bj = 0; bj < 2; ++bj) { const f32x4 a0 = acc[ai][bj][m][0] * rs, a1 = acc[ai][bj][m][1] * rs;
;                     const f32x2 g0 = gelu_pk((f32x2){a0[0], a0[1]}), g1 = gelu_pk((f32x2){a0[2], a0[3]}), g2 = gelu_pk((f32x2){a1[0], a1[1]}), g3 = gelu_pk((f32x2){a1[2], a1[3]});
.LBB0_224:
	s_add_i32 s23, s33, -8
	s_cmp_gt_i32 s33, 7
	s_cselect_b64 s[28:29], -1, 0
	s_and_b64 s[0:1], s[28:29], exec
	s_mov_b32 s0, 0x1fe00000
	s_cselect_b32 s0, s0, 0x1de00000
	s_cselect_b32 s25, s23, s33
	s_add_u32 s4, s6, s0
	v_mov_b32_e32 v138, v148
	v_mov_b32_e32 v142, v149
	s_addc_u32 s5, s7, 0
	s_lshl_b32 s0, s45, 8
	s_add_i32 s0, s0, s40
	v_add_u32_e32 v138, s0, v138
	v_ashrrev_i32_e32 v139, 31, v138
	v_lshl_add_u64 v[140:141], v[138:139], 2, s[14:15]
	global_load_dword v146, v[140:141], off
	global_load_dword v200, v[140:141], off offset:64
	global_load_dword v201, v[140:141], off offset:128
	global_load_dword v202, v[140:141], off offset:192
	global_load_dword v203, v[140:141], off offset:512
	global_load_dword v204, v[140:141], off offset:576
	global_load_dword v205, v[140:141], off offset:640
	global_load_dword v206, v[140:141], off offset:704
	v_mov_b64_e32 v[144:145], s[80:81]
	s_mov_b32 s48, 0xbe11a98e
	s_mov_b32 s50, 0x3e027906
	s_mov_b32 s52, 0xbf38aa3b
	s_lshl_b32 s25, s25, 8
	s_or_b32 s25, s25, s41
	v_lshl_add_u32 v140, v142, 3, s25
	v_ashrrev_i32_e32 v141, 31, v140
	v_cmp_eq_u32_e64 s[0:1], 0, v142
	v_lshl_add_u64 v[140:141], v[140:141], 1, s[4:5]
	v_lshlrev_b64 v[142:143], 12, v[138:139]
	v_lshl_add_u64 v[142:143], v[140:141], 0, v[142:143]
	s_lshl_b32 s23, s23, 2
	s_or_b32 s72, s23, s39
	s_cmp_lt_i32 s33, 8
	s_waitcnt vmcnt(0)
	v_pk_mul_f32 v[126:127], v[126:127], v[146:147] op_sel_hi:[1,0]
	s_nop 0
	v_and_b32_e32 v171, 0x7fffffff, v127
	v_and_b32_e32 v170, 0x7fffffff, v126
	v_pk_fma_f32 v[170:171], v[170:171], s[76:77], 1.0 op_sel_hi:[1,0,0]
	v_pk_mul_f32 v[124:125], v[124:125], v[146:147] op_sel_hi:[1,0]
	v_rcp_f32_e32 v170, v170
	v_rcp_f32_e32 v171, v171
	v_pk_mul_f32 v[164:165], v[120:121], v[146:147] op_sel_hi:[1,0]
	v_pk_mul_f32 v[116:117], v[116:117], v[146:147] op_sel_hi:[1,0]
	v_and_b32_e32 v121, 0x7fffffff, v125
	v_and_b32_e32 v120, 0x7fffffff, v124
	v_and_b32_e32 v181, 0x7fffffff, v117
	v_and_b32_e32 v180, 0x7fffffff, v116
	v_pk_fma_f32 v[120:121], v[120:121], s[76:77], 1.0 op_sel_hi:[1,0,0]
	v_pk_fma_f32 v[180:181], v[180:181], s[76:77], 1.0 op_sel_hi:[1,0,0]
	v_rcp_f32_e32 v120, v120
	v_rcp_f32_e32 v121, v121
	v_pk_fma_f32 v[184:185], v[170:171], s[78:79], v[144:145] op_sel_hi:[1,0,0]
	v_rcp_f32_e32 v180, v180
	v_rcp_f32_e32 v181, v181
	v_pk_fma_f32 v[184:185], v[170:171], v[184:185], s[96:97] op_sel_hi:[1,1,0]
	v_pk_fma_f32 v[182:183], v[120:121], s[78:79], v[144:145] op_sel_hi:[1,0,0]
	v_pk_fma_f32 v[184:185], v[170:171], v[184:185], s[48:49] op_sel_hi:[1,1,0]
	v_and_b32_e32 v173, 0x7fffffff, v165
	v_pk_fma_f32 v[184:185], v[170:171], v[184:185], s[50:51] op_sel_hi:[1,1,0]
	v_and_b32_e32 v172, 0x7fffffff, v164
	v_pk_fma_f32 v[182:183], v[120:121], v[182:183], s[96:97] op_sel_hi:[1,1,0]
	v_pk_mul_f32 v[170:171], v[170:171], v[184:185]
	v_pk_mul_f32 v[184:185], v[112:113], v[146:147] op_sel_hi:[1,0]
	v_pk_fma_f32 v[112:113], v[180:181], s[78:79], v[144:145] op_sel_hi:[1,0,0]
	v_pk_fma_f32 v[172:173], v[172:173], s[76:77], 1.0 op_sel_hi:[1,0,0]
	v_pk_fma_f32 v[182:183], v[120:121], v[182:183], s[48:49] op_sel_hi:[1,1,0]
	v_pk_fma_f32 v[112:113], v[180:181], v[112:113], s[96:97] op_sel_hi:[1,1,0]
	v_rcp_f32_e32 v172, v172
	v_rcp_f32_e32 v173, v173
	v_pk_fma_f32 v[182:183], v[120:121], v[182:183], s[50:51] op_sel_hi:[1,1,0]
	v_pk_fma_f32 v[112:113], v[180:181], v[112:113], s[48:49] op_sel_hi:[1,1,0]
	v_pk_mul_f32 v[122:123], v[122:123], v[146:147] op_sel_hi:[1,0]
	v_pk_mul_f32 v[120:121], v[120:121], v[182:183]
	v_pk_mul_f32 v[118:119], v[118:119], v[146:147] op_sel_hi:[1,0]
	v_pk_mul_f32 v[182:183], v[114:115], v[146:147] op_sel_hi:[1,0]
	v_pk_fma_f32 v[112:113], v[180:181], v[112:113], s[50:51] op_sel_hi:[1,1,0]
	v_pk_mul_f32 v[146:147], v[116:117], v[116:117]
	v_pk_mul_f32 v[112:113], v[180:181], v[112:113]
	v_pk_mul_f32 v[146:147], v[146:147], s[52:53] op_sel_hi:[1,0]
	v_and_b32_e32 v181, 0x7fffffff, v119
	v_and_b32_e32 v180, 0x7fffffff, v118
	v_exp_f32_e32 v146, v146
	v_exp_f32_e32 v147, v147
	v_pk_fma_f32 v[180:181], v[180:181], s[76:77], 1.0 op_sel_hi:[1,0,0]
	v_and_b32_e32 v179, 0x7fffffff, v123
	v_and_b32_e32 v178, 0x7fffffff, v122
	v_pk_fma_f32 v[186:187], v[172:173], s[78:79], v[144:145] op_sel_hi:[1,0,0]
	v_rcp_f32_e32 v180, v180
	v_rcp_f32_e32 v181, v181
	v_pk_fma_f32 v[178:179], v[178:179], s[76:77], 1.0 op_sel_hi:[1,0,0]
	v_pk_fma_f32 v[186:187], v[172:173], v[186:187], s[96:97] op_sel_hi:[1,1,0]
	v_pk_mul_f32 v[168:169], v[124:125], v[124:125]
	v_rcp_f32_e32 v178, v178
	v_rcp_f32_e32 v179, v179
	v_pk_fma_f32 v[186:187], v[172:173], v[186:187], s[48:49] op_sel_hi:[1,1,0]
	v_pk_mul_f32 v[176:177], v[164:165], v[164:165]
	v_pk_mul_f32 v[168:169], v[168:169], s[52:53] op_sel_hi:[1,0]
	v_pk_fma_f32 v[186:187], v[172:173], v[186:187], s[50:51] op_sel_hi:[1,1,0]
	v_pk_mul_f32 v[114:115], v[118:119], v[118:119]
	v_pk_mul_f32 v[112:113], v[146:147], v[112:113]
	v_pk_mul_f32 v[176:177], v[176:177], s[52:53] op_sel_hi:[1,0]
	v_exp_f32_e32 v168, v168
	v_exp_f32_e32 v169, v169
	v_pk_mul_f32 v[172:173], v[172:173], v[186:187]
	v_pk_mul_f32 v[146:147], v[116:117], v[112:113]
	v_pk_fma_f32 v[186:187], v[116:117], v[112:113], v[116:117] neg_lo:[1,0,0] neg_hi:[1,0,0]
	v_pk_fma_f32 v[112:113], v[180:181], s[78:79], v[144:145] op_sel_hi:[1,0,0]
	v_pk_mul_f32 v[114:115], v[114:115], s[52:53] op_sel_hi:[1,0]
	v_pk_mul_f32 v[166:167], v[126:127], v[126:127]
	v_exp_f32_e32 v176, v176
	v_exp_f32_e32 v177, v177
	v_pk_fma_f32 v[112:113], v[180:181], v[112:113], s[96:97] op_sel_hi:[1,1,0]
	v_exp_f32_e32 v114, v114
	v_exp_f32_e32 v115, v115
	v_pk_mul_f32 v[174:175], v[122:123], v[122:123]
; DI unsigned pk2(float a, float b) { f32x2 v = {a, b}; hbf16x2 r = __builtin_convertvector(v, hbf16x2); return __builtin_bit_cast(unsigned, r); }
;     DI void operator()(const f32x4 (&acc)[2][2][4][2], const Unit& u, int wr, int wc, int fr, int fq) const {
;     ...
;                     const f32x2 g0 = gelu_pk((f32x2){a0[0], a0[1]}), g1 = gelu_pk((f32x2){a0[2], a0[3]}), g2 = gelu_pk((f32x2){a1[0], a1[1]}), g3 = gelu_pk((f32x2){a1[2], a1[3]});
;                     s += ((g0.x + g0.y) + (g1.x + g1.y)) + ((g2.x + g2.y) + (g3.x + g3.y));
;                     q += ((g0.x * g0.x + g0.y * g0.y) + (g1.x * g1.x + g1.y * g1.y)) + ((g2.x * g2.x + g2.y * g2.y) + (g3.x * g3.x + g3.y * g3.y));
;                     u32x4 w; w.x = pk2(g0.x, g0.y); w.y = pk2(g1.x, g1.y); w.z = pk2(g2.x, g2.y); w.w = pk2(g3.x, g3.y);
;                     *(u32x4*)(base + (size_t)r * 2048 + colt + bj * HALF) = w; }
	v_pk_mul_f32 v[166:167], v[166:167], s[52:53] op_sel_hi:[1,0]
	v_pk_fma_f32 v[188:189], v[178:179], s[78:79], v[144:145] op_sel_hi:[1,0,0]
	v_pk_fma_f32 v[112:113], v[180:181], v[112:113], s[48:49] op_sel_hi:[1,1,0]
	v_pk_mul_f32 v[174:175], v[174:175], s[52:53] op_sel_hi:[1,0]
	v_exp_f32_e32 v166, v166
	v_exp_f32_e32 v167, v167
	v_pk_fma_f32 v[188:189], v[178:179], v[188:189], s[96:97] op_sel_hi:[1,1,0]
	v_pk_fma_f32 v[112:113], v[180:181], v[112:113], s[50:51] op_sel_hi:[1,1,0]
	v_exp_f32_e32 v174, v174
	v_exp_f32_e32 v175, v175
	v_pk_fma_f32 v[188:189], v[178:179], v[188:189], s[48:49] op_sel_hi:[1,1,0]
	v_pk_mul_f32 v[120:121], v[168:169], v[120:121]
	v_pk_mul_f32 v[112:113], v[180:181], v[112:113]
	v_pk_fma_f32 v[188:189], v[178:179], v[188:189], s[50:51] op_sel_hi:[1,1,0]
	v_pk_mul_f32 v[168:169], v[176:177], v[172:173]
	v_pk_mul_f32 v[172:173], v[124:125], v[120:121]
	v_pk_fma_f32 v[120:121], v[124:125], v[120:121], v[124:125] neg_lo:[1,0,0] neg_hi:[1,0,0]
	v_pk_mul_f32 v[112:113], v[114:115], v[112:113]
	v_cmp_gt_f32_e32 vcc, 0, v124
	v_pk_mul_f32 v[178:179], v[178:179], v[188:189]
	v_pk_mul_f32 v[180:181], v[118:119], v[112:113]
	v_pk_fma_f32 v[188:189], v[118:119], v[112:113], v[118:119] neg_lo:[1,0,0] neg_hi:[1,0,0]
	v_cndmask_b32_e32 v112, v120, v172, vcc
	v_cmp_gt_f32_e32 vcc, 0, v116
	v_pk_mul_f32 v[166:167], v[166:167], v[170:171]
	v_pk_mul_f32 v[170:171], v[174:175], v[178:179]
	v_cndmask_b32_e32 v113, v186, v146, vcc
	v_cmp_gt_f32_e32 vcc, 0, v125
	v_pk_mul_f32 v[174:175], v[126:127], v[166:167]
	v_pk_fma_f32 v[166:167], v[126:127], v[166:167], v[126:127] neg_lo:[1,0,0] neg_hi:[1,0,0]
	v_cndmask_b32_e32 v120, v121, v173, vcc
	v_cmp_gt_f32_e32 vcc, 0, v126
	v_pk_mul_f32 v[176:177], v[164:165], v[168:169]
	v_pk_fma_f32 v[168:169], v[164:165], v[168:169], v[164:165] neg_lo:[1,0,0] neg_hi:[1,0,0]
	v_cndmask_b32_e32 v114, v166, v174, vcc
	v_cmp_gt_f32_e32 vcc, 0, v117
	v_pk_mul_f32 v[178:179], v[122:123], v[170:171]
	v_pk_fma_f32 v[170:171], v[122:123], v[170:171], v[122:123] neg_lo:[1,0,0] neg_hi:[1,0,0]
	v_cndmask_b32_e32 v115, v187, v147, vcc
	v_cmp_gt_f32_e32 vcc, 0, v127
	v_and_b32_e32 v147, 0x7fffffff, v185
	v_and_b32_e32 v146, 0x7fffffff, v184
	v_cndmask_b32_e32 v124, v167, v175, vcc
	v_cmp_gt_f32_e32 vcc, 0, v164
	v_pk_fma_f32 v[146:147], v[146:147], s[76:77], 1.0 op_sel_hi:[1,0,0]
	v_cvt_pk_bf16_f32 v164, v112, v120
	v_cndmask_b32_e32 v116, v168, v176, vcc
	v_cmp_gt_f32_e32 vcc, 0, v118
	v_rcp_f32_e32 v146, v146
	v_rcp_f32_e32 v147, v147
	v_cndmask_b32_e32 v117, v188, v180, vcc
	v_cmp_gt_f32_e32 vcc, 0, v165
	v_cvt_pk_bf16_f32 v165, v114, v124
	v_and_b32_e32 v168, 0x7fffffff, v182
	v_cndmask_b32_e32 v126, v169, v177, vcc
	v_cmp_gt_f32_e32 vcc, 0, v122
	v_cvt_pk_bf16_f32 v166, v116, v126
	v_and_b32_e32 v169, 0x7fffffff, v183
	v_cndmask_b32_e32 v118, v170, v178, vcc
	v_cmp_gt_f32_e32 vcc, 0, v119
	v_pk_fma_f32 v[168:169], v[168:169], s[76:77], 1.0 op_sel_hi:[1,0,0]
	s_nop 0
	v_cndmask_b32_e32 v119, v189, v181, vcc
	v_cmp_gt_f32_e32 vcc, 0, v123
	v_rcp_f32_e32 v168, v168
	v_rcp_f32_e32 v169, v169
	v_cndmask_b32_e32 v122, v171, v179, vcc
	v_cvt_pk_bf16_f32 v167, v118, v122
	global_store_dwordx4 v[142:143], v[164:167], off
	v_cmp_gt_f32_e32 vcc, 0, v182
	s_nop 0
	v_pk_mul_f32 v[166:167], v[184:185], v[184:185]
	v_pk_fma_f32 v[164:165], v[146:147], s[78:79], v[144:145] op_sel_hi:[1,0,0]
	v_pk_mul_f32 v[166:167], v[166:167], s[52:53] op_sel_hi:[1,0]
	v_pk_fma_f32 v[164:165], v[146:147], v[164:165], s[96:97] op_sel_hi:[1,1,0]
	v_exp_f32_e32 v166, v166
	v_exp_f32_e32 v167, v167
	v_pk_fma_f32 v[164:165], v[146:147], v[164:165], s[48:49] op_sel_hi:[1,1,0]
	v_pk_fma_f32 v[144:145], v[168:169], s[78:79], v[144:145] op_sel_hi:[1,0,0]
	v_pk_fma_f32 v[164:165], v[146:147], v[164:165], s[50:51] op_sel_hi:[1,1,0]
	v_pk_fma_f32 v[144:145], v[168:169], v[144:145], s[96:97] op_sel_hi:[1,1,0]
	v_pk_mul_f32 v[146:147], v[146:147], v[164:165]
	v_pk_mul_f32 v[164:165], v[182:183], v[182:183]
	v_pk_mul_f32 v[146:147], v[166:167], v[146:147]
	v_pk_fma_f32 v[144:145], v[168:169], v[144:145], s[48:49] op_sel_hi:[1,1,0]
	v_pk_mul_f32 v[166:167], v[184:185], v[146:147]
	v_pk_fma_f32 v[170:171], v[184:185], v[146:147], v[184:185] neg_lo:[1,0,0] neg_hi:[1,0,0]
	v_pk_mul_f32 v[146:147], v[164:165], s[52:53] op_sel_hi:[1,0]
	v_pk_fma_f32 v[144:145], v[168:169], v[144:145], s[50:51] op_sel_hi:[1,1,0]
	v_exp_f32_e32 v146, v146
	v_exp_f32_e32 v147, v147
	v_pk_mul_f32 v[144:145], v[168:169], v[144:145]
	s_nop 0
	v_pk_mul_f32 v[144:145], v[146:147], v[144:145]
	s_nop 0
	v_pk_mul_f32 v[146:147], v[182:183], v[144:145]
	v_pk_fma_f32 v[164:165], v[182:183], v[144:145], v[182:183] neg_lo:[1,0,0] neg_hi:[1,0,0]
	s_nop 0
	v_cndmask_b32_e32 v145, v164, v146, vcc
	v_cmp_gt_f32_e32 vcc, 0, v184
	v_cvt_pk_bf16_f32 v164, v113, v115
	s_nop 0
	v_cndmask_b32_e32 v144, v170, v166, vcc
	v_cmp_gt_f32_e32 vcc, 0, v183
	s_nop 1
	v_cndmask_b32_e32 v147, v165, v147, vcc
	v_cmp_gt_f32_e32 vcc, 0, v185
	v_cvt_pk_bf16_f32 v165, v117, v119
	s_nop 0
	v_cndmask_b32_e32 v146, v171, v167, vcc
	v_cvt_pk_bf16_f32 v166, v144, v146
	v_cvt_pk_bf16_f32 v167, v145, v147
	global_store_dwordx4 v[142:143], v[164:167], off offset:256
	s_cbranch_scc1 .LBB0_228
; DI unsigned pk2(float a, float b) { f32x2 v = {a, b}; hbf16x2 r = __builtin_convertvector(v, hbf16x2); return __builtin_bit_cast(unsigned, r); }
;     DI void operator()(const f32x4 (&acc)[2][2][4][2], const Unit& u, int wr, int wc, int fr, int fq) const {
;     ...
;                     s += ((g0.x + g0.y) + (g1.x + g1.y)) + ((g2.x + g2.y) + (g3.x + g3.y));
;                     q += ((g0.x * g0.x + g0.y * g0.y) + (g1.x * g1.x + g1.y * g1.y)) + ((g2.x * g2.x + g2.y * g2.y) + (g3.x * g3.x + g3.y * g3.y));
;                     u32x4 w; w.x = pk2(g0.x, g0.y); w.y = pk2(g1.x, g1.y); w.z = pk2(g2.x, g2.y); w.w = pk2(g3.x, g3.y);
;                     *(u32x4*)(base + (size_t)r * 2048 + colt + bj * HALF) = w; }
;                 if (isv) { s += __shfl_xor(s, 16); s += __shfl_xor(s, 32); q += __shfl_xor(q, 16); q += __shfl_xor(q, 32);
;                     if (fq == 0) *(f32x2*)(STATS + ((size_t)r * 32 + (pn - 8) * 4 + wc) * 2) = (f32x2){s, q}; }
	v_mov_b32_e32 v121, v113
	v_mov_b32_e32 v125, v115
	v_pk_mul_f32 v[164:165], v[120:121], v[120:121]
	v_pk_add_f32 v[178:179], v[112:113], v[120:121]
	v_pk_mul_f32 v[120:121], v[112:113], v[120:121]
	v_mov_b32_e32 v127, v117
	v_pk_mul_f32 v[142:143], v[112:113], v[112:113]
	v_pk_mul_f32 v[168:169], v[124:125], v[124:125]
	v_mov_b32_e32 v179, v121
	v_pk_add_f32 v[120:121], v[114:115], v[124:125]
	v_pk_mul_f32 v[124:125], v[114:115], v[124:125]
	v_mov_b32_e32 v123, v119
	v_pk_mul_f32 v[166:167], v[114:115], v[114:115]
	v_pk_mul_f32 v[172:173], v[126:127], v[126:127]
	v_mov_b32_e32 v121, v125
	v_pk_add_f32 v[124:125], v[116:117], v[126:127]
	v_pk_mul_f32 v[126:127], v[116:117], v[126:127]
	v_pk_mov_b32 v[112:113], v[112:113], v[142:143] op_sel:[1,0]
	v_pk_mov_b32 v[114:115], v[114:115], v[164:165] op_sel:[1,0]
	v_pk_mul_f32 v[170:171], v[116:117], v[116:117]
	v_pk_mul_f32 v[176:177], v[122:123], v[122:123]
	v_mov_b32_e32 v125, v127
	v_pk_add_f32 v[126:127], v[118:119], v[122:123]
	v_pk_mul_f32 v[122:123], v[118:119], v[122:123]
	v_pk_add_f32 v[112:113], v[112:113], v[114:115]
	v_pk_mov_b32 v[114:115], v[116:117], v[166:167] op_sel:[1,0]
	v_pk_mov_b32 v[116:117], v[118:119], v[168:169] op_sel:[1,0]
	v_mov_b32_e32 v127, v123
	v_pk_mul_f32 v[122:123], v[146:147], v[146:147]
	v_pk_add_f32 v[114:115], v[114:115], v[116:117]
	v_pk_mul_f32 v[174:175], v[118:119], v[118:119]
	v_pk_fma_f32 v[122:123], v[144:145], v[144:145], v[122:123]
	v_pk_add_f32 v[112:113], v[112:113], v[114:115]
	v_mov_b32_e32 v114, v144
	v_mov_b32_e32 v115, v170
	v_mov_b32_e32 v116, v146
	v_mov_b32_e32 v117, v172
	v_pk_add_f32 v[122:123], v[122:123], v[122:123] op_sel_hi:[0,1]
	v_cmp_lt_i32_e32 vcc, v248, v243
	v_pk_add_f32 v[114:115], v[114:115], v[116:117]
	v_pk_mov_b32 v[116:117], v[144:145], v[174:175] op_sel:[1,0]
	v_pk_mov_b32 v[118:119], v[146:147], v[176:177] op_sel:[1,0]
	v_cndmask_b32_e32 v122, v241, v248, vcc
	v_pk_add_f32 v[120:121], v[178:179], v[120:121]
	v_pk_add_f32 v[124:125], v[124:125], v[126:127]
	v_pk_add_f32 v[116:117], v[116:117], v[118:119]
	v_lshlrev_b32_e32 v171, 2, v122
	v_pk_add_f32 v[120:121], v[120:121], v[124:125]
	v_mov_b32_e32 v122, v153
	v_pk_add_f32 v[114:115], v[114:115], v[116:117]
	v_pk_add_f32 v[120:121], v[120:121], v[122:123]
	v_pk_add_f32 v[112:113], v[112:113], v[114:115]
	v_cmp_lt_i32_e32 vcc, v249, v243
	v_pk_add_f32 v[112:113], v[112:113], v[120:121]
	ds_bpermute_b32 v114, v171, v112
	ds_bpermute_b32 v115, v171, v113
	v_cndmask_b32_e32 v116, v241, v249, vcc
	v_lshlrev_b32_e32 v116, 2, v116
	s_waitcnt lgkmcnt(0)
	v_pk_add_f32 v[112:113], v[112:113], v[114:115]
	ds_bpermute_b32 v114, v116, v112
	ds_bpermute_b32 v115, v116, v113
	s_and_saveexec_b64 s[4:5], s[0:1]
	s_cbranch_execz .LBB0_227
	v_lshlrev_b64 v[116:117], 8, v[138:139]
	s_waitcnt lgkmcnt(0)
	v_pk_add_f32 v[112:113], v[112:113], v[114:115]
	v_lshl_add_u64 v[114:115], s[18:19], 0, v[116:117]
	v_lshl_add_u64 v[114:115], s[72:73], 3, v[114:115]
	global_store_dwordx2 v[114:115], v[112:113], off

;     DI void operator()(const f32x4 (&acc)[2][2][4][2], const Unit& u, int wr, int wc, int fr, int fq) const {
;     ...
;                 const int r = u.pm * BM + ai * HALF + wr * 64 + m * 16 + fr; float s = 0.f, q = 0.f; const float rs = RS[r];
; #pragma unroll
;                 for (int bj = 0; bj < 2; ++bj) { const f32x4 a0 = acc[ai][bj][m][0] * rs, a1 = acc[ai][bj][m][1] * rs;
;                     const f32x2 g0 = gelu_pk((f32x2){a0[0], a0[1]}), g1 = gelu_pk((f32x2){a0[2], a0[3]}), g2 = gelu_pk((f32x2){a1[0], a1[1]}), g3 = gelu_pk((f32x2){a1[2], a1[3]});
.LBB0_228:
	v_add_u32_e32 v112, 16, v138
	v_ashrrev_i32_e32 v113, 31, v112
	s_waitcnt lgkmcnt(0)
	v_lshl_add_u64 v[114:115], v[112:113], 2, s[14:15]
	v_mov_b64_e32 v[116:117], s[80:81]
	v_lshlrev_b64 v[114:115], 12, v[112:113]
	v_lshl_add_u64 v[114:115], v[140:141], 0, v[114:115]
	v_mov_b32_e32 v118, v200
	v_pk_mul_f32 v[108:109], v[108:109], v[118:119] op_sel_hi:[1,0]
	v_pk_mul_f32 v[110:111], v[110:111], v[118:119] op_sel_hi:[1,0]
	v_pk_mul_f32 v[106:107], v[106:107], v[118:119] op_sel_hi:[1,0]
	v_pk_mul_f32 v[120:121], v[104:105], v[118:119] op_sel_hi:[1,0]
	v_pk_mul_f32 v[124:125], v[96:97], v[118:119] op_sel_hi:[1,0]
	v_and_b32_e32 v97, 0x7fffffff, v109
	v_and_b32_e32 v96, 0x7fffffff, v108
	v_pk_mul_f32 v[102:103], v[102:103], v[118:119] op_sel_hi:[1,0]
	v_pk_mul_f32 v[100:101], v[100:101], v[118:119] op_sel_hi:[1,0]
	v_pk_mul_f32 v[122:123], v[98:99], v[118:119] op_sel_hi:[1,0]
	v_and_b32_e32 v119, 0x7fffffff, v111
	v_and_b32_e32 v118, 0x7fffffff, v110
	v_and_b32_e32 v127, 0x7fffffff, v121
	v_and_b32_e32 v126, 0x7fffffff, v120
	v_and_b32_e32 v147, 0x7fffffff, v107
	v_and_b32_e32 v146, 0x7fffffff, v106
	v_pk_fma_f32 v[96:97], v[96:97], s[76:77], 1.0 op_sel_hi:[1,0,0]
	v_pk_fma_f32 v[118:119], v[118:119], s[76:77], 1.0 op_sel_hi:[1,0,0]
	v_pk_fma_f32 v[126:127], v[126:127], s[76:77], 1.0 op_sel_hi:[1,0,0]
	v_pk_fma_f32 v[146:147], v[146:147], s[76:77], 1.0 op_sel_hi:[1,0,0]
	v_rcp_f32_e32 v96, v96
	v_rcp_f32_e32 v97, v97
	v_rcp_f32_e32 v118, v118
	v_rcp_f32_e32 v119, v119
	v_rcp_f32_e32 v126, v126
	v_rcp_f32_e32 v127, v127
	v_rcp_f32_e32 v146, v146
	v_rcp_f32_e32 v147, v147
	v_pk_mul_f32 v[104:105], v[108:109], v[108:109]
	v_pk_mul_f32 v[98:99], v[110:111], v[110:111]
	v_pk_mul_f32 v[142:143], v[106:107], v[106:107]
	v_pk_mul_f32 v[144:145], v[120:121], v[120:121]
	v_pk_mul_f32 v[104:105], v[104:105], s[52:53] op_sel_hi:[1,0]
	v_pk_fma_f32 v[170:171], v[96:97], s[78:79], v[116:117] op_sel_hi:[1,0,0]
	v_pk_mul_f32 v[98:99], v[98:99], s[52:53] op_sel_hi:[1,0]
	v_pk_mul_f32 v[144:145], v[144:145], s[52:53] op_sel_hi:[1,0]
	v_pk_mul_f32 v[142:143], v[142:143], s[52:53] op_sel_hi:[1,0]
	v_exp_f32_e32 v104, v104
	v_exp_f32_e32 v105, v105
	v_pk_fma_f32 v[172:173], v[118:119], s[78:79], v[116:117] op_sel_hi:[1,0,0]
	v_pk_fma_f32 v[174:175], v[126:127], s[78:79], v[116:117] op_sel_hi:[1,0,0]
	v_pk_fma_f32 v[176:177], v[146:147], s[78:79], v[116:117] op_sel_hi:[1,0,0]
	v_pk_fma_f32 v[170:171], v[96:97], v[170:171], s[96:97] op_sel_hi:[1,1,0]
	v_exp_f32_e32 v98, v98
	v_exp_f32_e32 v99, v99
	v_exp_f32_e32 v144, v144
	v_exp_f32_e32 v145, v145
	v_exp_f32_e32 v142, v142
	v_exp_f32_e32 v143, v143
	v_pk_fma_f32 v[172:173], v[118:119], v[172:173], s[96:97] op_sel_hi:[1,1,0]
	v_pk_fma_f32 v[174:175], v[126:127], v[174:175], s[96:97] op_sel_hi:[1,1,0]
	v_pk_fma_f32 v[176:177], v[146:147], v[176:177], s[96:97] op_sel_hi:[1,1,0]
	v_pk_fma_f32 v[170:171], v[96:97], v[170:171], s[48:49] op_sel_hi:[1,1,0]
	v_pk_fma_f32 v[172:173], v[118:119], v[172:173], s[48:49] op_sel_hi:[1,1,0]
	v_pk_fma_f32 v[174:175], v[126:127], v[174:175], s[48:49] op_sel_hi:[1,1,0]
	v_pk_fma_f32 v[176:177], v[146:147], v[176:177], s[48:49] op_sel_hi:[1,1,0]
	v_pk_fma_f32 v[170:171], v[96:97], v[170:171], s[50:51] op_sel_hi:[1,1,0]
	v_pk_fma_f32 v[172:173], v[118:119], v[172:173], s[50:51] op_sel_hi:[1,1,0]
	v_pk_fma_f32 v[174:175], v[126:127], v[174:175], s[50:51] op_sel_hi:[1,1,0]
	v_pk_fma_f32 v[176:177], v[146:147], v[176:177], s[50:51] op_sel_hi:[1,1,0]
	v_pk_mul_f32 v[96:97], v[96:97], v[170:171]
	v_pk_mul_f32 v[118:119], v[118:119], v[172:173]
	v_pk_mul_f32 v[126:127], v[126:127], v[174:175]
	v_pk_mul_f32 v[146:147], v[146:147], v[176:177]
	v_pk_mul_f32 v[96:97], v[104:105], v[96:97]
	v_and_b32_e32 v165, 0x7fffffff, v101
	v_and_b32_e32 v164, 0x7fffffff, v100
	v_pk_mul_f32 v[98:99], v[98:99], v[118:119]
	v_pk_mul_f32 v[104:105], v[144:145], v[126:127]
	v_pk_mul_f32 v[118:119], v[142:143], v[146:147]
	v_pk_mul_f32 v[126:127], v[108:109], v[96:97]
	v_pk_fma_f32 v[142:143], v[108:109], v[96:97], v[108:109] neg_lo:[1,0,0] neg_hi:[1,0,0]
	v_and_b32_e32 v97, 0x7fffffff, v103
	v_and_b32_e32 v96, 0x7fffffff, v102
	v_pk_fma_f32 v[164:165], v[164:165], s[76:77], 1.0 op_sel_hi:[1,0,0]
	v_pk_fma_f32 v[96:97], v[96:97], s[76:77], 1.0 op_sel_hi:[1,0,0]
	v_rcp_f32_e32 v164, v164
	v_rcp_f32_e32 v165, v165
	v_rcp_f32_e32 v96, v96
	v_rcp_f32_e32 v97, v97
	v_pk_mul_f32 v[166:167], v[102:103], v[102:103]
	v_pk_mul_f32 v[168:169], v[100:101], v[100:101]
	v_pk_fma_f32 v[178:179], v[164:165], s[78:79], v[116:117] op_sel_hi:[1,0,0]
	v_pk_mul_f32 v[168:169], v[168:169], s[52:53] op_sel_hi:[1,0]
	v_pk_mul_f32 v[170:171], v[120:121], v[104:105]
	v_pk_fma_f32 v[172:173], v[120:121], v[104:105], v[120:121] neg_lo:[1,0,0] neg_hi:[1,0,0]
	v_pk_fma_f32 v[104:105], v[96:97], s[78:79], v[116:117] op_sel_hi:[1,0,0]
	v_pk_mul_f32 v[166:167], v[166:167], s[52:53] op_sel_hi:[1,0]
	v_exp_f32_e32 v168, v168
	v_pk_fma_f32 v[178:179], v[164:165], v[178:179], s[96:97] op_sel_hi:[1,1,0]
	v_exp_f32_e32 v169, v169
	v_pk_fma_f32 v[104:105], v[96:97], v[104:105], s[96:97] op_sel_hi:[1,1,0]
	v_exp_f32_e32 v166, v166
	v_exp_f32_e32 v167, v167
	v_pk_fma_f32 v[178:179], v[164:165], v[178:179], s[48:49] op_sel_hi:[1,1,0]
	v_pk_fma_f32 v[104:105], v[96:97], v[104:105], s[48:49] op_sel_hi:[1,1,0]
	v_pk_fma_f32 v[178:179], v[164:165], v[178:179], s[50:51] op_sel_hi:[1,1,0]
	v_pk_fma_f32 v[104:105], v[96:97], v[104:105], s[50:51] op_sel_hi:[1,1,0]
	v_pk_mul_f32 v[164:165], v[164:165], v[178:179]
	v_pk_mul_f32 v[96:97], v[96:97], v[104:105]
	v_pk_mul_f32 v[144:145], v[110:111], v[98:99]
	v_pk_fma_f32 v[146:147], v[110:111], v[98:99], v[110:111] neg_lo:[1,0,0] neg_hi:[1,0,0]
; DI unsigned pk2(float a, float b) { f32x2 v = {a, b}; hbf16x2 r = __builtin_convertvector(v, hbf16x2); return __builtin_bit_cast(unsigned, r); }
;     DI void operator()(const f32x4 (&acc)[2][2][4][2], const Unit& u, int wr, int wc, int fr, int fq) const {
;     ...
;                     const f32x2 g0 = gelu_pk((f32x2){a0[0], a0[1]}), g1 = gelu_pk((f32x2){a0[2], a0[3]}), g2 = gelu_pk((f32x2){a1[0], a1[1]}), g3 = gelu_pk((f32x2){a1[2], a1[3]});
;                     s += ((g0.x + g0.y) + (g1.x + g1.y)) + ((g2.x + g2.y) + (g3.x + g3.y));
;                     q += ((g0.x * g0.x + g0.y * g0.y) + (g1.x * g1.x + g1.y * g1.y)) + ((g2.x * g2.x + g2.y * g2.y) + (g3.x * g3.x + g3.y * g3.y));
;                     u32x4 w; w.x = pk2(g0.x, g0.y); w.y = pk2(g1.x, g1.y); w.z = pk2(g2.x, g2.y); w.w = pk2(g3.x, g3.y);
;                     *(u32x4*)(base + (size_t)r * 2048 + colt + bj * HALF) = w; }
;                 if (isv) { s += __shfl_xor(s, 16); s += __shfl_xor(s, 32); q += __shfl_xor(q, 16); q += __shfl_xor(q, 32);
;                     if (fq == 0) *(f32x2*)(STATS + ((size_t)r * 32 + (pn - 8) * 4 + wc) * 2) = (f32x2){s, q}; }
	v_pk_mul_f32 v[98:99], v[168:169], v[164:165]
	v_pk_mul_f32 v[96:97], v[166:167], v[96:97]
	v_cmp_gt_f32_e32 vcc, 0, v108
	v_pk_mul_f32 v[164:165], v[100:101], v[98:99]
	v_pk_fma_f32 v[98:99], v[100:101], v[98:99], v[100:101] neg_lo:[1,0,0] neg_hi:[1,0,0]
	v_pk_mul_f32 v[166:167], v[102:103], v[96:97]
	v_pk_fma_f32 v[168:169], v[102:103], v[96:97], v[102:103] neg_lo:[1,0,0] neg_hi:[1,0,0]
	v_cndmask_b32_e32 v96, v142, v126, vcc
	v_cmp_gt_f32_e32 vcc, 0, v100
	v_pk_mul_f32 v[174:175], v[106:107], v[118:119]
	v_pk_fma_f32 v[118:119], v[106:107], v[118:119], v[106:107] neg_lo:[1,0,0] neg_hi:[1,0,0]
	v_cndmask_b32_e32 v97, v98, v164, vcc
	v_cmp_gt_f32_e32 vcc, 0, v109
	v_and_b32_e32 v142, 0x7fffffff, v122
	s_nop 0
	v_cndmask_b32_e32 v104, v143, v127, vcc
	v_cmp_gt_f32_e32 vcc, 0, v110
	v_and_b32_e32 v143, 0x7fffffff, v123
	v_pk_fma_f32 v[142:143], v[142:143], s[76:77], 1.0 op_sel_hi:[1,0,0]
	v_cndmask_b32_e32 v98, v146, v144, vcc
	v_cmp_gt_f32_e32 vcc, 0, v101
	v_rcp_f32_e32 v142, v142
	v_rcp_f32_e32 v143, v143
	v_cndmask_b32_e32 v99, v99, v165, vcc
	v_cmp_gt_f32_e32 vcc, 0, v111
	s_nop 1
	v_cndmask_b32_e32 v108, v147, v145, vcc
	v_cmp_gt_f32_e32 vcc, 0, v120
	v_and_b32_e32 v120, 0x7fffffff, v124
	s_nop 0
	v_cndmask_b32_e32 v100, v172, v170, vcc
	v_cmp_gt_f32_e32 vcc, 0, v102
	s_nop 1
	v_cndmask_b32_e32 v101, v168, v166, vcc
	v_cmp_gt_f32_e32 vcc, 0, v121
	v_and_b32_e32 v121, 0x7fffffff, v125
	v_pk_fma_f32 v[120:121], v[120:121], s[76:77], 1.0 op_sel_hi:[1,0,0]
	v_cndmask_b32_e32 v110, v173, v171, vcc
	v_cmp_gt_f32_e32 vcc, 0, v106
	v_rcp_f32_e32 v126, v120
	v_rcp_f32_e32 v127, v121
	v_cndmask_b32_e32 v102, v118, v174, vcc
	v_cmp_gt_f32_e32 vcc, 0, v103
	v_cvt_pk_bf16_f32 v118, v96, v104
	v_cvt_pk_bf16_f32 v120, v100, v110
	v_cndmask_b32_e32 v103, v169, v167, vcc
	v_cmp_gt_f32_e32 vcc, 0, v107
	s_nop 1
	v_cndmask_b32_e32 v106, v119, v175, vcc
	v_cvt_pk_bf16_f32 v119, v98, v108
	v_cvt_pk_bf16_f32 v121, v102, v106
	global_store_dwordx4 v[114:115], v[118:121], off
	v_cmp_gt_f32_e32 vcc, 0, v122
	s_nop 0
	v_pk_fma_f32 v[118:119], v[126:127], s[78:79], v[116:117] op_sel_hi:[1,0,0]
	v_pk_mul_f32 v[120:121], v[122:123], v[122:123]
	v_pk_fma_f32 v[118:119], v[126:127], v[118:119], s[96:97] op_sel_hi:[1,1,0]
	v_pk_fma_f32 v[116:117], v[142:143], s[78:79], v[116:117] op_sel_hi:[1,0,0]
	v_pk_fma_f32 v[118:119], v[126:127], v[118:119], s[48:49] op_sel_hi:[1,1,0]
	v_pk_fma_f32 v[116:117], v[142:143], v[116:117], s[96:97] op_sel_hi:[1,1,0]
	v_pk_fma_f32 v[118:119], v[126:127], v[118:119], s[50:51] op_sel_hi:[1,1,0]
	v_pk_fma_f32 v[116:117], v[142:143], v[116:117], s[48:49] op_sel_hi:[1,1,0]
	v_pk_mul_f32 v[118:119], v[126:127], v[118:119]
	v_pk_mul_f32 v[126:127], v[124:125], v[124:125]
	v_pk_fma_f32 v[116:117], v[142:143], v[116:117], s[50:51] op_sel_hi:[1,1,0]
	v_pk_mul_f32 v[126:127], v[126:127], s[52:53] op_sel_hi:[1,0]
	v_pk_mul_f32 v[116:117], v[142:143], v[116:117]
	v_exp_f32_e32 v126, v126
	v_exp_f32_e32 v127, v127
	s_nop 0
	v_pk_mul_f32 v[118:119], v[126:127], v[118:119]
	s_nop 0
	v_pk_mul_f32 v[126:127], v[124:125], v[118:119]
	v_pk_fma_f32 v[144:145], v[124:125], v[118:119], v[124:125] neg_lo:[1,0,0] neg_hi:[1,0,0]
	v_pk_mul_f32 v[118:119], v[120:121], s[52:53] op_sel_hi:[1,0]
	s_nop 0
	v_exp_f32_e32 v118, v118
	v_exp_f32_e32 v119, v119
	s_nop 0
	v_pk_mul_f32 v[116:117], v[118:119], v[116:117]
	s_nop 0
	v_pk_mul_f32 v[118:119], v[122:123], v[116:117]
	v_pk_fma_f32 v[120:121], v[122:123], v[116:117], v[122:123] neg_lo:[1,0,0] neg_hi:[1,0,0]
	s_nop 0
	v_cndmask_b32_e32 v117, v120, v118, vcc
	v_cmp_gt_f32_e32 vcc, 0, v124
	v_cndmask_b32_e64 v124, 0, 1, s[28:29]
	v_cvt_pk_bf16_f32 v120, v97, v99
	v_cndmask_b32_e32 v116, v144, v126, vcc
	v_cmp_gt_f32_e32 vcc, 0, v123
	v_cmp_ne_u32_e64 s[4:5], 1, v124
	s_nop 0
	v_cndmask_b32_e32 v119, v121, v119, vcc
	v_cmp_gt_f32_e32 vcc, 0, v125
	v_cvt_pk_bf16_f32 v121, v101, v103
	v_cvt_pk_bf16_f32 v123, v117, v119
	v_cndmask_b32_e32 v118, v145, v127, vcc
	v_cvt_pk_bf16_f32 v122, v116, v118
	s_andn2_b64 vcc, exec, s[28:29]
	global_store_dwordx4 v[114:115], v[120:123], off offset:256
	s_cbranch_vccnz .LBB0_232
	v_mov_b32_e32 v105, v97
	v_mov_b32_e32 v109, v99
	v_pk_mul_f32 v[120:121], v[104:105], v[104:105]
	v_pk_add_f32 v[164:165], v[96:97], v[104:105]
	v_pk_mul_f32 v[104:105], v[96:97], v[104:105]
	v_mov_b32_e32 v111, v101
	v_pk_mul_f32 v[114:115], v[96:97], v[96:97]
	v_pk_mul_f32 v[124:125], v[108:109], v[108:109]
	v_mov_b32_e32 v165, v105
	v_pk_add_f32 v[104:105], v[98:99], v[108:109]
	v_pk_mul_f32 v[108:109], v[98:99], v[108:109]
	v_mov_b32_e32 v107, v103
	v_pk_mul_f32 v[122:123], v[98:99], v[98:99]
	v_pk_mul_f32 v[142:143], v[110:111], v[110:111]
	v_mov_b32_e32 v105, v109
	v_pk_add_f32 v[108:109], v[100:101], v[110:111]
	v_pk_mul_f32 v[110:111], v[100:101], v[110:111]
	v_pk_mov_b32 v[96:97], v[96:97], v[114:115] op_sel:[1,0]
	v_pk_mov_b32 v[98:99], v[98:99], v[120:121] op_sel:[1,0]
	v_pk_mul_f32 v[126:127], v[100:101], v[100:101]
	v_pk_mul_f32 v[146:147], v[106:107], v[106:107]
	v_mov_b32_e32 v109, v111
	v_pk_add_f32 v[110:111], v[102:103], v[106:107]
	v_pk_mul_f32 v[106:107], v[102:103], v[106:107]
	v_pk_add_f32 v[96:97], v[96:97], v[98:99]
	v_pk_mov_b32 v[98:99], v[100:101], v[122:123] op_sel:[1,0]
	v_pk_mov_b32 v[100:101], v[102:103], v[124:125] op_sel:[1,0]
	v_mov_b32_e32 v111, v107
	v_pk_mul_f32 v[106:107], v[118:119], v[118:119]
	v_pk_add_f32 v[98:99], v[98:99], v[100:101]
	v_pk_mul_f32 v[144:145], v[102:103], v[102:103]
	v_pk_fma_f32 v[106:107], v[116:117], v[116:117], v[106:107]
	v_pk_add_f32 v[96:97], v[96:97], v[98:99]
	v_mov_b32_e32 v98, v116
	v_mov_b32_e32 v99, v126
	v_mov_b32_e32 v100, v118
	v_mov_b32_e32 v101, v142
	v_pk_add_f32 v[106:107], v[106:107], v[106:107] op_sel_hi:[0,1]
	v_cmp_lt_i32_e32 vcc, v248, v243
	v_pk_add_f32 v[98:99], v[98:99], v[100:101]
	v_pk_mov_b32 v[100:101], v[116:117], v[144:145] op_sel:[1,0]
	v_pk_mov_b32 v[102:103], v[118:119], v[146:147] op_sel:[1,0]
	v_cndmask_b32_e32 v106, v241, v248, vcc
	v_pk_add_f32 v[104:105], v[164:165], v[104:105]
	v_pk_add_f32 v[108:109], v[108:109], v[110:111]
	v_pk_add_f32 v[100:101], v[100:101], v[102:103]
	v_lshlrev_b32_e32 v127, 2, v106
	v_pk_add_f32 v[104:105], v[104:105], v[108:109]
	v_mov_b32_e32 v106, v153
	v_pk_add_f32 v[98:99], v[98:99], v[100:101]
	v_pk_add_f32 v[104:105], v[104:105], v[106:107]
	v_pk_add_f32 v[96:97], v[96:97], v[98:99]
	v_cmp_lt_i32_e32 vcc, v249, v243
	v_pk_add_f32 v[96:97], v[96:97], v[104:105]
	ds_bpermute_b32 v98, v127, v96
	ds_bpermute_b32 v99, v127, v97
	v_cndmask_b32_e32 v100, v241, v249, vcc
	v_lshlrev_b32_e32 v100, 2, v100
	s_waitcnt lgkmcnt(0)
	v_pk_add_f32 v[96:97], v[96:97], v[98:99]
	ds_bpermute_b32 v98, v100, v96
	ds_bpermute_b32 v99, v100, v97
	s_and_saveexec_b64 s[28:29], s[0:1]
	s_cbranch_execz .LBB0_231
	v_lshlrev_b64 v[100:101], 8, v[112:113]
	s_waitcnt lgkmcnt(0)
	v_pk_add_f32 v[96:97], v[96:97], v[98:99]
	v_lshl_add_u64 v[98:99], s[18:19], 0, v[100:101]
	v_lshl_add_u64 v[98:99], s[72:73], 3, v[98:99]
	global_store_dwordx2 v[98:99], v[96:97], off

;     DI void operator()(const f32x4 (&acc)[2][2][4][2], const Unit& u, int wr, int wc, int fr, int fq) const {
;     ...
;                 const int r = u.pm * BM + ai * HALF + wr * 64 + m * 16 + fr; float s = 0.f, q = 0.f; const float rs = RS[r];
; #pragma unroll
;                 for (int bj = 0; bj < 2; ++bj) { const f32x4 a0 = acc[ai][bj][m][0] * rs, a1 = acc[ai][bj][m][1] * rs;
;                     const f32x2 g0 = gelu_pk((f32x2){a0[0], a0[1]}), g1 = gelu_pk((f32x2){a0[2], a0[3]}), g2 = gelu_pk((f32x2){a1[0], a1[1]}), g3 = gelu_pk((f32x2){a1[2], a1[3]});
.LBB0_232:
	v_add_u32_e32 v96, 32, v138
	v_ashrrev_i32_e32 v97, 31, v96
	s_waitcnt lgkmcnt(0)
	v_lshl_add_u64 v[98:99], v[96:97], 2, s[14:15]
	v_mov_b64_e32 v[100:101], s[80:81]
	v_lshlrev_b64 v[98:99], 12, v[96:97]
	v_lshl_add_u64 v[98:99], v[140:141], 0, v[98:99]
	v_mov_b32_e32 v102, v201
	v_pk_mul_f32 v[92:93], v[92:93], v[102:103] op_sel_hi:[1,0]
	v_pk_mul_f32 v[94:95], v[94:95], v[102:103] op_sel_hi:[1,0]
	v_pk_mul_f32 v[90:91], v[90:91], v[102:103] op_sel_hi:[1,0]
	v_pk_mul_f32 v[104:105], v[88:89], v[102:103] op_sel_hi:[1,0]
	v_pk_mul_f32 v[108:109], v[80:81], v[102:103] op_sel_hi:[1,0]
	v_and_b32_e32 v81, 0x7fffffff, v93
	v_and_b32_e32 v80, 0x7fffffff, v92
	v_pk_mul_f32 v[86:87], v[86:87], v[102:103] op_sel_hi:[1,0]
	v_pk_mul_f32 v[84:85], v[84:85], v[102:103] op_sel_hi:[1,0]
	v_pk_mul_f32 v[106:107], v[82:83], v[102:103] op_sel_hi:[1,0]
	v_and_b32_e32 v103, 0x7fffffff, v95
	v_and_b32_e32 v102, 0x7fffffff, v94
	v_and_b32_e32 v111, 0x7fffffff, v105
	v_and_b32_e32 v110, 0x7fffffff, v104
	v_and_b32_e32 v117, 0x7fffffff, v91
	v_and_b32_e32 v116, 0x7fffffff, v90
	v_pk_fma_f32 v[80:81], v[80:81], s[76:77], 1.0 op_sel_hi:[1,0,0]
	v_pk_fma_f32 v[102:103], v[102:103], s[76:77], 1.0 op_sel_hi:[1,0,0]
	v_pk_fma_f32 v[110:111], v[110:111], s[76:77], 1.0 op_sel_hi:[1,0,0]
	v_pk_fma_f32 v[116:117], v[116:117], s[76:77], 1.0 op_sel_hi:[1,0,0]
	v_rcp_f32_e32 v80, v80
	v_rcp_f32_e32 v81, v81
	v_rcp_f32_e32 v102, v102
	v_rcp_f32_e32 v103, v103
	v_rcp_f32_e32 v110, v110
	v_rcp_f32_e32 v111, v111
	v_rcp_f32_e32 v116, v116
	v_rcp_f32_e32 v117, v117
	v_pk_mul_f32 v[88:89], v[92:93], v[92:93]
	v_pk_mul_f32 v[82:83], v[94:95], v[94:95]
	v_pk_mul_f32 v[112:113], v[90:91], v[90:91]
	v_pk_mul_f32 v[114:115], v[104:105], v[104:105]
	v_pk_mul_f32 v[88:89], v[88:89], s[52:53] op_sel_hi:[1,0]
	v_pk_fma_f32 v[124:125], v[80:81], s[78:79], v[100:101] op_sel_hi:[1,0,0]
	v_pk_mul_f32 v[82:83], v[82:83], s[52:53] op_sel_hi:[1,0]
	v_pk_mul_f32 v[114:115], v[114:115], s[52:53] op_sel_hi:[1,0]
	v_pk_mul_f32 v[112:113], v[112:113], s[52:53] op_sel_hi:[1,0]
	v_exp_f32_e32 v88, v88
	v_exp_f32_e32 v89, v89
	v_pk_fma_f32 v[126:127], v[102:103], s[78:79], v[100:101] op_sel_hi:[1,0,0]
	v_pk_fma_f32 v[142:143], v[110:111], s[78:79], v[100:101] op_sel_hi:[1,0,0]
	v_pk_fma_f32 v[144:145], v[116:117], s[78:79], v[100:101] op_sel_hi:[1,0,0]
	v_pk_fma_f32 v[124:125], v[80:81], v[124:125], s[96:97] op_sel_hi:[1,1,0]
	v_exp_f32_e32 v82, v82
	v_exp_f32_e32 v83, v83
	v_exp_f32_e32 v114, v114
	v_exp_f32_e32 v115, v115
	v_exp_f32_e32 v112, v112
	v_exp_f32_e32 v113, v113
	v_pk_fma_f32 v[126:127], v[102:103], v[126:127], s[96:97] op_sel_hi:[1,1,0]
	v_pk_fma_f32 v[142:143], v[110:111], v[142:143], s[96:97] op_sel_hi:[1,1,0]
	v_pk_fma_f32 v[144:145], v[116:117], v[144:145], s[96:97] op_sel_hi:[1,1,0]
	v_pk_fma_f32 v[124:125], v[80:81], v[124:125], s[48:49] op_sel_hi:[1,1,0]
	v_pk_fma_f32 v[126:127], v[102:103], v[126:127], s[48:49] op_sel_hi:[1,1,0]
	v_pk_fma_f32 v[142:143], v[110:111], v[142:143], s[48:49] op_sel_hi:[1,1,0]
	v_pk_fma_f32 v[144:145], v[116:117], v[144:145], s[48:49] op_sel_hi:[1,1,0]
	v_pk_fma_f32 v[124:125], v[80:81], v[124:125], s[50:51] op_sel_hi:[1,1,0]
	v_pk_fma_f32 v[126:127], v[102:103], v[126:127], s[50:51] op_sel_hi:[1,1,0]
	v_pk_fma_f32 v[142:143], v[110:111], v[142:143], s[50:51] op_sel_hi:[1,1,0]
	v_pk_fma_f32 v[144:145], v[116:117], v[144:145], s[50:51] op_sel_hi:[1,1,0]
	v_pk_mul_f32 v[80:81], v[80:81], v[124:125]
	v_pk_mul_f32 v[102:103], v[102:103], v[126:127]
	v_pk_mul_f32 v[110:111], v[110:111], v[142:143]
	v_pk_mul_f32 v[116:117], v[116:117], v[144:145]
	v_pk_mul_f32 v[80:81], v[88:89], v[80:81]
	v_and_b32_e32 v119, 0x7fffffff, v85
	v_and_b32_e32 v118, 0x7fffffff, v84
	v_pk_mul_f32 v[82:83], v[82:83], v[102:103]
	v_pk_mul_f32 v[88:89], v[114:115], v[110:111]
	v_pk_mul_f32 v[102:103], v[112:113], v[116:117]
	v_pk_mul_f32 v[110:111], v[92:93], v[80:81]
	v_pk_fma_f32 v[112:113], v[92:93], v[80:81], v[92:93] neg_lo:[1,0,0] neg_hi:[1,0,0]
	v_and_b32_e32 v81, 0x7fffffff, v87
	v_and_b32_e32 v80, 0x7fffffff, v86
	v_pk_fma_f32 v[118:119], v[118:119], s[76:77], 1.0 op_sel_hi:[1,0,0]
	v_pk_fma_f32 v[80:81], v[80:81], s[76:77], 1.0 op_sel_hi:[1,0,0]
	v_rcp_f32_e32 v118, v118
	v_rcp_f32_e32 v119, v119
	v_rcp_f32_e32 v80, v80
	v_rcp_f32_e32 v81, v81
	v_pk_mul_f32 v[120:121], v[86:87], v[86:87]
	v_pk_mul_f32 v[122:123], v[84:85], v[84:85]
	v_pk_fma_f32 v[146:147], v[118:119], s[78:79], v[100:101] op_sel_hi:[1,0,0]
	v_pk_mul_f32 v[122:123], v[122:123], s[52:53] op_sel_hi:[1,0]
	v_pk_mul_f32 v[124:125], v[104:105], v[88:89]
	v_pk_fma_f32 v[126:127], v[104:105], v[88:89], v[104:105] neg_lo:[1,0,0] neg_hi:[1,0,0]
	v_pk_fma_f32 v[88:89], v[80:81], s[78:79], v[100:101] op_sel_hi:[1,0,0]
	v_pk_mul_f32 v[120:121], v[120:121], s[52:53] op_sel_hi:[1,0]
	v_exp_f32_e32 v122, v122
	v_pk_fma_f32 v[146:147], v[118:119], v[146:147], s[96:97] op_sel_hi:[1,1,0]
	v_exp_f32_e32 v123, v123
	v_pk_fma_f32 v[88:89], v[80:81], v[88:89], s[96:97] op_sel_hi:[1,1,0]
	v_exp_f32_e32 v120, v120
	v_exp_f32_e32 v121, v121
	v_pk_fma_f32 v[146:147], v[118:119], v[146:147], s[48:49] op_sel_hi:[1,1,0]
	v_pk_fma_f32 v[88:89], v[80:81], v[88:89], s[48:49] op_sel_hi:[1,1,0]
	v_pk_fma_f32 v[146:147], v[118:119], v[146:147], s[50:51] op_sel_hi:[1,1,0]
	v_pk_fma_f32 v[88:89], v[80:81], v[88:89], s[50:51] op_sel_hi:[1,1,0]
	v_pk_mul_f32 v[118:119], v[118:119], v[146:147]
	v_pk_mul_f32 v[80:81], v[80:81], v[88:89]
	v_pk_mul_f32 v[114:115], v[94:95], v[82:83]
	v_pk_fma_f32 v[116:117], v[94:95], v[82:83], v[94:95] neg_lo:[1,0,0] neg_hi:[1,0,0]
	v_pk_mul_f32 v[82:83], v[122:123], v[118:119]
	v_pk_mul_f32 v[80:81], v[120:121], v[80:81]
; DI unsigned pk2(float a, float b) { f32x2 v = {a, b}; hbf16x2 r = __builtin_convertvector(v, hbf16x2); return __builtin_bit_cast(unsigned, r); }
;     DI void operator()(const f32x4 (&acc)[2][2][4][2], const Unit& u, int wr, int wc, int fr, int fq) const {
;     ...
;                     const f32x2 g0 = gelu_pk((f32x2){a0[0], a0[1]}), g1 = gelu_pk((f32x2){a0[2], a0[3]}), g2 = gelu_pk((f32x2){a1[0], a1[1]}), g3 = gelu_pk((f32x2){a1[2], a1[3]});
;                     s += ((g0.x + g0.y) + (g1.x + g1.y)) + ((g2.x + g2.y) + (g3.x + g3.y));
;                     q += ((g0.x * g0.x + g0.y * g0.y) + (g1.x * g1.x + g1.y * g1.y)) + ((g2.x * g2.x + g2.y * g2.y) + (g3.x * g3.x + g3.y * g3.y));
;                     u32x4 w; w.x = pk2(g0.x, g0.y); w.y = pk2(g1.x, g1.y); w.z = pk2(g2.x, g2.y); w.w = pk2(g3.x, g3.y);
;                     *(u32x4*)(base + (size_t)r * 2048 + colt + bj * HALF) = w; }
;                 if (isv) { s += __shfl_xor(s, 16); s += __shfl_xor(s, 32); q += __shfl_xor(q, 16); q += __shfl_xor(q, 32);
;                     if (fq == 0) *(f32x2*)(STATS + ((size_t)r * 32 + (pn - 8) * 4 + wc) * 2) = (f32x2){s, q}; }
	v_cmp_gt_f32_e32 vcc, 0, v92
	v_pk_mul_f32 v[118:119], v[84:85], v[82:83]
	v_pk_fma_f32 v[82:83], v[84:85], v[82:83], v[84:85] neg_lo:[1,0,0] neg_hi:[1,0,0]
	v_pk_mul_f32 v[120:121], v[86:87], v[80:81]
	v_pk_fma_f32 v[122:123], v[86:87], v[80:81], v[86:87] neg_lo:[1,0,0] neg_hi:[1,0,0]
	v_cndmask_b32_e32 v80, v112, v110, vcc
	v_cmp_gt_f32_e32 vcc, 0, v84
	v_pk_mul_f32 v[142:143], v[90:91], v[102:103]
	v_pk_fma_f32 v[102:103], v[90:91], v[102:103], v[90:91] neg_lo:[1,0,0] neg_hi:[1,0,0]
	v_cndmask_b32_e32 v81, v82, v118, vcc
	v_cmp_gt_f32_e32 vcc, 0, v93
	v_and_b32_e32 v112, 0x7fffffff, v106
	s_nop 0
	v_cndmask_b32_e32 v88, v113, v111, vcc
	v_cmp_gt_f32_e32 vcc, 0, v94
	v_and_b32_e32 v113, 0x7fffffff, v107
	v_pk_fma_f32 v[112:113], v[112:113], s[76:77], 1.0 op_sel_hi:[1,0,0]
	v_cndmask_b32_e32 v82, v116, v114, vcc
	v_cmp_gt_f32_e32 vcc, 0, v85
	v_rcp_f32_e32 v112, v112
	v_rcp_f32_e32 v113, v113
	v_cndmask_b32_e32 v83, v83, v119, vcc
	v_cmp_gt_f32_e32 vcc, 0, v95
	s_nop 1
	v_cndmask_b32_e32 v92, v117, v115, vcc
	v_cmp_gt_f32_e32 vcc, 0, v104
	v_and_b32_e32 v104, 0x7fffffff, v108
	s_nop 0
	v_cndmask_b32_e32 v84, v126, v124, vcc
	v_cmp_gt_f32_e32 vcc, 0, v86
	s_nop 1
	v_cndmask_b32_e32 v85, v122, v120, vcc
	v_cmp_gt_f32_e32 vcc, 0, v105
	v_and_b32_e32 v105, 0x7fffffff, v109
	v_pk_fma_f32 v[104:105], v[104:105], s[76:77], 1.0 op_sel_hi:[1,0,0]
	v_cndmask_b32_e32 v94, v127, v125, vcc
	v_cmp_gt_f32_e32 vcc, 0, v90
	v_rcp_f32_e32 v110, v104
	v_rcp_f32_e32 v111, v105
	v_cndmask_b32_e32 v86, v102, v142, vcc
	v_cmp_gt_f32_e32 vcc, 0, v87
	v_cvt_pk_bf16_f32 v102, v80, v88
	v_cvt_pk_bf16_f32 v104, v84, v94
	v_cndmask_b32_e32 v87, v123, v121, vcc
	v_cmp_gt_f32_e32 vcc, 0, v91
	s_nop 1
	v_cndmask_b32_e32 v90, v103, v143, vcc
	v_cvt_pk_bf16_f32 v103, v82, v92
	v_cvt_pk_bf16_f32 v105, v86, v90
	global_store_dwordx4 v[98:99], v[102:105], off
	v_cmp_gt_f32_e32 vcc, 0, v106
	s_nop 0
	v_pk_fma_f32 v[102:103], v[110:111], s[78:79], v[100:101] op_sel_hi:[1,0,0]
	v_pk_mul_f32 v[104:105], v[106:107], v[106:107]
	v_pk_fma_f32 v[102:103], v[110:111], v[102:103], s[96:97] op_sel_hi:[1,1,0]
	v_pk_fma_f32 v[100:101], v[112:113], s[78:79], v[100:101] op_sel_hi:[1,0,0]
	v_pk_fma_f32 v[102:103], v[110:111], v[102:103], s[48:49] op_sel_hi:[1,1,0]
	v_pk_fma_f32 v[100:101], v[112:113], v[100:101], s[96:97] op_sel_hi:[1,1,0]
	v_pk_fma_f32 v[102:103], v[110:111], v[102:103], s[50:51] op_sel_hi:[1,1,0]
	v_pk_fma_f32 v[100:101], v[112:113], v[100:101], s[48:49] op_sel_hi:[1,1,0]
	v_pk_mul_f32 v[102:103], v[110:111], v[102:103]
	v_pk_mul_f32 v[110:111], v[108:109], v[108:109]
	v_pk_fma_f32 v[100:101], v[112:113], v[100:101], s[50:51] op_sel_hi:[1,1,0]
	v_pk_mul_f32 v[110:111], v[110:111], s[52:53] op_sel_hi:[1,0]
	v_pk_mul_f32 v[100:101], v[112:113], v[100:101]
	v_exp_f32_e32 v110, v110
	v_exp_f32_e32 v111, v111
	s_nop 0
	v_pk_mul_f32 v[102:103], v[110:111], v[102:103]
	s_nop 0
	v_pk_mul_f32 v[110:111], v[108:109], v[102:103]
	v_pk_fma_f32 v[114:115], v[108:109], v[102:103], v[108:109] neg_lo:[1,0,0] neg_hi:[1,0,0]
	v_pk_mul_f32 v[102:103], v[104:105], s[52:53] op_sel_hi:[1,0]
	s_nop 0
	v_exp_f32_e32 v102, v102
	v_exp_f32_e32 v103, v103
	s_nop 0
	v_pk_mul_f32 v[100:101], v[102:103], v[100:101]
	s_nop 0
	v_pk_mul_f32 v[102:103], v[106:107], v[100:101]
	v_pk_fma_f32 v[104:105], v[106:107], v[100:101], v[106:107] neg_lo:[1,0,0] neg_hi:[1,0,0]
	s_nop 0
	v_cndmask_b32_e32 v101, v104, v102, vcc
	v_cmp_gt_f32_e32 vcc, 0, v108
	v_cvt_pk_bf16_f32 v104, v81, v83
	s_nop 0
	v_cndmask_b32_e32 v100, v114, v110, vcc
	v_cmp_gt_f32_e32 vcc, 0, v107
	s_nop 1
	v_cndmask_b32_e32 v103, v105, v103, vcc
	v_cmp_gt_f32_e32 vcc, 0, v109
	v_cvt_pk_bf16_f32 v105, v85, v87
	v_cvt_pk_bf16_f32 v107, v101, v103
	v_cndmask_b32_e32 v102, v115, v111, vcc
	v_cvt_pk_bf16_f32 v106, v100, v102
	s_and_b64 vcc, exec, s[4:5]
	global_store_dwordx4 v[98:99], v[104:107], off offset:256
	s_cbranch_vccnz .LBB0_236
	v_mov_b32_e32 v89, v81
	v_mov_b32_e32 v93, v83
	v_pk_mul_f32 v[104:105], v[88:89], v[88:89]
	v_pk_add_f32 v[118:119], v[80:81], v[88:89]
	v_pk_mul_f32 v[88:89], v[80:81], v[88:89]
	v_mov_b32_e32 v95, v85
	v_pk_mul_f32 v[98:99], v[80:81], v[80:81]
	v_pk_mul_f32 v[108:109], v[92:93], v[92:93]
	v_mov_b32_e32 v119, v89
	v_pk_add_f32 v[88:89], v[82:83], v[92:93]
	v_pk_mul_f32 v[92:93], v[82:83], v[92:93]
	v_mov_b32_e32 v91, v87
	v_pk_mul_f32 v[106:107], v[82:83], v[82:83]
	v_pk_mul_f32 v[112:113], v[94:95], v[94:95]
	v_mov_b32_e32 v89, v93
	v_pk_add_f32 v[92:93], v[84:85], v[94:95]
	v_pk_mul_f32 v[94:95], v[84:85], v[94:95]
	v_pk_mov_b32 v[80:81], v[80:81], v[98:99] op_sel:[1,0]
	v_pk_mov_b32 v[82:83], v[82:83], v[104:105] op_sel:[1,0]
	v_pk_mul_f32 v[110:111], v[84:85], v[84:85]
	v_pk_mul_f32 v[116:117], v[90:91], v[90:91]
	v_mov_b32_e32 v93, v95
	v_pk_add_f32 v[94:95], v[86:87], v[90:91]
	v_pk_mul_f32 v[90:91], v[86:87], v[90:91]
	v_pk_add_f32 v[80:81], v[80:81], v[82:83]
	v_pk_mov_b32 v[82:83], v[84:85], v[106:107] op_sel:[1,0]
	v_pk_mov_b32 v[84:85], v[86:87], v[108:109] op_sel:[1,0]
	v_mov_b32_e32 v95, v91
	v_pk_mul_f32 v[90:91], v[102:103], v[102:103]
	v_pk_add_f32 v[82:83], v[82:83], v[84:85]
	v_pk_mul_f32 v[114:115], v[86:87], v[86:87]
	v_pk_fma_f32 v[90:91], v[100:101], v[100:101], v[90:91]
	v_pk_add_f32 v[80:81], v[80:81], v[82:83]
	v_mov_b32_e32 v82, v100
	v_mov_b32_e32 v83, v110
	v_mov_b32_e32 v84, v102
	v_mov_b32_e32 v85, v112
	v_pk_add_f32 v[90:91], v[90:91], v[90:91] op_sel_hi:[0,1]
	v_cmp_lt_i32_e32 vcc, v248, v243
	v_pk_add_f32 v[82:83], v[82:83], v[84:85]
	v_pk_mov_b32 v[84:85], v[100:101], v[114:115] op_sel:[1,0]
	v_pk_mov_b32 v[86:87], v[102:103], v[116:117] op_sel:[1,0]
	v_cndmask_b32_e32 v90, v241, v248, vcc
	v_pk_add_f32 v[88:89], v[118:119], v[88:89]
	v_pk_add_f32 v[92:93], v[92:93], v[94:95]
	v_pk_add_f32 v[84:85], v[84:85], v[86:87]
	v_lshlrev_b32_e32 v111, 2, v90
	v_pk_add_f32 v[88:89], v[88:89], v[92:93]
	v_mov_b32_e32 v90, v153
	v_pk_add_f32 v[82:83], v[82:83], v[84:85]
	v_pk_add_f32 v[88:89], v[88:89], v[90:91]
	v_pk_add_f32 v[80:81], v[80:81], v[82:83]
	v_cmp_lt_i32_e32 vcc, v249, v243
	v_pk_add_f32 v[80:81], v[80:81], v[88:89]
	ds_bpermute_b32 v82, v111, v80
	ds_bpermute_b32 v83, v111, v81
	v_cndmask_b32_e32 v84, v241, v249, vcc
	v_lshlrev_b32_e32 v84, 2, v84
	s_waitcnt lgkmcnt(0)
	v_pk_add_f32 v[80:81], v[80:81], v[82:83]
	ds_bpermute_b32 v82, v84, v80
	ds_bpermute_b32 v83, v84, v81
	s_and_saveexec_b64 s[28:29], s[0:1]
	s_cbranch_execz .LBB0_235
	v_lshlrev_b64 v[84:85], 8, v[96:97]
	s_waitcnt lgkmcnt(0)
	v_pk_add_f32 v[80:81], v[80:81], v[82:83]
	v_lshl_add_u64 v[82:83], s[18:19], 0, v[84:85]
	v_lshl_add_u64 v[82:83], s[72:73], 3, v[82:83]
	global_store_dwordx2 v[82:83], v[80:81], off

;     DI void operator()(const f32x4 (&acc)[2][2][4][2], const Unit& u, int wr, int wc, int fr, int fq) const {
;     ...
;                 const int r = u.pm * BM + ai * HALF + wr * 64 + m * 16 + fr; float s = 0.f, q = 0.f; const float rs = RS[r];
; #pragma unroll
;                 for (int bj = 0; bj < 2; ++bj) { const f32x4 a0 = acc[ai][bj][m][0] * rs, a1 = acc[ai][bj][m][1] * rs;
;                     const f32x2 g0 = gelu_pk((f32x2){a0[0], a0[1]}), g1 = gelu_pk((f32x2){a0[2], a0[3]}), g2 = gelu_pk((f32x2){a1[0], a1[1]}), g3 = gelu_pk((f32x2){a1[2], a1[3]});
.LBB0_236:
	v_add_u32_e32 v80, 48, v138
	v_ashrrev_i32_e32 v81, 31, v80
	s_waitcnt lgkmcnt(0)
	v_lshl_add_u64 v[82:83], v[80:81], 2, s[14:15]
	v_mov_b64_e32 v[84:85], s[80:81]
	v_lshlrev_b64 v[82:83], 12, v[80:81]
	v_lshl_add_u64 v[82:83], v[140:141], 0, v[82:83]
	v_mov_b32_e32 v86, v202
	v_pk_mul_f32 v[76:77], v[76:77], v[86:87] op_sel_hi:[1,0]
	v_pk_mul_f32 v[78:79], v[78:79], v[86:87] op_sel_hi:[1,0]
	v_pk_mul_f32 v[74:75], v[74:75], v[86:87] op_sel_hi:[1,0]
	v_pk_mul_f32 v[88:89], v[72:73], v[86:87] op_sel_hi:[1,0]
	v_pk_mul_f32 v[92:93], v[64:65], v[86:87] op_sel_hi:[1,0]
	v_and_b32_e32 v65, 0x7fffffff, v77
	v_and_b32_e32 v64, 0x7fffffff, v76
	v_pk_mul_f32 v[70:71], v[70:71], v[86:87] op_sel_hi:[1,0]
	v_pk_mul_f32 v[68:69], v[68:69], v[86:87] op_sel_hi:[1,0]
	v_pk_mul_f32 v[90:91], v[66:67], v[86:87] op_sel_hi:[1,0]
	v_and_b32_e32 v87, 0x7fffffff, v79
	v_and_b32_e32 v86, 0x7fffffff, v78
	v_and_b32_e32 v95, 0x7fffffff, v89
	v_and_b32_e32 v94, 0x7fffffff, v88
	v_and_b32_e32 v101, 0x7fffffff, v75
	v_and_b32_e32 v100, 0x7fffffff, v74
	v_pk_fma_f32 v[64:65], v[64:65], s[76:77], 1.0 op_sel_hi:[1,0,0]
	v_pk_fma_f32 v[86:87], v[86:87], s[76:77], 1.0 op_sel_hi:[1,0,0]
	v_pk_fma_f32 v[94:95], v[94:95], s[76:77], 1.0 op_sel_hi:[1,0,0]
	v_pk_fma_f32 v[100:101], v[100:101], s[76:77], 1.0 op_sel_hi:[1,0,0]
	v_rcp_f32_e32 v64, v64
	v_rcp_f32_e32 v65, v65
	v_rcp_f32_e32 v86, v86
	v_rcp_f32_e32 v87, v87
	v_rcp_f32_e32 v94, v94
	v_rcp_f32_e32 v95, v95
	v_rcp_f32_e32 v100, v100
	v_rcp_f32_e32 v101, v101
	v_pk_mul_f32 v[72:73], v[76:77], v[76:77]
	v_pk_mul_f32 v[66:67], v[78:79], v[78:79]
	v_pk_mul_f32 v[96:97], v[74:75], v[74:75]
	v_pk_mul_f32 v[98:99], v[88:89], v[88:89]
	v_pk_mul_f32 v[72:73], v[72:73], s[52:53] op_sel_hi:[1,0]
	v_pk_fma_f32 v[108:109], v[64:65], s[78:79], v[84:85] op_sel_hi:[1,0,0]
	v_pk_mul_f32 v[66:67], v[66:67], s[52:53] op_sel_hi:[1,0]
	v_pk_mul_f32 v[98:99], v[98:99], s[52:53] op_sel_hi:[1,0]
	v_pk_mul_f32 v[96:97], v[96:97], s[52:53] op_sel_hi:[1,0]
	v_exp_f32_e32 v72, v72
	v_exp_f32_e32 v73, v73
	v_pk_fma_f32 v[110:111], v[86:87], s[78:79], v[84:85] op_sel_hi:[1,0,0]
	v_pk_fma_f32 v[112:113], v[94:95], s[78:79], v[84:85] op_sel_hi:[1,0,0]
	v_pk_fma_f32 v[114:115], v[100:101], s[78:79], v[84:85] op_sel_hi:[1,0,0]
	v_pk_fma_f32 v[108:109], v[64:65], v[108:109], s[96:97] op_sel_hi:[1,1,0]
	v_exp_f32_e32 v66, v66
	v_exp_f32_e32 v67, v67
	v_exp_f32_e32 v98, v98
	v_exp_f32_e32 v99, v99
	v_exp_f32_e32 v96, v96
	v_exp_f32_e32 v97, v97
	v_pk_fma_f32 v[110:111], v[86:87], v[110:111], s[96:97] op_sel_hi:[1,1,0]
	v_pk_fma_f32 v[112:113], v[94:95], v[112:113], s[96:97] op_sel_hi:[1,1,0]
	v_pk_fma_f32 v[114:115], v[100:101], v[114:115], s[96:97] op_sel_hi:[1,1,0]
	v_pk_fma_f32 v[108:109], v[64:65], v[108:109], s[48:49] op_sel_hi:[1,1,0]
	v_pk_fma_f32 v[110:111], v[86:87], v[110:111], s[48:49] op_sel_hi:[1,1,0]
	v_pk_fma_f32 v[112:113], v[94:95], v[112:113], s[48:49] op_sel_hi:[1,1,0]
	v_pk_fma_f32 v[114:115], v[100:101], v[114:115], s[48:49] op_sel_hi:[1,1,0]
	v_pk_fma_f32 v[108:109], v[64:65], v[108:109], s[50:51] op_sel_hi:[1,1,0]
	v_pk_fma_f32 v[110:111], v[86:87], v[110:111], s[50:51] op_sel_hi:[1,1,0]
	v_pk_fma_f32 v[112:113], v[94:95], v[112:113], s[50:51] op_sel_hi:[1,1,0]
	v_pk_fma_f32 v[114:115], v[100:101], v[114:115], s[50:51] op_sel_hi:[1,1,0]
	v_pk_mul_f32 v[64:65], v[64:65], v[108:109]
	v_pk_mul_f32 v[86:87], v[86:87], v[110:111]
	v_pk_mul_f32 v[94:95], v[94:95], v[112:113]
	v_pk_mul_f32 v[100:101], v[100:101], v[114:115]
	v_pk_mul_f32 v[64:65], v[72:73], v[64:65]
	v_and_b32_e32 v103, 0x7fffffff, v69
	v_and_b32_e32 v102, 0x7fffffff, v68
	v_pk_mul_f32 v[66:67], v[66:67], v[86:87]
	v_pk_mul_f32 v[72:73], v[98:99], v[94:95]
	v_pk_mul_f32 v[86:87], v[96:97], v[100:101]
	v_pk_mul_f32 v[94:95], v[76:77], v[64:65]
	v_pk_fma_f32 v[96:97], v[76:77], v[64:65], v[76:77] neg_lo:[1,0,0] neg_hi:[1,0,0]
	v_and_b32_e32 v65, 0x7fffffff, v71
	v_and_b32_e32 v64, 0x7fffffff, v70
	v_pk_fma_f32 v[102:103], v[102:103], s[76:77], 1.0 op_sel_hi:[1,0,0]
	v_pk_fma_f32 v[64:65], v[64:65], s[76:77], 1.0 op_sel_hi:[1,0,0]
	v_rcp_f32_e32 v102, v102
	v_rcp_f32_e32 v103, v103
	v_rcp_f32_e32 v64, v64
	v_rcp_f32_e32 v65, v65
	v_pk_mul_f32 v[104:105], v[70:71], v[70:71]
	v_pk_mul_f32 v[106:107], v[68:69], v[68:69]
	v_pk_fma_f32 v[116:117], v[102:103], s[78:79], v[84:85] op_sel_hi:[1,0,0]
	v_pk_mul_f32 v[106:107], v[106:107], s[52:53] op_sel_hi:[1,0]
	v_pk_mul_f32 v[108:109], v[88:89], v[72:73]
	v_pk_fma_f32 v[110:111], v[88:89], v[72:73], v[88:89] neg_lo:[1,0,0] neg_hi:[1,0,0]
	v_pk_fma_f32 v[72:73], v[64:65], s[78:79], v[84:85] op_sel_hi:[1,0,0]
	v_pk_mul_f32 v[104:105], v[104:105], s[52:53] op_sel_hi:[1,0]
	v_exp_f32_e32 v106, v106
	v_pk_fma_f32 v[116:117], v[102:103], v[116:117], s[96:97] op_sel_hi:[1,1,0]
	v_exp_f32_e32 v107, v107
	v_pk_fma_f32 v[72:73], v[64:65], v[72:73], s[96:97] op_sel_hi:[1,1,0]
	v_exp_f32_e32 v104, v104
	v_exp_f32_e32 v105, v105
	v_pk_fma_f32 v[116:117], v[102:103], v[116:117], s[48:49] op_sel_hi:[1,1,0]
	v_pk_fma_f32 v[72:73], v[64:65], v[72:73], s[48:49] op_sel_hi:[1,1,0]
	v_pk_fma_f32 v[116:117], v[102:103], v[116:117], s[50:51] op_sel_hi:[1,1,0]
	v_pk_fma_f32 v[72:73], v[64:65], v[72:73], s[50:51] op_sel_hi:[1,1,0]
	v_pk_mul_f32 v[102:103], v[102:103], v[116:117]
	v_pk_mul_f32 v[64:65], v[64:65], v[72:73]
	v_pk_mul_f32 v[98:99], v[78:79], v[66:67]
	v_pk_fma_f32 v[100:101], v[78:79], v[66:67], v[78:79] neg_lo:[1,0,0] neg_hi:[1,0,0]
	v_pk_mul_f32 v[66:67], v[106:107], v[102:103]
	v_pk_mul_f32 v[64:65], v[104:105], v[64:65]
	v_cmp_gt_f32_e32 vcc, 0, v76
	v_pk_mul_f32 v[102:103], v[68:69], v[66:67]
; DI unsigned pk2(float a, float b) { f32x2 v = {a, b}; hbf16x2 r = __builtin_convertvector(v, hbf16x2); return __builtin_bit_cast(unsigned, r); }
;     DI void operator()(const f32x4 (&acc)[2][2][4][2], const Unit& u, int wr, int wc, int fr, int fq) const {
;     ...
;                     const f32x2 g0 = gelu_pk((f32x2){a0[0], a0[1]}), g1 = gelu_pk((f32x2){a0[2], a0[3]}), g2 = gelu_pk((f32x2){a1[0], a1[1]}), g3 = gelu_pk((f32x2){a1[2], a1[3]});
;                     s += ((g0.x + g0.y) + (g1.x + g1.y)) + ((g2.x + g2.y) + (g3.x + g3.y));
;                     q += ((g0.x * g0.x + g0.y * g0.y) + (g1.x * g1.x + g1.y * g1.y)) + ((g2.x * g2.x + g2.y * g2.y) + (g3.x * g3.x + g3.y * g3.y));
;                     u32x4 w; w.x = pk2(g0.x, g0.y); w.y = pk2(g1.x, g1.y); w.z = pk2(g2.x, g2.y); w.w = pk2(g3.x, g3.y);
;                     *(u32x4*)(base + (size_t)r * 2048 + colt + bj * HALF) = w; }
;                 if (isv) { s += __shfl_xor(s, 16); s += __shfl_xor(s, 32); q += __shfl_xor(q, 16); q += __shfl_xor(q, 32);
;                     if (fq == 0) *(f32x2*)(STATS + ((size_t)r * 32 + (pn - 8) * 4 + wc) * 2) = (f32x2){s, q}; }
	v_pk_fma_f32 v[66:67], v[68:69], v[66:67], v[68:69] neg_lo:[1,0,0] neg_hi:[1,0,0]
	v_pk_mul_f32 v[104:105], v[70:71], v[64:65]
	v_pk_fma_f32 v[106:107], v[70:71], v[64:65], v[70:71] neg_lo:[1,0,0] neg_hi:[1,0,0]
	v_cndmask_b32_e32 v64, v96, v94, vcc
	v_cmp_gt_f32_e32 vcc, 0, v68
	v_pk_mul_f32 v[112:113], v[74:75], v[86:87]
	v_pk_fma_f32 v[86:87], v[74:75], v[86:87], v[74:75] neg_lo:[1,0,0] neg_hi:[1,0,0]
	v_cndmask_b32_e32 v65, v66, v102, vcc
	v_cmp_gt_f32_e32 vcc, 0, v77
	v_and_b32_e32 v96, 0x7fffffff, v90
	s_nop 0
	v_cndmask_b32_e32 v72, v97, v95, vcc
	v_cmp_gt_f32_e32 vcc, 0, v78
	v_and_b32_e32 v97, 0x7fffffff, v91
	v_pk_fma_f32 v[96:97], v[96:97], s[76:77], 1.0 op_sel_hi:[1,0,0]
	v_cndmask_b32_e32 v66, v100, v98, vcc
	v_cmp_gt_f32_e32 vcc, 0, v69
	v_rcp_f32_e32 v96, v96
	v_rcp_f32_e32 v97, v97
	v_cndmask_b32_e32 v67, v67, v103, vcc
	v_cmp_gt_f32_e32 vcc, 0, v79
	s_nop 1
	v_cndmask_b32_e32 v76, v101, v99, vcc
	v_cmp_gt_f32_e32 vcc, 0, v88
	v_and_b32_e32 v88, 0x7fffffff, v92
	s_nop 0
	v_cndmask_b32_e32 v68, v110, v108, vcc
	v_cmp_gt_f32_e32 vcc, 0, v70
	s_nop 1
	v_cndmask_b32_e32 v69, v106, v104, vcc
	v_cmp_gt_f32_e32 vcc, 0, v89
	v_and_b32_e32 v89, 0x7fffffff, v93
	v_pk_fma_f32 v[88:89], v[88:89], s[76:77], 1.0 op_sel_hi:[1,0,0]
	v_cndmask_b32_e32 v78, v111, v109, vcc
	v_cmp_gt_f32_e32 vcc, 0, v74
	v_rcp_f32_e32 v94, v88
	v_rcp_f32_e32 v95, v89
	v_cndmask_b32_e32 v70, v86, v112, vcc
	v_cmp_gt_f32_e32 vcc, 0, v71
	v_cvt_pk_bf16_f32 v86, v64, v72
	v_cvt_pk_bf16_f32 v88, v68, v78
	v_cndmask_b32_e32 v71, v107, v105, vcc
	v_cmp_gt_f32_e32 vcc, 0, v75
	s_nop 1
	v_cndmask_b32_e32 v74, v87, v113, vcc
	v_cvt_pk_bf16_f32 v87, v66, v76
	v_cvt_pk_bf16_f32 v89, v70, v74
	global_store_dwordx4 v[82:83], v[86:89], off
	v_cmp_gt_f32_e32 vcc, 0, v90
	s_nop 0
	v_pk_fma_f32 v[86:87], v[94:95], s[78:79], v[84:85] op_sel_hi:[1,0,0]
	v_pk_mul_f32 v[88:89], v[90:91], v[90:91]
	v_pk_fma_f32 v[86:87], v[94:95], v[86:87], s[96:97] op_sel_hi:[1,1,0]
	v_pk_fma_f32 v[84:85], v[96:97], s[78:79], v[84:85] op_sel_hi:[1,0,0]
	v_pk_fma_f32 v[86:87], v[94:95], v[86:87], s[48:49] op_sel_hi:[1,1,0]
	v_pk_fma_f32 v[84:85], v[96:97], v[84:85], s[96:97] op_sel_hi:[1,1,0]
	v_pk_fma_f32 v[86:87], v[94:95], v[86:87], s[50:51] op_sel_hi:[1,1,0]
	v_pk_fma_f32 v[84:85], v[96:97], v[84:85], s[48:49] op_sel_hi:[1,1,0]
	v_pk_mul_f32 v[86:87], v[94:95], v[86:87]
	v_pk_mul_f32 v[94:95], v[92:93], v[92:93]
	v_pk_fma_f32 v[84:85], v[96:97], v[84:85], s[50:51] op_sel_hi:[1,1,0]
	v_pk_mul_f32 v[94:95], v[94:95], s[52:53] op_sel_hi:[1,0]
	v_pk_mul_f32 v[84:85], v[96:97], v[84:85]
	v_exp_f32_e32 v94, v94
	v_exp_f32_e32 v95, v95
	s_nop 0
	v_pk_mul_f32 v[86:87], v[94:95], v[86:87]
	s_nop 0
	v_pk_mul_f32 v[94:95], v[92:93], v[86:87]
	v_pk_fma_f32 v[98:99], v[92:93], v[86:87], v[92:93] neg_lo:[1,0,0] neg_hi:[1,0,0]
	v_pk_mul_f32 v[86:87], v[88:89], s[52:53] op_sel_hi:[1,0]
	s_nop 0
	v_exp_f32_e32 v86, v86
	v_exp_f32_e32 v87, v87
	s_nop 0
	v_pk_mul_f32 v[84:85], v[86:87], v[84:85]
	s_nop 0
	v_pk_mul_f32 v[86:87], v[90:91], v[84:85]
	v_pk_fma_f32 v[88:89], v[90:91], v[84:85], v[90:91] neg_lo:[1,0,0] neg_hi:[1,0,0]
	s_nop 0
	v_cndmask_b32_e32 v85, v88, v86, vcc
	v_cmp_gt_f32_e32 vcc, 0, v92
	v_cvt_pk_bf16_f32 v88, v65, v67
	s_nop 0
	v_cndmask_b32_e32 v84, v98, v94, vcc
	v_cmp_gt_f32_e32 vcc, 0, v91
	s_nop 1
	v_cndmask_b32_e32 v87, v89, v87, vcc
	v_cmp_gt_f32_e32 vcc, 0, v93
	v_cvt_pk_bf16_f32 v89, v69, v71
	v_cvt_pk_bf16_f32 v91, v85, v87
	v_cndmask_b32_e32 v86, v99, v95, vcc
	v_cvt_pk_bf16_f32 v90, v84, v86
	s_and_b64 vcc, exec, s[4:5]
	global_store_dwordx4 v[82:83], v[88:91], off offset:256
	s_cbranch_vccnz .LBB0_240
	v_mov_b32_e32 v73, v65
	v_mov_b32_e32 v77, v67
	v_pk_mul_f32 v[88:89], v[72:73], v[72:73]
	v_pk_add_f32 v[102:103], v[64:65], v[72:73]
	v_pk_mul_f32 v[72:73], v[64:65], v[72:73]
	v_mov_b32_e32 v79, v69
	v_pk_mul_f32 v[82:83], v[64:65], v[64:65]
	v_pk_mul_f32 v[92:93], v[76:77], v[76:77]
	v_mov_b32_e32 v103, v73
	v_pk_add_f32 v[72:73], v[66:67], v[76:77]
	v_pk_mul_f32 v[76:77], v[66:67], v[76:77]
	v_mov_b32_e32 v75, v71
	v_pk_mul_f32 v[90:91], v[66:67], v[66:67]
	v_pk_mul_f32 v[96:97], v[78:79], v[78:79]
	v_mov_b32_e32 v73, v77
	v_pk_add_f32 v[76:77], v[68:69], v[78:79]
	v_pk_mul_f32 v[78:79], v[68:69], v[78:79]
	v_pk_mov_b32 v[64:65], v[64:65], v[82:83] op_sel:[1,0]
	v_pk_mov_b32 v[66:67], v[66:67], v[88:89] op_sel:[1,0]
	v_pk_mul_f32 v[94:95], v[68:69], v[68:69]
	v_pk_mul_f32 v[100:101], v[74:75], v[74:75]
	v_mov_b32_e32 v77, v79
	v_pk_add_f32 v[78:79], v[70:71], v[74:75]
	v_pk_mul_f32 v[74:75], v[70:71], v[74:75]
	v_pk_add_f32 v[64:65], v[64:65], v[66:67]
	v_pk_mov_b32 v[66:67], v[68:69], v[90:91] op_sel:[1,0]
	v_pk_mov_b32 v[68:69], v[70:71], v[92:93] op_sel:[1,0]
	v_mov_b32_e32 v79, v75
	v_pk_mul_f32 v[74:75], v[86:87], v[86:87]
	v_pk_add_f32 v[66:67], v[66:67], v[68:69]
	v_pk_mul_f32 v[98:99], v[70:71], v[70:71]
	v_pk_fma_f32 v[74:75], v[84:85], v[84:85], v[74:75]
	v_pk_add_f32 v[64:65], v[64:65], v[66:67]
	v_mov_b32_e32 v66, v84
	v_mov_b32_e32 v67, v94
	v_mov_b32_e32 v68, v86
	v_mov_b32_e32 v69, v96
	v_pk_add_f32 v[74:75], v[74:75], v[74:75] op_sel_hi:[0,1]
	v_cmp_lt_i32_e32 vcc, v248, v243
	v_pk_add_f32 v[66:67], v[66:67], v[68:69]
	v_pk_mov_b32 v[68:69], v[84:85], v[98:99] op_sel:[1,0]
	v_pk_mov_b32 v[70:71], v[86:87], v[100:101] op_sel:[1,0]
	v_cndmask_b32_e32 v74, v241, v248, vcc
	v_pk_add_f32 v[72:73], v[102:103], v[72:73]
	v_pk_add_f32 v[76:77], v[76:77], v[78:79]
	v_pk_add_f32 v[68:69], v[68:69], v[70:71]
	v_lshlrev_b32_e32 v95, 2, v74
	v_pk_add_f32 v[72:73], v[72:73], v[76:77]
	v_mov_b32_e32 v74, v153
	v_pk_add_f32 v[66:67], v[66:67], v[68:69]
	v_pk_add_f32 v[72:73], v[72:73], v[74:75]
	v_pk_add_f32 v[64:65], v[64:65], v[66:67]
	v_cmp_lt_i32_e32 vcc, v249, v243
	v_pk_add_f32 v[64:65], v[64:65], v[72:73]
	ds_bpermute_b32 v66, v95, v64
	ds_bpermute_b32 v67, v95, v65
	v_cndmask_b32_e32 v68, v241, v249, vcc
	v_lshlrev_b32_e32 v68, 2, v68
	s_waitcnt lgkmcnt(0)
	v_pk_add_f32 v[64:65], v[64:65], v[66:67]
	ds_bpermute_b32 v66, v68, v64
	ds_bpermute_b32 v67, v68, v65
	s_and_saveexec_b64 s[28:29], s[0:1]
	s_cbranch_execz .LBB0_239
	v_lshlrev_b64 v[68:69], 8, v[80:81]
	s_waitcnt lgkmcnt(0)
	v_pk_add_f32 v[64:65], v[64:65], v[66:67]
	v_lshl_add_u64 v[66:67], s[18:19], 0, v[68:69]
	v_lshl_add_u64 v[66:67], s[72:73], 3, v[66:67]
	global_store_dwordx2 v[66:67], v[64:65], off

;     DI void operator()(const f32x4 (&acc)[2][2][4][2], const Unit& u, int wr, int wc, int fr, int fq) const {
;     ...
;                 const int r = u.pm * BM + ai * HALF + wr * 64 + m * 16 + fr; float s = 0.f, q = 0.f; const float rs = RS[r];
; #pragma unroll
;                 for (int bj = 0; bj < 2; ++bj) { const f32x4 a0 = acc[ai][bj][m][0] * rs, a1 = acc[ai][bj][m][1] * rs;
;                     const f32x2 g0 = gelu_pk((f32x2){a0[0], a0[1]}), g1 = gelu_pk((f32x2){a0[2], a0[3]}), g2 = gelu_pk((f32x2){a1[0], a1[1]}), g3 = gelu_pk((f32x2){a1[2], a1[3]});
.LBB0_240:
	v_add_u32_e32 v64, 0x80, v138
	v_ashrrev_i32_e32 v65, 31, v64
	s_waitcnt lgkmcnt(0)
	v_lshl_add_u64 v[66:67], v[64:65], 2, s[14:15]
	v_mov_b64_e32 v[68:69], s[80:81]
	v_lshlrev_b64 v[66:67], 12, v[64:65]
	v_lshl_add_u64 v[66:67], v[140:141], 0, v[66:67]
	v_mov_b32_e32 v70, v203
	v_pk_mul_f32 v[60:61], v[60:61], v[70:71] op_sel_hi:[1,0]
	v_pk_mul_f32 v[62:63], v[62:63], v[70:71] op_sel_hi:[1,0]
	v_pk_mul_f32 v[58:59], v[58:59], v[70:71] op_sel_hi:[1,0]
	v_pk_mul_f32 v[72:73], v[56:57], v[70:71] op_sel_hi:[1,0]
	v_pk_mul_f32 v[76:77], v[48:49], v[70:71] op_sel_hi:[1,0]
	v_and_b32_e32 v49, 0x7fffffff, v61
	v_and_b32_e32 v48, 0x7fffffff, v60
	v_pk_mul_f32 v[54:55], v[54:55], v[70:71] op_sel_hi:[1,0]
	v_pk_mul_f32 v[52:53], v[52:53], v[70:71] op_sel_hi:[1,0]
	v_pk_mul_f32 v[74:75], v[50:51], v[70:71] op_sel_hi:[1,0]
	v_and_b32_e32 v71, 0x7fffffff, v63
	v_and_b32_e32 v70, 0x7fffffff, v62
	v_and_b32_e32 v79, 0x7fffffff, v73
	v_and_b32_e32 v78, 0x7fffffff, v72
	v_and_b32_e32 v85, 0x7fffffff, v59
	v_and_b32_e32 v84, 0x7fffffff, v58
	v_pk_fma_f32 v[48:49], v[48:49], s[76:77], 1.0 op_sel_hi:[1,0,0]
	v_pk_fma_f32 v[70:71], v[70:71], s[76:77], 1.0 op_sel_hi:[1,0,0]
	v_pk_fma_f32 v[78:79], v[78:79], s[76:77], 1.0 op_sel_hi:[1,0,0]
	v_pk_fma_f32 v[84:85], v[84:85], s[76:77], 1.0 op_sel_hi:[1,0,0]
	v_rcp_f32_e32 v48, v48
	v_rcp_f32_e32 v49, v49
	v_rcp_f32_e32 v70, v70
	v_rcp_f32_e32 v71, v71
	v_rcp_f32_e32 v78, v78
	v_rcp_f32_e32 v79, v79
	v_rcp_f32_e32 v84, v84
	v_rcp_f32_e32 v85, v85
	v_pk_mul_f32 v[56:57], v[60:61], v[60:61]
	v_pk_mul_f32 v[50:51], v[62:63], v[62:63]
	v_pk_mul_f32 v[80:81], v[58:59], v[58:59]
	v_pk_mul_f32 v[82:83], v[72:73], v[72:73]
	v_pk_mul_f32 v[56:57], v[56:57], s[52:53] op_sel_hi:[1,0]
	v_pk_fma_f32 v[92:93], v[48:49], s[78:79], v[68:69] op_sel_hi:[1,0,0]
	v_pk_mul_f32 v[50:51], v[50:51], s[52:53] op_sel_hi:[1,0]
	v_pk_mul_f32 v[82:83], v[82:83], s[52:53] op_sel_hi:[1,0]
	v_pk_mul_f32 v[80:81], v[80:81], s[52:53] op_sel_hi:[1,0]
	v_exp_f32_e32 v56, v56
	v_exp_f32_e32 v57, v57
	v_pk_fma_f32 v[94:95], v[70:71], s[78:79], v[68:69] op_sel_hi:[1,0,0]
	v_pk_fma_f32 v[96:97], v[78:79], s[78:79], v[68:69] op_sel_hi:[1,0,0]
	v_pk_fma_f32 v[98:99], v[84:85], s[78:79], v[68:69] op_sel_hi:[1,0,0]
	v_pk_fma_f32 v[92:93], v[48:49], v[92:93], s[96:97] op_sel_hi:[1,1,0]
	v_exp_f32_e32 v50, v50
	v_exp_f32_e32 v51, v51
	v_exp_f32_e32 v82, v82
	v_exp_f32_e32 v83, v83
	v_exp_f32_e32 v80, v80
	v_exp_f32_e32 v81, v81
	v_pk_fma_f32 v[94:95], v[70:71], v[94:95], s[96:97] op_sel_hi:[1,1,0]
	v_pk_fma_f32 v[96:97], v[78:79], v[96:97], s[96:97] op_sel_hi:[1,1,0]
	v_pk_fma_f32 v[98:99], v[84:85], v[98:99], s[96:97] op_sel_hi:[1,1,0]
	v_pk_fma_f32 v[92:93], v[48:49], v[92:93], s[48:49] op_sel_hi:[1,1,0]
	v_pk_fma_f32 v[94:95], v[70:71], v[94:95], s[48:49] op_sel_hi:[1,1,0]
	v_pk_fma_f32 v[96:97], v[78:79], v[96:97], s[48:49] op_sel_hi:[1,1,0]
	v_pk_fma_f32 v[98:99], v[84:85], v[98:99], s[48:49] op_sel_hi:[1,1,0]
	v_pk_fma_f32 v[92:93], v[48:49], v[92:93], s[50:51] op_sel_hi:[1,1,0]
	v_pk_fma_f32 v[94:95], v[70:71], v[94:95], s[50:51] op_sel_hi:[1,1,0]
	v_pk_fma_f32 v[96:97], v[78:79], v[96:97], s[50:51] op_sel_hi:[1,1,0]
	v_pk_fma_f32 v[98:99], v[84:85], v[98:99], s[50:51] op_sel_hi:[1,1,0]
	v_pk_mul_f32 v[48:49], v[48:49], v[92:93]
	v_pk_mul_f32 v[70:71], v[70:71], v[94:95]
	v_pk_mul_f32 v[78:79], v[78:79], v[96:97]
	v_pk_mul_f32 v[84:85], v[84:85], v[98:99]
	v_pk_mul_f32 v[48:49], v[56:57], v[48:49]
	v_and_b32_e32 v87, 0x7fffffff, v53
	v_and_b32_e32 v86, 0x7fffffff, v52
	v_pk_mul_f32 v[50:51], v[50:51], v[70:71]
	v_pk_mul_f32 v[56:57], v[82:83], v[78:79]
	v_pk_mul_f32 v[70:71], v[80:81], v[84:85]
	v_pk_mul_f32 v[78:79], v[60:61], v[48:49]
	v_pk_fma_f32 v[80:81], v[60:61], v[48:49], v[60:61] neg_lo:[1,0,0] neg_hi:[1,0,0]
	v_and_b32_e32 v49, 0x7fffffff, v55
	v_and_b32_e32 v48, 0x7fffffff, v54
	v_pk_fma_f32 v[86:87], v[86:87], s[76:77], 1.0 op_sel_hi:[1,0,0]
	v_pk_fma_f32 v[48:49], v[48:49], s[76:77], 1.0 op_sel_hi:[1,0,0]
	v_rcp_f32_e32 v86, v86
	v_rcp_f32_e32 v87, v87
	v_rcp_f32_e32 v48, v48
	v_rcp_f32_e32 v49, v49
	v_pk_mul_f32 v[88:89], v[54:55], v[54:55]
	v_pk_mul_f32 v[90:91], v[52:53], v[52:53]
	v_pk_fma_f32 v[100:101], v[86:87], s[78:79], v[68:69] op_sel_hi:[1,0,0]
	v_pk_mul_f32 v[90:91], v[90:91], s[52:53] op_sel_hi:[1,0]
	v_pk_mul_f32 v[92:93], v[72:73], v[56:57]
	v_pk_fma_f32 v[94:95], v[72:73], v[56:57], v[72:73] neg_lo:[1,0,0] neg_hi:[1,0,0]
	v_pk_fma_f32 v[56:57], v[48:49], s[78:79], v[68:69] op_sel_hi:[1,0,0]
	v_pk_mul_f32 v[88:89], v[88:89], s[52:53] op_sel_hi:[1,0]
	v_exp_f32_e32 v90, v90
	v_pk_fma_f32 v[100:101], v[86:87], v[100:101], s[96:97] op_sel_hi:[1,1,0]
	v_exp_f32_e32 v91, v91
	v_pk_fma_f32 v[56:57], v[48:49], v[56:57], s[96:97] op_sel_hi:[1,1,0]
	v_exp_f32_e32 v88, v88
	v_exp_f32_e32 v89, v89
	v_pk_fma_f32 v[100:101], v[86:87], v[100:101], s[48:49] op_sel_hi:[1,1,0]
	v_pk_fma_f32 v[56:57], v[48:49], v[56:57], s[48:49] op_sel_hi:[1,1,0]
	v_pk_fma_f32 v[100:101], v[86:87], v[100:101], s[50:51] op_sel_hi:[1,1,0]
	v_pk_fma_f32 v[56:57], v[48:49], v[56:57], s[50:51] op_sel_hi:[1,1,0]
	v_pk_mul_f32 v[86:87], v[86:87], v[100:101]
	v_pk_mul_f32 v[48:49], v[48:49], v[56:57]
	v_pk_mul_f32 v[82:83], v[62:63], v[50:51]
	v_pk_fma_f32 v[84:85], v[62:63], v[50:51], v[62:63] neg_lo:[1,0,0] neg_hi:[1,0,0]
	v_pk_mul_f32 v[50:51], v[90:91], v[86:87]
	v_pk_mul_f32 v[48:49], v[88:89], v[48:49]
	v_cmp_gt_f32_e32 vcc, 0, v60
	v_pk_mul_f32 v[86:87], v[52:53], v[50:51]
	v_pk_fma_f32 v[50:51], v[52:53], v[50:51], v[52:53] neg_lo:[1,0,0] neg_hi:[1,0,0]
	v_pk_mul_f32 v[88:89], v[54:55], v[48:49]
	v_pk_fma_f32 v[90:91], v[54:55], v[48:49], v[54:55] neg_lo:[1,0,0] neg_hi:[1,0,0]
; DI unsigned pk2(float a, float b) { f32x2 v = {a, b}; hbf16x2 r = __builtin_convertvector(v, hbf16x2); return __builtin_bit_cast(unsigned, r); }
;     DI void operator()(const f32x4 (&acc)[2][2][4][2], const Unit& u, int wr, int wc, int fr, int fq) const {
;     ...
;                     const f32x2 g0 = gelu_pk((f32x2){a0[0], a0[1]}), g1 = gelu_pk((f32x2){a0[2], a0[3]}), g2 = gelu_pk((f32x2){a1[0], a1[1]}), g3 = gelu_pk((f32x2){a1[2], a1[3]});
;                     s += ((g0.x + g0.y) + (g1.x + g1.y)) + ((g2.x + g2.y) + (g3.x + g3.y));
;                     q += ((g0.x * g0.x + g0.y * g0.y) + (g1.x * g1.x + g1.y * g1.y)) + ((g2.x * g2.x + g2.y * g2.y) + (g3.x * g3.x + g3.y * g3.y));
;                     u32x4 w; w.x = pk2(g0.x, g0.y); w.y = pk2(g1.x, g1.y); w.z = pk2(g2.x, g2.y); w.w = pk2(g3.x, g3.y);
;                     *(u32x4*)(base + (size_t)r * 2048 + colt + bj * HALF) = w; }
;                 if (isv) { s += __shfl_xor(s, 16); s += __shfl_xor(s, 32); q += __shfl_xor(q, 16); q += __shfl_xor(q, 32);
;                     if (fq == 0) *(f32x2*)(STATS + ((size_t)r * 32 + (pn - 8) * 4 + wc) * 2) = (f32x2){s, q}; }
	v_cndmask_b32_e32 v48, v80, v78, vcc
	v_cmp_gt_f32_e32 vcc, 0, v52
	v_pk_mul_f32 v[96:97], v[58:59], v[70:71]
	v_pk_fma_f32 v[70:71], v[58:59], v[70:71], v[58:59] neg_lo:[1,0,0] neg_hi:[1,0,0]
	v_cndmask_b32_e32 v49, v50, v86, vcc
	v_cmp_gt_f32_e32 vcc, 0, v61
	v_and_b32_e32 v80, 0x7fffffff, v74
	s_nop 0
	v_cndmask_b32_e32 v56, v81, v79, vcc
	v_cmp_gt_f32_e32 vcc, 0, v62
	v_and_b32_e32 v81, 0x7fffffff, v75
	v_pk_fma_f32 v[80:81], v[80:81], s[76:77], 1.0 op_sel_hi:[1,0,0]
	v_cndmask_b32_e32 v50, v84, v82, vcc
	v_cmp_gt_f32_e32 vcc, 0, v53
	v_rcp_f32_e32 v80, v80
	v_rcp_f32_e32 v81, v81
	v_cndmask_b32_e32 v51, v51, v87, vcc
	v_cmp_gt_f32_e32 vcc, 0, v63
	s_nop 1
	v_cndmask_b32_e32 v60, v85, v83, vcc
	v_cmp_gt_f32_e32 vcc, 0, v72
	v_and_b32_e32 v72, 0x7fffffff, v76
	s_nop 0
	v_cndmask_b32_e32 v52, v94, v92, vcc
	v_cmp_gt_f32_e32 vcc, 0, v54
	s_nop 1
	v_cndmask_b32_e32 v53, v90, v88, vcc
	v_cmp_gt_f32_e32 vcc, 0, v73
	v_and_b32_e32 v73, 0x7fffffff, v77
	v_pk_fma_f32 v[72:73], v[72:73], s[76:77], 1.0 op_sel_hi:[1,0,0]
	v_cndmask_b32_e32 v62, v95, v93, vcc
	v_cmp_gt_f32_e32 vcc, 0, v58
	v_rcp_f32_e32 v78, v72
	v_rcp_f32_e32 v79, v73
	v_cndmask_b32_e32 v54, v70, v96, vcc
	v_cmp_gt_f32_e32 vcc, 0, v55
	v_cvt_pk_bf16_f32 v70, v48, v56
	v_cvt_pk_bf16_f32 v72, v52, v62
	v_cndmask_b32_e32 v55, v91, v89, vcc
	v_cmp_gt_f32_e32 vcc, 0, v59
	s_nop 1
	v_cndmask_b32_e32 v58, v71, v97, vcc
	v_cvt_pk_bf16_f32 v71, v50, v60
	v_cvt_pk_bf16_f32 v73, v54, v58
	global_store_dwordx4 v[66:67], v[70:73], off
	v_cmp_gt_f32_e32 vcc, 0, v74
	s_nop 0
	v_pk_fma_f32 v[70:71], v[78:79], s[78:79], v[68:69] op_sel_hi:[1,0,0]
	v_pk_mul_f32 v[72:73], v[74:75], v[74:75]
	v_pk_fma_f32 v[70:71], v[78:79], v[70:71], s[96:97] op_sel_hi:[1,1,0]
	v_pk_fma_f32 v[68:69], v[80:81], s[78:79], v[68:69] op_sel_hi:[1,0,0]
	v_pk_fma_f32 v[70:71], v[78:79], v[70:71], s[48:49] op_sel_hi:[1,1,0]
	v_pk_fma_f32 v[68:69], v[80:81], v[68:69], s[96:97] op_sel_hi:[1,1,0]
	v_pk_fma_f32 v[70:71], v[78:79], v[70:71], s[50:51] op_sel_hi:[1,1,0]
	v_pk_fma_f32 v[68:69], v[80:81], v[68:69], s[48:49] op_sel_hi:[1,1,0]
	v_pk_mul_f32 v[70:71], v[78:79], v[70:71]
	v_pk_mul_f32 v[78:79], v[76:77], v[76:77]
	v_pk_fma_f32 v[68:69], v[80:81], v[68:69], s[50:51] op_sel_hi:[1,1,0]
	v_pk_mul_f32 v[78:79], v[78:79], s[52:53] op_sel_hi:[1,0]
	v_pk_mul_f32 v[68:69], v[80:81], v[68:69]
	v_exp_f32_e32 v78, v78
	v_exp_f32_e32 v79, v79
	s_nop 0
	v_pk_mul_f32 v[70:71], v[78:79], v[70:71]
	s_nop 0
	v_pk_mul_f32 v[78:79], v[76:77], v[70:71]
	v_pk_fma_f32 v[82:83], v[76:77], v[70:71], v[76:77] neg_lo:[1,0,0] neg_hi:[1,0,0]
	v_pk_mul_f32 v[70:71], v[72:73], s[52:53] op_sel_hi:[1,0]
	s_nop 0
	v_exp_f32_e32 v70, v70
	v_exp_f32_e32 v71, v71
	s_nop 0
	v_pk_mul_f32 v[68:69], v[70:71], v[68:69]
	s_nop 0
	v_pk_mul_f32 v[70:71], v[74:75], v[68:69]
	v_pk_fma_f32 v[72:73], v[74:75], v[68:69], v[74:75] neg_lo:[1,0,0] neg_hi:[1,0,0]
	s_nop 0
	v_cndmask_b32_e32 v69, v72, v70, vcc
	v_cmp_gt_f32_e32 vcc, 0, v76
	v_cvt_pk_bf16_f32 v72, v49, v51
	s_nop 0
	v_cndmask_b32_e32 v68, v82, v78, vcc
	v_cmp_gt_f32_e32 vcc, 0, v75
	s_nop 1
	v_cndmask_b32_e32 v71, v73, v71, vcc
	v_cmp_gt_f32_e32 vcc, 0, v77
	v_cvt_pk_bf16_f32 v73, v53, v55
	v_cvt_pk_bf16_f32 v75, v69, v71
	v_cndmask_b32_e32 v70, v83, v79, vcc
	v_cvt_pk_bf16_f32 v74, v68, v70
	s_and_b64 vcc, exec, s[4:5]
	global_store_dwordx4 v[66:67], v[72:75], off offset:256
	s_cbranch_vccnz .LBB0_244
	v_mov_b32_e32 v57, v49
	v_mov_b32_e32 v61, v51
	v_pk_mul_f32 v[72:73], v[56:57], v[56:57]
	v_pk_add_f32 v[86:87], v[48:49], v[56:57]
	v_pk_mul_f32 v[56:57], v[48:49], v[56:57]
	v_mov_b32_e32 v63, v53
	v_pk_mul_f32 v[66:67], v[48:49], v[48:49]
	v_pk_mul_f32 v[76:77], v[60:61], v[60:61]
	v_mov_b32_e32 v87, v57
	v_pk_add_f32 v[56:57], v[50:51], v[60:61]
	v_pk_mul_f32 v[60:61], v[50:51], v[60:61]
	v_mov_b32_e32 v59, v55
	v_pk_mul_f32 v[74:75], v[50:51], v[50:51]
	v_pk_mul_f32 v[80:81], v[62:63], v[62:63]
	v_mov_b32_e32 v57, v61
	v_pk_add_f32 v[60:61], v[52:53], v[62:63]
	v_pk_mul_f32 v[62:63], v[52:53], v[62:63]
	v_pk_mov_b32 v[48:49], v[48:49], v[66:67] op_sel:[1,0]
	v_pk_mov_b32 v[50:51], v[50:51], v[72:73] op_sel:[1,0]
	v_pk_mul_f32 v[78:79], v[52:53], v[52:53]
	v_pk_mul_f32 v[84:85], v[58:59], v[58:59]
	v_mov_b32_e32 v61, v63
	v_pk_add_f32 v[62:63], v[54:55], v[58:59]
	v_pk_mul_f32 v[58:59], v[54:55], v[58:59]
	v_pk_add_f32 v[48:49], v[48:49], v[50:51]
	v_pk_mov_b32 v[50:51], v[52:53], v[74:75] op_sel:[1,0]
	v_pk_mov_b32 v[52:53], v[54:55], v[76:77] op_sel:[1,0]
	v_mov_b32_e32 v63, v59
	v_pk_mul_f32 v[58:59], v[70:71], v[70:71]
	v_pk_add_f32 v[50:51], v[50:51], v[52:53]
	v_pk_mul_f32 v[82:83], v[54:55], v[54:55]
	v_pk_fma_f32 v[58:59], v[68:69], v[68:69], v[58:59]
	v_pk_add_f32 v[48:49], v[48:49], v[50:51]
	v_mov_b32_e32 v50, v68
	v_mov_b32_e32 v51, v78
	v_mov_b32_e32 v52, v70
	v_mov_b32_e32 v53, v80
	v_pk_add_f32 v[58:59], v[58:59], v[58:59] op_sel_hi:[0,1]
	v_cmp_lt_i32_e32 vcc, v248, v243
	v_pk_add_f32 v[50:51], v[50:51], v[52:53]
	v_pk_mov_b32 v[52:53], v[68:69], v[82:83] op_sel:[1,0]
	v_pk_mov_b32 v[54:55], v[70:71], v[84:85] op_sel:[1,0]
	v_cndmask_b32_e32 v58, v241, v248, vcc
	v_pk_add_f32 v[56:57], v[86:87], v[56:57]
	v_pk_add_f32 v[60:61], v[60:61], v[62:63]
	v_pk_add_f32 v[52:53], v[52:53], v[54:55]
	v_lshlrev_b32_e32 v79, 2, v58
	v_pk_add_f32 v[56:57], v[56:57], v[60:61]
	v_mov_b32_e32 v58, v153
	v_pk_add_f32 v[50:51], v[50:51], v[52:53]
	v_pk_add_f32 v[56:57], v[56:57], v[58:59]
	v_pk_add_f32 v[48:49], v[48:49], v[50:51]
	v_cmp_lt_i32_e32 vcc, v249, v243
	v_pk_add_f32 v[48:49], v[48:49], v[56:57]
	ds_bpermute_b32 v50, v79, v48
	ds_bpermute_b32 v51, v79, v49
	v_cndmask_b32_e32 v52, v241, v249, vcc
	v_lshlrev_b32_e32 v52, 2, v52
	s_waitcnt lgkmcnt(0)
	v_pk_add_f32 v[48:49], v[48:49], v[50:51]
	ds_bpermute_b32 v50, v52, v48
	ds_bpermute_b32 v51, v52, v49
	s_and_saveexec_b64 s[28:29], s[0:1]
	s_cbranch_execz .LBB0_243
	v_lshlrev_b64 v[52:53], 8, v[64:65]
	s_waitcnt lgkmcnt(0)
	v_pk_add_f32 v[48:49], v[48:49], v[50:51]
	v_lshl_add_u64 v[50:51], s[18:19], 0, v[52:53]
	v_lshl_add_u64 v[50:51], s[72:73], 3, v[50:51]
	global_store_dwordx2 v[50:51], v[48:49], off

;     DI void operator()(const f32x4 (&acc)[2][2][4][2], const Unit& u, int wr, int wc, int fr, int fq) const {
;     ...
;                 const int r = u.pm * BM + ai * HALF + wr * 64 + m * 16 + fr; float s = 0.f, q = 0.f; const float rs = RS[r];
; #pragma unroll
;                 for (int bj = 0; bj < 2; ++bj) { const f32x4 a0 = acc[ai][bj][m][0] * rs, a1 = acc[ai][bj][m][1] * rs;
;                     const f32x2 g0 = gelu_pk((f32x2){a0[0], a0[1]}), g1 = gelu_pk((f32x2){a0[2], a0[3]}), g2 = gelu_pk((f32x2){a1[0], a1[1]}), g3 = gelu_pk((f32x2){a1[2], a1[3]});
.LBB0_244:
	v_add_u32_e32 v48, 0x90, v138
	v_ashrrev_i32_e32 v49, 31, v48
	s_waitcnt lgkmcnt(0)
	v_lshl_add_u64 v[50:51], v[48:49], 2, s[14:15]
	v_mov_b64_e32 v[52:53], s[80:81]
	v_lshlrev_b64 v[50:51], 12, v[48:49]
	v_lshl_add_u64 v[50:51], v[140:141], 0, v[50:51]
	v_mov_b32_e32 v54, v204
	v_pk_mul_f32 v[44:45], v[44:45], v[54:55] op_sel_hi:[1,0]
	v_pk_mul_f32 v[46:47], v[46:47], v[54:55] op_sel_hi:[1,0]
	v_pk_mul_f32 v[42:43], v[42:43], v[54:55] op_sel_hi:[1,0]
	v_pk_mul_f32 v[56:57], v[40:41], v[54:55] op_sel_hi:[1,0]
	v_pk_mul_f32 v[60:61], v[32:33], v[54:55] op_sel_hi:[1,0]
	v_and_b32_e32 v33, 0x7fffffff, v45
	v_and_b32_e32 v32, 0x7fffffff, v44
	v_pk_mul_f32 v[38:39], v[38:39], v[54:55] op_sel_hi:[1,0]
	v_pk_mul_f32 v[36:37], v[36:37], v[54:55] op_sel_hi:[1,0]
	v_pk_mul_f32 v[58:59], v[34:35], v[54:55] op_sel_hi:[1,0]
	v_and_b32_e32 v55, 0x7fffffff, v47
	v_and_b32_e32 v54, 0x7fffffff, v46
	v_and_b32_e32 v63, 0x7fffffff, v57
	v_and_b32_e32 v62, 0x7fffffff, v56
	v_and_b32_e32 v69, 0x7fffffff, v43
	v_and_b32_e32 v68, 0x7fffffff, v42
	v_pk_fma_f32 v[32:33], v[32:33], s[76:77], 1.0 op_sel_hi:[1,0,0]
	v_pk_fma_f32 v[54:55], v[54:55], s[76:77], 1.0 op_sel_hi:[1,0,0]
	v_pk_fma_f32 v[62:63], v[62:63], s[76:77], 1.0 op_sel_hi:[1,0,0]
	v_pk_fma_f32 v[68:69], v[68:69], s[76:77], 1.0 op_sel_hi:[1,0,0]
	v_rcp_f32_e32 v32, v32
	v_rcp_f32_e32 v33, v33
	v_rcp_f32_e32 v54, v54
	v_rcp_f32_e32 v55, v55
	v_rcp_f32_e32 v62, v62
	v_rcp_f32_e32 v63, v63
	v_rcp_f32_e32 v68, v68
	v_rcp_f32_e32 v69, v69
	v_pk_mul_f32 v[40:41], v[44:45], v[44:45]
	v_pk_mul_f32 v[34:35], v[46:47], v[46:47]
	v_pk_mul_f32 v[64:65], v[42:43], v[42:43]
	v_pk_mul_f32 v[66:67], v[56:57], v[56:57]
	v_pk_mul_f32 v[40:41], v[40:41], s[52:53] op_sel_hi:[1,0]
	v_pk_fma_f32 v[76:77], v[32:33], s[78:79], v[52:53] op_sel_hi:[1,0,0]
	v_pk_mul_f32 v[34:35], v[34:35], s[52:53] op_sel_hi:[1,0]
	v_pk_mul_f32 v[66:67], v[66:67], s[52:53] op_sel_hi:[1,0]
	v_pk_mul_f32 v[64:65], v[64:65], s[52:53] op_sel_hi:[1,0]
	v_exp_f32_e32 v40, v40
	v_exp_f32_e32 v41, v41
	v_pk_fma_f32 v[78:79], v[54:55], s[78:79], v[52:53] op_sel_hi:[1,0,0]
	v_pk_fma_f32 v[80:81], v[62:63], s[78:79], v[52:53] op_sel_hi:[1,0,0]
	v_pk_fma_f32 v[82:83], v[68:69], s[78:79], v[52:53] op_sel_hi:[1,0,0]
	v_pk_fma_f32 v[76:77], v[32:33], v[76:77], s[96:97] op_sel_hi:[1,1,0]
	v_exp_f32_e32 v34, v34
	v_exp_f32_e32 v35, v35
	v_exp_f32_e32 v66, v66
	v_exp_f32_e32 v67, v67
	v_exp_f32_e32 v64, v64
	v_exp_f32_e32 v65, v65
	v_pk_fma_f32 v[78:79], v[54:55], v[78:79], s[96:97] op_sel_hi:[1,1,0]
	v_pk_fma_f32 v[80:81], v[62:63], v[80:81], s[96:97] op_sel_hi:[1,1,0]
	v_pk_fma_f32 v[82:83], v[68:69], v[82:83], s[96:97] op_sel_hi:[1,1,0]
	v_pk_fma_f32 v[76:77], v[32:33], v[76:77], s[48:49] op_sel_hi:[1,1,0]
	v_pk_fma_f32 v[78:79], v[54:55], v[78:79], s[48:49] op_sel_hi:[1,1,0]
	v_pk_fma_f32 v[80:81], v[62:63], v[80:81], s[48:49] op_sel_hi:[1,1,0]
	v_pk_fma_f32 v[82:83], v[68:69], v[82:83], s[48:49] op_sel_hi:[1,1,0]
	v_pk_fma_f32 v[76:77], v[32:33], v[76:77], s[50:51] op_sel_hi:[1,1,0]
	v_pk_fma_f32 v[78:79], v[54:55], v[78:79], s[50:51] op_sel_hi:[1,1,0]
	v_pk_fma_f32 v[80:81], v[62:63], v[80:81], s[50:51] op_sel_hi:[1,1,0]
	v_pk_fma_f32 v[82:83], v[68:69], v[82:83], s[50:51] op_sel_hi:[1,1,0]
	v_pk_mul_f32 v[32:33], v[32:33], v[76:77]
	v_pk_mul_f32 v[54:55], v[54:55], v[78:79]
	v_pk_mul_f32 v[62:63], v[62:63], v[80:81]
	v_pk_mul_f32 v[68:69], v[68:69], v[82:83]
	v_pk_mul_f32 v[32:33], v[40:41], v[32:33]
	v_and_b32_e32 v71, 0x7fffffff, v37
	v_and_b32_e32 v70, 0x7fffffff, v36
	v_pk_mul_f32 v[34:35], v[34:35], v[54:55]
	v_pk_mul_f32 v[40:41], v[66:67], v[62:63]
	v_pk_mul_f32 v[54:55], v[64:65], v[68:69]
	v_pk_mul_f32 v[62:63], v[44:45], v[32:33]
	v_pk_fma_f32 v[64:65], v[44:45], v[32:33], v[44:45] neg_lo:[1,0,0] neg_hi:[1,0,0]
	v_and_b32_e32 v33, 0x7fffffff, v39
	v_and_b32_e32 v32, 0x7fffffff, v38
	v_pk_fma_f32 v[70:71], v[70:71], s[76:77], 1.0 op_sel_hi:[1,0,0]
	v_pk_fma_f32 v[32:33], v[32:33], s[76:77], 1.0 op_sel_hi:[1,0,0]
	v_rcp_f32_e32 v70, v70
	v_rcp_f32_e32 v71, v71
	v_rcp_f32_e32 v32, v32
	v_rcp_f32_e32 v33, v33
	v_pk_mul_f32 v[72:73], v[38:39], v[38:39]
	v_pk_mul_f32 v[74:75], v[36:37], v[36:37]
	v_pk_fma_f32 v[84:85], v[70:71], s[78:79], v[52:53] op_sel_hi:[1,0,0]
	v_pk_mul_f32 v[74:75], v[74:75], s[52:53] op_sel_hi:[1,0]
	v_pk_mul_f32 v[76:77], v[56:57], v[40:41]
	v_pk_fma_f32 v[78:79], v[56:57], v[40:41], v[56:57] neg_lo:[1,0,0] neg_hi:[1,0,0]
	v_pk_fma_f32 v[40:41], v[32:33], s[78:79], v[52:53] op_sel_hi:[1,0,0]
	v_pk_mul_f32 v[72:73], v[72:73], s[52:53] op_sel_hi:[1,0]
	v_exp_f32_e32 v74, v74
	v_pk_fma_f32 v[84:85], v[70:71], v[84:85], s[96:97] op_sel_hi:[1,1,0]
	v_exp_f32_e32 v75, v75
	v_pk_fma_f32 v[40:41], v[32:33], v[40:41], s[96:97] op_sel_hi:[1,1,0]
	v_exp_f32_e32 v72, v72
	v_exp_f32_e32 v73, v73
	v_pk_fma_f32 v[84:85], v[70:71], v[84:85], s[48:49] op_sel_hi:[1,1,0]
	v_pk_fma_f32 v[40:41], v[32:33], v[40:41], s[48:49] op_sel_hi:[1,1,0]
	v_pk_fma_f32 v[84:85], v[70:71], v[84:85], s[50:51] op_sel_hi:[1,1,0]
	v_pk_fma_f32 v[40:41], v[32:33], v[40:41], s[50:51] op_sel_hi:[1,1,0]
	v_pk_mul_f32 v[70:71], v[70:71], v[84:85]
	v_pk_mul_f32 v[32:33], v[32:33], v[40:41]
	v_pk_mul_f32 v[66:67], v[46:47], v[34:35]
	v_pk_fma_f32 v[68:69], v[46:47], v[34:35], v[46:47] neg_lo:[1,0,0] neg_hi:[1,0,0]
	v_pk_mul_f32 v[34:35], v[74:75], v[70:71]
	v_pk_mul_f32 v[32:33], v[72:73], v[32:33]
	v_cmp_gt_f32_e32 vcc, 0, v44
	v_pk_mul_f32 v[70:71], v[36:37], v[34:35]
	v_pk_fma_f32 v[34:35], v[36:37], v[34:35], v[36:37] neg_lo:[1,0,0] neg_hi:[1,0,0]
	v_pk_mul_f32 v[72:73], v[38:39], v[32:33]
	v_pk_fma_f32 v[74:75], v[38:39], v[32:33], v[38:39] neg_lo:[1,0,0] neg_hi:[1,0,0]
; DI unsigned pk2(float a, float b) { f32x2 v = {a, b}; hbf16x2 r = __builtin_convertvector(v, hbf16x2); return __builtin_bit_cast(unsigned, r); }
;     DI void operator()(const f32x4 (&acc)[2][2][4][2], const Unit& u, int wr, int wc, int fr, int fq) const {
;     ...
;                     const f32x2 g0 = gelu_pk((f32x2){a0[0], a0[1]}), g1 = gelu_pk((f32x2){a0[2], a0[3]}), g2 = gelu_pk((f32x2){a1[0], a1[1]}), g3 = gelu_pk((f32x2){a1[2], a1[3]});
;                     s += ((g0.x + g0.y) + (g1.x + g1.y)) + ((g2.x + g2.y) + (g3.x + g3.y));
;                     q += ((g0.x * g0.x + g0.y * g0.y) + (g1.x * g1.x + g1.y * g1.y)) + ((g2.x * g2.x + g2.y * g2.y) + (g3.x * g3.x + g3.y * g3.y));
;                     u32x4 w; w.x = pk2(g0.x, g0.y); w.y = pk2(g1.x, g1.y); w.z = pk2(g2.x, g2.y); w.w = pk2(g3.x, g3.y);
;                     *(u32x4*)(base + (size_t)r * 2048 + colt + bj * HALF) = w; }
;                 if (isv) { s += __shfl_xor(s, 16); s += __shfl_xor(s, 32); q += __shfl_xor(q, 16); q += __shfl_xor(q, 32);
;                     if (fq == 0) *(f32x2*)(STATS + ((size_t)r * 32 + (pn - 8) * 4 + wc) * 2) = (f32x2){s, q}; }
	v_cndmask_b32_e32 v32, v64, v62, vcc
	v_cmp_gt_f32_e32 vcc, 0, v36
	v_pk_mul_f32 v[80:81], v[42:43], v[54:55]
	v_pk_fma_f32 v[54:55], v[42:43], v[54:55], v[42:43] neg_lo:[1,0,0] neg_hi:[1,0,0]
	v_cndmask_b32_e32 v33, v34, v70, vcc
	v_cmp_gt_f32_e32 vcc, 0, v45
	v_and_b32_e32 v64, 0x7fffffff, v58
	s_nop 0
	v_cndmask_b32_e32 v40, v65, v63, vcc
	v_cmp_gt_f32_e32 vcc, 0, v46
	v_and_b32_e32 v65, 0x7fffffff, v59
	v_pk_fma_f32 v[64:65], v[64:65], s[76:77], 1.0 op_sel_hi:[1,0,0]
	v_cndmask_b32_e32 v34, v68, v66, vcc
	v_cmp_gt_f32_e32 vcc, 0, v37
	v_rcp_f32_e32 v64, v64
	v_rcp_f32_e32 v65, v65
	v_cndmask_b32_e32 v35, v35, v71, vcc
	v_cmp_gt_f32_e32 vcc, 0, v47
	s_nop 1
	v_cndmask_b32_e32 v44, v69, v67, vcc
	v_cmp_gt_f32_e32 vcc, 0, v56
	v_and_b32_e32 v56, 0x7fffffff, v60
	s_nop 0
	v_cndmask_b32_e32 v36, v78, v76, vcc
	v_cmp_gt_f32_e32 vcc, 0, v38
	s_nop 1
	v_cndmask_b32_e32 v37, v74, v72, vcc
	v_cmp_gt_f32_e32 vcc, 0, v57
	v_and_b32_e32 v57, 0x7fffffff, v61
	v_pk_fma_f32 v[56:57], v[56:57], s[76:77], 1.0 op_sel_hi:[1,0,0]
	v_cndmask_b32_e32 v46, v79, v77, vcc
	v_cmp_gt_f32_e32 vcc, 0, v42
	v_rcp_f32_e32 v62, v56
	v_rcp_f32_e32 v63, v57
	v_cndmask_b32_e32 v38, v54, v80, vcc
	v_cmp_gt_f32_e32 vcc, 0, v39
	v_cvt_pk_bf16_f32 v54, v32, v40
	v_cvt_pk_bf16_f32 v56, v36, v46
	v_cndmask_b32_e32 v39, v75, v73, vcc
	v_cmp_gt_f32_e32 vcc, 0, v43
	s_nop 1
	v_cndmask_b32_e32 v42, v55, v81, vcc
	v_cvt_pk_bf16_f32 v55, v34, v44
	v_cvt_pk_bf16_f32 v57, v38, v42
	global_store_dwordx4 v[50:51], v[54:57], off
	v_cmp_gt_f32_e32 vcc, 0, v58
	s_nop 0
	v_pk_fma_f32 v[54:55], v[62:63], s[78:79], v[52:53] op_sel_hi:[1,0,0]
	v_pk_mul_f32 v[56:57], v[58:59], v[58:59]
	v_pk_fma_f32 v[54:55], v[62:63], v[54:55], s[96:97] op_sel_hi:[1,1,0]
	v_pk_fma_f32 v[52:53], v[64:65], s[78:79], v[52:53] op_sel_hi:[1,0,0]
	v_pk_fma_f32 v[54:55], v[62:63], v[54:55], s[48:49] op_sel_hi:[1,1,0]
	v_pk_fma_f32 v[52:53], v[64:65], v[52:53], s[96:97] op_sel_hi:[1,1,0]
	v_pk_fma_f32 v[54:55], v[62:63], v[54:55], s[50:51] op_sel_hi:[1,1,0]
	v_pk_fma_f32 v[52:53], v[64:65], v[52:53], s[48:49] op_sel_hi:[1,1,0]
	v_pk_mul_f32 v[54:55], v[62:63], v[54:55]
	v_pk_mul_f32 v[62:63], v[60:61], v[60:61]
	v_pk_fma_f32 v[52:53], v[64:65], v[52:53], s[50:51] op_sel_hi:[1,1,0]
	v_pk_mul_f32 v[62:63], v[62:63], s[52:53] op_sel_hi:[1,0]
	v_pk_mul_f32 v[52:53], v[64:65], v[52:53]
	v_exp_f32_e32 v62, v62
	v_exp_f32_e32 v63, v63
	s_nop 0
	v_pk_mul_f32 v[54:55], v[62:63], v[54:55]
	s_nop 0
	v_pk_mul_f32 v[62:63], v[60:61], v[54:55]
	v_pk_fma_f32 v[66:67], v[60:61], v[54:55], v[60:61] neg_lo:[1,0,0] neg_hi:[1,0,0]
	v_pk_mul_f32 v[54:55], v[56:57], s[52:53] op_sel_hi:[1,0]
	s_nop 0
	v_exp_f32_e32 v54, v54
	v_exp_f32_e32 v55, v55
	s_nop 0
	v_pk_mul_f32 v[52:53], v[54:55], v[52:53]
	s_nop 0
	v_pk_mul_f32 v[54:55], v[58:59], v[52:53]
	v_pk_fma_f32 v[56:57], v[58:59], v[52:53], v[58:59] neg_lo:[1,0,0] neg_hi:[1,0,0]
	s_nop 0
	v_cndmask_b32_e32 v53, v56, v54, vcc
	v_cmp_gt_f32_e32 vcc, 0, v60
	v_cvt_pk_bf16_f32 v56, v33, v35
	s_nop 0
	v_cndmask_b32_e32 v52, v66, v62, vcc
	v_cmp_gt_f32_e32 vcc, 0, v59
	s_nop 1
	v_cndmask_b32_e32 v55, v57, v55, vcc
	v_cmp_gt_f32_e32 vcc, 0, v61
	v_cvt_pk_bf16_f32 v57, v37, v39
	v_cvt_pk_bf16_f32 v59, v53, v55
	v_cndmask_b32_e32 v54, v67, v63, vcc
	v_cvt_pk_bf16_f32 v58, v52, v54
	s_and_b64 vcc, exec, s[4:5]
	global_store_dwordx4 v[50:51], v[56:59], off offset:256
	s_cbranch_vccnz .LBB0_248
	v_mov_b32_e32 v41, v33
	v_mov_b32_e32 v45, v35
	v_pk_mul_f32 v[56:57], v[40:41], v[40:41]
	v_pk_add_f32 v[70:71], v[32:33], v[40:41]
	v_pk_mul_f32 v[40:41], v[32:33], v[40:41]
	v_mov_b32_e32 v47, v37
	v_pk_mul_f32 v[50:51], v[32:33], v[32:33]
	v_pk_mul_f32 v[60:61], v[44:45], v[44:45]
	v_mov_b32_e32 v71, v41
	v_pk_add_f32 v[40:41], v[34:35], v[44:45]
	v_pk_mul_f32 v[44:45], v[34:35], v[44:45]
	v_mov_b32_e32 v43, v39
	v_pk_mul_f32 v[58:59], v[34:35], v[34:35]
	v_pk_mul_f32 v[64:65], v[46:47], v[46:47]
	v_mov_b32_e32 v41, v45
	v_pk_add_f32 v[44:45], v[36:37], v[46:47]
	v_pk_mul_f32 v[46:47], v[36:37], v[46:47]
	v_pk_mov_b32 v[32:33], v[32:33], v[50:51] op_sel:[1,0]
	v_pk_mov_b32 v[34:35], v[34:35], v[56:57] op_sel:[1,0]
	v_pk_mul_f32 v[62:63], v[36:37], v[36:37]
	v_pk_mul_f32 v[68:69], v[42:43], v[42:43]
	v_mov_b32_e32 v45, v47
	v_pk_add_f32 v[46:47], v[38:39], v[42:43]
	v_pk_mul_f32 v[42:43], v[38:39], v[42:43]
	v_pk_add_f32 v[32:33], v[32:33], v[34:35]
	v_pk_mov_b32 v[34:35], v[36:37], v[58:59] op_sel:[1,0]
	v_pk_mov_b32 v[36:37], v[38:39], v[60:61] op_sel:[1,0]
	v_mov_b32_e32 v47, v43
	v_pk_mul_f32 v[42:43], v[54:55], v[54:55]
	v_pk_add_f32 v[34:35], v[34:35], v[36:37]
	v_pk_mul_f32 v[66:67], v[38:39], v[38:39]
	v_pk_fma_f32 v[42:43], v[52:53], v[52:53], v[42:43]
	v_pk_add_f32 v[32:33], v[32:33], v[34:35]
	v_mov_b32_e32 v34, v52
	v_mov_b32_e32 v35, v62
	v_mov_b32_e32 v36, v54
	v_mov_b32_e32 v37, v64
	v_pk_add_f32 v[42:43], v[42:43], v[42:43] op_sel_hi:[0,1]
	v_cmp_lt_i32_e32 vcc, v248, v243
	v_pk_add_f32 v[34:35], v[34:35], v[36:37]
	v_pk_mov_b32 v[36:37], v[52:53], v[66:67] op_sel:[1,0]
	v_pk_mov_b32 v[38:39], v[54:55], v[68:69] op_sel:[1,0]
	v_cndmask_b32_e32 v42, v241, v248, vcc
	v_pk_add_f32 v[40:41], v[70:71], v[40:41]
	v_pk_add_f32 v[44:45], v[44:45], v[46:47]
	v_pk_add_f32 v[36:37], v[36:37], v[38:39]
	v_lshlrev_b32_e32 v63, 2, v42
	v_pk_add_f32 v[40:41], v[40:41], v[44:45]
	v_mov_b32_e32 v42, v153
	v_pk_add_f32 v[34:35], v[34:35], v[36:37]
	v_pk_add_f32 v[40:41], v[40:41], v[42:43]
	v_pk_add_f32 v[32:33], v[32:33], v[34:35]
	v_cmp_lt_i32_e32 vcc, v249, v243
	v_pk_add_f32 v[32:33], v[32:33], v[40:41]
	ds_bpermute_b32 v34, v63, v32
	ds_bpermute_b32 v35, v63, v33
	v_cndmask_b32_e32 v36, v241, v249, vcc
	v_lshlrev_b32_e32 v36, 2, v36
	s_waitcnt lgkmcnt(0)
	v_pk_add_f32 v[32:33], v[32:33], v[34:35]
	ds_bpermute_b32 v34, v36, v32
	ds_bpermute_b32 v35, v36, v33
	s_and_saveexec_b64 s[28:29], s[0:1]
	s_cbranch_execz .LBB0_247
	v_lshlrev_b64 v[36:37], 8, v[48:49]
	s_waitcnt lgkmcnt(0)
	v_pk_add_f32 v[32:33], v[32:33], v[34:35]
	v_lshl_add_u64 v[34:35], s[18:19], 0, v[36:37]
	v_lshl_add_u64 v[34:35], s[72:73], 3, v[34:35]
	global_store_dwordx2 v[34:35], v[32:33], off

; DI unsigned pk2(float a, float b) { f32x2 v = {a, b}; hbf16x2 r = __builtin_convertvector(v, hbf16x2); return __builtin_bit_cast(unsigned, r); }
; __device__ __forceinline__ f32x2 gelu_pk(f32x2 v) {
;     const f32x2 av = __builtin_elementwise_abs(v), d = av * 0.2316418882f + 1.0f;
;     f32x2 t; t.x = __builtin_amdgcn_rcpf(d.x); t.y = __builtin_amdgcn_rcpf(d.y);
;     f32x2 q = t * 0.5307027145f + (-0.7265760135f); q = q * t + 0.7107068705f; q = q * t + (-0.142248368f); q = q * t + 0.127414796f; q = q * t;
;     const f32x2 s = (v * v) * (-0.72134752044f);
;     f32x2 e; e.x = __builtin_amdgcn_exp2f(s.x); e.y = __builtin_amdgcn_exp2f(s.y);
;     const f32x2 m = v * (q * e), r = v - m;
;     f32x2 o; o.x = v.x < 0.f ? m.x : r.x; o.y = v.y < 0.f ? m.y : r.y; return o;
;     DI void operator()(const f32x4 (&acc)[2][2][4][2], const Unit& u, int wr, int wc, int fr, int fq) const {
;     ...
;                 const int r = u.pm * BM + ai * HALF + wr * 64 + m * 16 + fr; float s = 0.f, q = 0.f; const float rs = RS[r];
; #pragma unroll
;                 for (int bj = 0; bj < 2; ++bj) { const f32x4 a0 = acc[ai][bj][m][0] * rs, a1 = acc[ai][bj][m][1] * rs;
;                     const f32x2 g0 = gelu_pk((f32x2){a0[0], a0[1]}), g1 = gelu_pk((f32x2){a0[2], a0[3]}), g2 = gelu_pk((f32x2){a1[0], a1[1]}), g3 = gelu_pk((f32x2){a1[2], a1[3]});
;                     s += ((g0.x + g0.y) + (g1.x + g1.y)) + ((g2.x + g2.y) + (g3.x + g3.y));
;                     q += ((g0.x * g0.x + g0.y * g0.y) + (g1.x * g1.x + g1.y * g1.y)) + ((g2.x * g2.x + g2.y * g2.y) + (g3.x * g3.x + g3.y * g3.y));
;                     u32x4 w; w.x = pk2(g0.x, g0.y); w.y = pk2(g1.x, g1.y); w.z = pk2(g2.x, g2.y); w.w = pk2(g3.x, g3.y);
;                     *(u32x4*)(base + (size_t)r * 2048 + colt + bj * HALF) = w; }
.LBB0_248:
	v_add_u32_e32 v32, 0xa0, v138
	v_ashrrev_i32_e32 v33, 31, v32
	s_waitcnt lgkmcnt(0)
	v_lshl_add_u64 v[34:35], v[32:33], 2, s[14:15]
	v_mov_b64_e32 v[36:37], s[80:81]
	v_lshlrev_b64 v[34:35], 12, v[32:33]
	v_lshl_add_u64 v[34:35], v[140:141], 0, v[34:35]
	v_mov_b32_e32 v38, v205
	v_pk_mul_f32 v[28:29], v[28:29], v[38:39] op_sel_hi:[1,0]
	v_pk_mul_f32 v[30:31], v[30:31], v[38:39] op_sel_hi:[1,0]
	v_pk_mul_f32 v[26:27], v[26:27], v[38:39] op_sel_hi:[1,0]
	v_pk_mul_f32 v[40:41], v[24:25], v[38:39] op_sel_hi:[1,0]
	v_pk_mul_f32 v[44:45], v[16:17], v[38:39] op_sel_hi:[1,0]
	v_and_b32_e32 v17, 0x7fffffff, v29
	v_and_b32_e32 v16, 0x7fffffff, v28
	v_pk_mul_f32 v[22:23], v[22:23], v[38:39] op_sel_hi:[1,0]
	v_pk_mul_f32 v[20:21], v[20:21], v[38:39] op_sel_hi:[1,0]
	v_pk_mul_f32 v[42:43], v[18:19], v[38:39] op_sel_hi:[1,0]
	v_and_b32_e32 v39, 0x7fffffff, v31
	v_and_b32_e32 v38, 0x7fffffff, v30
	v_and_b32_e32 v47, 0x7fffffff, v41
	v_and_b32_e32 v46, 0x7fffffff, v40
	v_and_b32_e32 v53, 0x7fffffff, v27
	v_and_b32_e32 v52, 0x7fffffff, v26
	v_pk_fma_f32 v[16:17], v[16:17], s[76:77], 1.0 op_sel_hi:[1,0,0]
	v_pk_fma_f32 v[38:39], v[38:39], s[76:77], 1.0 op_sel_hi:[1,0,0]
	v_pk_fma_f32 v[46:47], v[46:47], s[76:77], 1.0 op_sel_hi:[1,0,0]
	v_pk_fma_f32 v[52:53], v[52:53], s[76:77], 1.0 op_sel_hi:[1,0,0]
	v_rcp_f32_e32 v16, v16
	v_rcp_f32_e32 v17, v17
	v_rcp_f32_e32 v38, v38
	v_rcp_f32_e32 v39, v39
	v_rcp_f32_e32 v46, v46
	v_rcp_f32_e32 v47, v47
	v_rcp_f32_e32 v52, v52
	v_rcp_f32_e32 v53, v53
	v_pk_mul_f32 v[24:25], v[28:29], v[28:29]
	v_pk_mul_f32 v[18:19], v[30:31], v[30:31]
	v_pk_mul_f32 v[48:49], v[26:27], v[26:27]
	v_pk_mul_f32 v[50:51], v[40:41], v[40:41]
	v_pk_mul_f32 v[24:25], v[24:25], s[52:53] op_sel_hi:[1,0]
	v_pk_fma_f32 v[60:61], v[16:17], s[78:79], v[36:37] op_sel_hi:[1,0,0]
	v_pk_mul_f32 v[18:19], v[18:19], s[52:53] op_sel_hi:[1,0]
	v_pk_mul_f32 v[50:51], v[50:51], s[52:53] op_sel_hi:[1,0]
	v_pk_mul_f32 v[48:49], v[48:49], s[52:53] op_sel_hi:[1,0]
	v_exp_f32_e32 v24, v24
	v_exp_f32_e32 v25, v25
	v_pk_fma_f32 v[62:63], v[38:39], s[78:79], v[36:37] op_sel_hi:[1,0,0]
	v_pk_fma_f32 v[64:65], v[46:47], s[78:79], v[36:37] op_sel_hi:[1,0,0]
	v_pk_fma_f32 v[66:67], v[52:53], s[78:79], v[36:37] op_sel_hi:[1,0,0]
	v_pk_fma_f32 v[60:61], v[16:17], v[60:61], s[96:97] op_sel_hi:[1,1,0]
	v_exp_f32_e32 v18, v18
	v_exp_f32_e32 v19, v19
	v_exp_f32_e32 v50, v50
	v_exp_f32_e32 v51, v51
	v_exp_f32_e32 v48, v48
	v_exp_f32_e32 v49, v49
	v_pk_fma_f32 v[62:63], v[38:39], v[62:63], s[96:97] op_sel_hi:[1,1,0]
	v_pk_fma_f32 v[64:65], v[46:47], v[64:65], s[96:97] op_sel_hi:[1,1,0]
	v_pk_fma_f32 v[66:67], v[52:53], v[66:67], s[96:97] op_sel_hi:[1,1,0]
	v_pk_fma_f32 v[60:61], v[16:17], v[60:61], s[48:49] op_sel_hi:[1,1,0]
	v_pk_fma_f32 v[62:63], v[38:39], v[62:63], s[48:49] op_sel_hi:[1,1,0]
	v_pk_fma_f32 v[64:65], v[46:47], v[64:65], s[48:49] op_sel_hi:[1,1,0]
	v_pk_fma_f32 v[66:67], v[52:53], v[66:67], s[48:49] op_sel_hi:[1,1,0]
	v_pk_fma_f32 v[60:61], v[16:17], v[60:61], s[50:51] op_sel_hi:[1,1,0]
	v_pk_fma_f32 v[62:63], v[38:39], v[62:63], s[50:51] op_sel_hi:[1,1,0]
	v_pk_fma_f32 v[64:65], v[46:47], v[64:65], s[50:51] op_sel_hi:[1,1,0]
	v_pk_fma_f32 v[66:67], v[52:53], v[66:67], s[50:51] op_sel_hi:[1,1,0]
	v_pk_mul_f32 v[16:17], v[16:17], v[60:61]
	v_pk_mul_f32 v[38:39], v[38:39], v[62:63]
	v_pk_mul_f32 v[46:47], v[46:47], v[64:65]
	v_pk_mul_f32 v[52:53], v[52:53], v[66:67]
	v_pk_mul_f32 v[16:17], v[24:25], v[16:17]
	v_and_b32_e32 v55, 0x7fffffff, v21
	v_and_b32_e32 v54, 0x7fffffff, v20
	v_pk_mul_f32 v[18:19], v[18:19], v[38:39]
	v_pk_mul_f32 v[24:25], v[50:51], v[46:47]
	v_pk_mul_f32 v[38:39], v[48:49], v[52:53]
	v_pk_mul_f32 v[46:47], v[28:29], v[16:17]
	v_pk_fma_f32 v[48:49], v[28:29], v[16:17], v[28:29] neg_lo:[1,0,0] neg_hi:[1,0,0]
	v_and_b32_e32 v17, 0x7fffffff, v23
	v_and_b32_e32 v16, 0x7fffffff, v22
	v_pk_fma_f32 v[54:55], v[54:55], s[76:77], 1.0 op_sel_hi:[1,0,0]
	v_pk_fma_f32 v[16:17], v[16:17], s[76:77], 1.0 op_sel_hi:[1,0,0]
	v_rcp_f32_e32 v54, v54
	v_rcp_f32_e32 v55, v55
	v_rcp_f32_e32 v16, v16
	v_rcp_f32_e32 v17, v17
	v_pk_mul_f32 v[56:57], v[22:23], v[22:23]
	v_pk_mul_f32 v[58:59], v[20:21], v[20:21]
	v_pk_fma_f32 v[68:69], v[54:55], s[78:79], v[36:37] op_sel_hi:[1,0,0]
	v_pk_mul_f32 v[58:59], v[58:59], s[52:53] op_sel_hi:[1,0]
	v_pk_mul_f32 v[60:61], v[40:41], v[24:25]
	v_pk_fma_f32 v[62:63], v[40:41], v[24:25], v[40:41] neg_lo:[1,0,0] neg_hi:[1,0,0]
	v_pk_fma_f32 v[24:25], v[16:17], s[78:79], v[36:37] op_sel_hi:[1,0,0]
	v_pk_mul_f32 v[56:57], v[56:57], s[52:53] op_sel_hi:[1,0]
	v_exp_f32_e32 v58, v58
	v_pk_fma_f32 v[68:69], v[54:55], v[68:69], s[96:97] op_sel_hi:[1,1,0]
	v_exp_f32_e32 v59, v59
	v_pk_fma_f32 v[24:25], v[16:17], v[24:25], s[96:97] op_sel_hi:[1,1,0]
	v_exp_f32_e32 v56, v56
	v_exp_f32_e32 v57, v57
	v_pk_fma_f32 v[68:69], v[54:55], v[68:69], s[48:49] op_sel_hi:[1,1,0]
	v_pk_fma_f32 v[24:25], v[16:17], v[24:25], s[48:49] op_sel_hi:[1,1,0]
	v_pk_fma_f32 v[68:69], v[54:55], v[68:69], s[50:51] op_sel_hi:[1,1,0]
	v_pk_fma_f32 v[24:25], v[16:17], v[24:25], s[50:51] op_sel_hi:[1,1,0]
	v_pk_mul_f32 v[54:55], v[54:55], v[68:69]
	v_pk_mul_f32 v[16:17], v[16:17], v[24:25]
	v_pk_mul_f32 v[50:51], v[30:31], v[18:19]
	v_pk_fma_f32 v[52:53], v[30:31], v[18:19], v[30:31] neg_lo:[1,0,0] neg_hi:[1,0,0]
	v_pk_mul_f32 v[18:19], v[58:59], v[54:55]
	v_pk_mul_f32 v[16:17], v[56:57], v[16:17]
	v_cmp_gt_f32_e32 vcc, 0, v28
	v_pk_mul_f32 v[54:55], v[20:21], v[18:19]
	v_pk_fma_f32 v[18:19], v[20:21], v[18:19], v[20:21] neg_lo:[1,0,0] neg_hi:[1,0,0]
	v_pk_mul_f32 v[56:57], v[22:23], v[16:17]
	v_pk_fma_f32 v[58:59], v[22:23], v[16:17], v[22:23] neg_lo:[1,0,0] neg_hi:[1,0,0]
; DI unsigned pk2(float a, float b) { f32x2 v = {a, b}; hbf16x2 r = __builtin_convertvector(v, hbf16x2); return __builtin_bit_cast(unsigned, r); }
; __device__ __forceinline__ f32x2 gelu_pk(f32x2 v) {
;     const f32x2 av = __builtin_elementwise_abs(v), d = av * 0.2316418882f + 1.0f;
;     f32x2 t; t.x = __builtin_amdgcn_rcpf(d.x); t.y = __builtin_amdgcn_rcpf(d.y);
;     f32x2 q = t * 0.5307027145f + (-0.7265760135f); q = q * t + 0.7107068705f; q = q * t + (-0.142248368f); q = q * t + 0.127414796f; q = q * t;
;     const f32x2 s = (v * v) * (-0.72134752044f);
;     f32x2 e; e.x = __builtin_amdgcn_exp2f(s.x); e.y = __builtin_amdgcn_exp2f(s.y);
;     const f32x2 m = v * (q * e), r = v - m;
;     f32x2 o; o.x = v.x < 0.f ? m.x : r.x; o.y = v.y < 0.f ? m.y : r.y; return o;
;     DI void operator()(const f32x4 (&acc)[2][2][4][2], const Unit& u, int wr, int wc, int fr, int fq) const {
;     ...
;                 for (int bj = 0; bj < 2; ++bj) { const f32x4 a0 = acc[ai][bj][m][0] * rs, a1 = acc[ai][bj][m][1] * rs;
;                     const f32x2 g0 = gelu_pk((f32x2){a0[0], a0[1]}), g1 = gelu_pk((f32x2){a0[2], a0[3]}), g2 = gelu_pk((f32x2){a1[0], a1[1]}), g3 = gelu_pk((f32x2){a1[2], a1[3]});
;                     s += ((g0.x + g0.y) + (g1.x + g1.y)) + ((g2.x + g2.y) + (g3.x + g3.y));
;                     q += ((g0.x * g0.x + g0.y * g0.y) + (g1.x * g1.x + g1.y * g1.y)) + ((g2.x * g2.x + g2.y * g2.y) + (g3.x * g3.x + g3.y * g3.y));
;                     u32x4 w; w.x = pk2(g0.x, g0.y); w.y = pk2(g1.x, g1.y); w.z = pk2(g2.x, g2.y); w.w = pk2(g3.x, g3.y);
;                     *(u32x4*)(base + (size_t)r * 2048 + colt + bj * HALF) = w; }
;                 if (isv) { s += __shfl_xor(s, 16); s += __shfl_xor(s, 32); q += __shfl_xor(q, 16); q += __shfl_xor(q, 32);
;                     if (fq == 0) *(f32x2*)(STATS + ((size_t)r * 32 + (pn - 8) * 4 + wc) * 2) = (f32x2){s, q}; }
	v_cndmask_b32_e32 v16, v48, v46, vcc
	v_cmp_gt_f32_e32 vcc, 0, v20
	v_pk_mul_f32 v[64:65], v[26:27], v[38:39]
	v_pk_fma_f32 v[38:39], v[26:27], v[38:39], v[26:27] neg_lo:[1,0,0] neg_hi:[1,0,0]
	v_cndmask_b32_e32 v17, v18, v54, vcc
	v_cmp_gt_f32_e32 vcc, 0, v29
	v_and_b32_e32 v48, 0x7fffffff, v42
	s_nop 0
	v_cndmask_b32_e32 v24, v49, v47, vcc
	v_cmp_gt_f32_e32 vcc, 0, v30
	v_and_b32_e32 v49, 0x7fffffff, v43
	v_pk_fma_f32 v[48:49], v[48:49], s[76:77], 1.0 op_sel_hi:[1,0,0]
	v_cndmask_b32_e32 v18, v52, v50, vcc
	v_cmp_gt_f32_e32 vcc, 0, v21
	v_rcp_f32_e32 v48, v48
	v_rcp_f32_e32 v49, v49
	v_cndmask_b32_e32 v19, v19, v55, vcc
	v_cmp_gt_f32_e32 vcc, 0, v31
	s_nop 1
	v_cndmask_b32_e32 v28, v53, v51, vcc
	v_cmp_gt_f32_e32 vcc, 0, v40
	v_and_b32_e32 v40, 0x7fffffff, v44
	s_nop 0
	v_cndmask_b32_e32 v20, v62, v60, vcc
	v_cmp_gt_f32_e32 vcc, 0, v22
	s_nop 1
	v_cndmask_b32_e32 v21, v58, v56, vcc
	v_cmp_gt_f32_e32 vcc, 0, v41
	v_and_b32_e32 v41, 0x7fffffff, v45
	v_pk_fma_f32 v[40:41], v[40:41], s[76:77], 1.0 op_sel_hi:[1,0,0]
	v_cndmask_b32_e32 v30, v63, v61, vcc
	v_cmp_gt_f32_e32 vcc, 0, v26
	v_rcp_f32_e32 v46, v40
	v_rcp_f32_e32 v47, v41
	v_cndmask_b32_e32 v22, v38, v64, vcc
	v_cmp_gt_f32_e32 vcc, 0, v23
	v_cvt_pk_bf16_f32 v38, v16, v24
	v_cvt_pk_bf16_f32 v40, v20, v30
	v_cndmask_b32_e32 v23, v59, v57, vcc
	v_cmp_gt_f32_e32 vcc, 0, v27
	s_nop 1
	v_cndmask_b32_e32 v26, v39, v65, vcc
	v_cvt_pk_bf16_f32 v39, v18, v28
	v_cvt_pk_bf16_f32 v41, v22, v26
	global_store_dwordx4 v[34:35], v[38:41], off
	v_cmp_gt_f32_e32 vcc, 0, v42
	s_nop 0
	v_pk_fma_f32 v[38:39], v[46:47], s[78:79], v[36:37] op_sel_hi:[1,0,0]
	v_pk_mul_f32 v[40:41], v[42:43], v[42:43]
	v_pk_fma_f32 v[38:39], v[46:47], v[38:39], s[96:97] op_sel_hi:[1,1,0]
	v_pk_fma_f32 v[36:37], v[48:49], s[78:79], v[36:37] op_sel_hi:[1,0,0]
	v_pk_fma_f32 v[38:39], v[46:47], v[38:39], s[48:49] op_sel_hi:[1,1,0]
	v_pk_fma_f32 v[36:37], v[48:49], v[36:37], s[96:97] op_sel_hi:[1,1,0]
	v_pk_fma_f32 v[38:39], v[46:47], v[38:39], s[50:51] op_sel_hi:[1,1,0]
	v_pk_fma_f32 v[36:37], v[48:49], v[36:37], s[48:49] op_sel_hi:[1,1,0]
	v_pk_mul_f32 v[38:39], v[46:47], v[38:39]
	v_pk_mul_f32 v[46:47], v[44:45], v[44:45]
	v_pk_fma_f32 v[36:37], v[48:49], v[36:37], s[50:51] op_sel_hi:[1,1,0]
	v_pk_mul_f32 v[46:47], v[46:47], s[52:53] op_sel_hi:[1,0]
	v_pk_mul_f32 v[36:37], v[48:49], v[36:37]
	v_exp_f32_e32 v46, v46
	v_exp_f32_e32 v47, v47
	s_nop 0
	v_pk_mul_f32 v[38:39], v[46:47], v[38:39]
	s_nop 0
	v_pk_mul_f32 v[46:47], v[44:45], v[38:39]
	v_pk_fma_f32 v[50:51], v[44:45], v[38:39], v[44:45] neg_lo:[1,0,0] neg_hi:[1,0,0]
	v_pk_mul_f32 v[38:39], v[40:41], s[52:53] op_sel_hi:[1,0]
	s_nop 0
	v_exp_f32_e32 v38, v38
	v_exp_f32_e32 v39, v39
	s_nop 0
	v_pk_mul_f32 v[36:37], v[38:39], v[36:37]
	s_nop 0
	v_pk_mul_f32 v[38:39], v[42:43], v[36:37]
	v_pk_fma_f32 v[40:41], v[42:43], v[36:37], v[42:43] neg_lo:[1,0,0] neg_hi:[1,0,0]
	s_nop 0
	v_cndmask_b32_e32 v37, v40, v38, vcc
	v_cmp_gt_f32_e32 vcc, 0, v44
	v_cvt_pk_bf16_f32 v40, v17, v19
	s_nop 0
	v_cndmask_b32_e32 v36, v50, v46, vcc
	v_cmp_gt_f32_e32 vcc, 0, v43
	s_nop 1
	v_cndmask_b32_e32 v39, v41, v39, vcc
	v_cmp_gt_f32_e32 vcc, 0, v45
	v_cvt_pk_bf16_f32 v41, v21, v23
	v_cvt_pk_bf16_f32 v43, v37, v39
	v_cndmask_b32_e32 v38, v51, v47, vcc
	v_cvt_pk_bf16_f32 v42, v36, v38
	s_and_b64 vcc, exec, s[4:5]
	global_store_dwordx4 v[34:35], v[40:43], off offset:256
	s_cbranch_vccnz .LBB0_252
	v_mov_b32_e32 v25, v17
	v_mov_b32_e32 v29, v19
	v_pk_mul_f32 v[40:41], v[24:25], v[24:25]
	v_pk_add_f32 v[54:55], v[16:17], v[24:25]
	v_pk_mul_f32 v[24:25], v[16:17], v[24:25]
	v_mov_b32_e32 v31, v21
	v_pk_mul_f32 v[34:35], v[16:17], v[16:17]
	v_pk_mul_f32 v[44:45], v[28:29], v[28:29]
	v_mov_b32_e32 v55, v25
	v_pk_add_f32 v[24:25], v[18:19], v[28:29]
	v_pk_mul_f32 v[28:29], v[18:19], v[28:29]
	v_mov_b32_e32 v27, v23
	v_pk_mul_f32 v[42:43], v[18:19], v[18:19]
	v_pk_mul_f32 v[48:49], v[30:31], v[30:31]
	v_mov_b32_e32 v25, v29
	v_pk_add_f32 v[28:29], v[20:21], v[30:31]
	v_pk_mul_f32 v[30:31], v[20:21], v[30:31]
	v_pk_mov_b32 v[16:17], v[16:17], v[34:35] op_sel:[1,0]
	v_pk_mov_b32 v[18:19], v[18:19], v[40:41] op_sel:[1,0]
	v_pk_mul_f32 v[46:47], v[20:21], v[20:21]
	v_pk_mul_f32 v[52:53], v[26:27], v[26:27]
	v_mov_b32_e32 v29, v31
	v_pk_add_f32 v[30:31], v[22:23], v[26:27]
	v_pk_mul_f32 v[26:27], v[22:23], v[26:27]
	v_pk_add_f32 v[16:17], v[16:17], v[18:19]
	v_pk_mov_b32 v[18:19], v[20:21], v[42:43] op_sel:[1,0]
	v_pk_mov_b32 v[20:21], v[22:23], v[44:45] op_sel:[1,0]
	v_mov_b32_e32 v31, v27
	v_pk_mul_f32 v[26:27], v[38:39], v[38:39]
	v_pk_add_f32 v[18:19], v[18:19], v[20:21]
	v_pk_mul_f32 v[50:51], v[22:23], v[22:23]
	v_pk_fma_f32 v[26:27], v[36:37], v[36:37], v[26:27]
	v_pk_add_f32 v[16:17], v[16:17], v[18:19]
	v_mov_b32_e32 v18, v36
	v_mov_b32_e32 v19, v46
	v_mov_b32_e32 v20, v38
	v_mov_b32_e32 v21, v48
	v_pk_add_f32 v[26:27], v[26:27], v[26:27] op_sel_hi:[0,1]
	v_cmp_lt_i32_e32 vcc, v248, v243
	v_pk_add_f32 v[18:19], v[18:19], v[20:21]
	v_pk_mov_b32 v[20:21], v[36:37], v[50:51] op_sel:[1,0]
	v_pk_mov_b32 v[22:23], v[38:39], v[52:53] op_sel:[1,0]
	v_cndmask_b32_e32 v26, v241, v248, vcc
	v_pk_add_f32 v[24:25], v[54:55], v[24:25]
	v_pk_add_f32 v[28:29], v[28:29], v[30:31]
	v_pk_add_f32 v[20:21], v[20:21], v[22:23]
	v_lshlrev_b32_e32 v47, 2, v26
	v_pk_add_f32 v[24:25], v[24:25], v[28:29]
	v_mov_b32_e32 v26, v153
	v_pk_add_f32 v[18:19], v[18:19], v[20:21]
	v_pk_add_f32 v[24:25], v[24:25], v[26:27]
	v_pk_add_f32 v[16:17], v[16:17], v[18:19]
	v_cmp_lt_i32_e32 vcc, v249, v243
	v_pk_add_f32 v[16:17], v[16:17], v[24:25]
	ds_bpermute_b32 v18, v47, v16
	ds_bpermute_b32 v19, v47, v17
	v_cndmask_b32_e32 v20, v241, v249, vcc
	v_lshlrev_b32_e32 v20, 2, v20
	s_waitcnt lgkmcnt(0)
	v_pk_add_f32 v[16:17], v[16:17], v[18:19]
	ds_bpermute_b32 v18, v20, v16
	ds_bpermute_b32 v19, v20, v17
	s_and_saveexec_b64 s[28:29], s[0:1]
	s_cbranch_execz .LBB0_251
	v_lshlrev_b64 v[20:21], 8, v[32:33]
	s_waitcnt lgkmcnt(0)
	v_pk_add_f32 v[16:17], v[16:17], v[18:19]
	v_lshl_add_u64 v[18:19], s[18:19], 0, v[20:21]
	v_lshl_add_u64 v[18:19], s[72:73], 3, v[18:19]
	global_store_dwordx2 v[18:19], v[16:17], off

; DI unsigned pk2(float a, float b) { f32x2 v = {a, b}; hbf16x2 r = __builtin_convertvector(v, hbf16x2); return __builtin_bit_cast(unsigned, r); }
; __device__ __forceinline__ f32x2 gelu_pk(f32x2 v) {
;     const f32x2 av = __builtin_elementwise_abs(v), d = av * 0.2316418882f + 1.0f;
;     f32x2 t; t.x = __builtin_amdgcn_rcpf(d.x); t.y = __builtin_amdgcn_rcpf(d.y);
;     f32x2 q = t * 0.5307027145f + (-0.7265760135f); q = q * t + 0.7107068705f; q = q * t + (-0.142248368f); q = q * t + 0.127414796f; q = q * t;
;     const f32x2 s = (v * v) * (-0.72134752044f);
;     f32x2 e; e.x = __builtin_amdgcn_exp2f(s.x); e.y = __builtin_amdgcn_exp2f(s.y);
;     const f32x2 m = v * (q * e), r = v - m;
;     f32x2 o; o.x = v.x < 0.f ? m.x : r.x; o.y = v.y < 0.f ? m.y : r.y; return o;
;     DI void operator()(const f32x4 (&acc)[2][2][4][2], const Unit& u, int wr, int wc, int fr, int fq) const {
;     ...
;                 const int r = u.pm * BM + ai * HALF + wr * 64 + m * 16 + fr; float s = 0.f, q = 0.f; const float rs = RS[r];
; #pragma unroll
;                 for (int bj = 0; bj < 2; ++bj) { const f32x4 a0 = acc[ai][bj][m][0] * rs, a1 = acc[ai][bj][m][1] * rs;
;                     const f32x2 g0 = gelu_pk((f32x2){a0[0], a0[1]}), g1 = gelu_pk((f32x2){a0[2], a0[3]}), g2 = gelu_pk((f32x2){a1[0], a1[1]}), g3 = gelu_pk((f32x2){a1[2], a1[3]});
;                     s += ((g0.x + g0.y) + (g1.x + g1.y)) + ((g2.x + g2.y) + (g3.x + g3.y));
;                     q += ((g0.x * g0.x + g0.y * g0.y) + (g1.x * g1.x + g1.y * g1.y)) + ((g2.x * g2.x + g2.y * g2.y) + (g3.x * g3.x + g3.y * g3.y));
;                     u32x4 w; w.x = pk2(g0.x, g0.y); w.y = pk2(g1.x, g1.y); w.z = pk2(g2.x, g2.y); w.w = pk2(g3.x, g3.y);
;                     *(u32x4*)(base + (size_t)r * 2048 + colt + bj * HALF) = w; }
.LBB0_252:
	v_add_u32_e32 v16, 0xb0, v138
	v_ashrrev_i32_e32 v17, 31, v16
	s_waitcnt lgkmcnt(0)
	v_lshl_add_u64 v[18:19], v[16:17], 2, s[14:15]
	v_mov_b64_e32 v[20:21], s[80:81]
	v_lshlrev_b64 v[18:19], 12, v[16:17]
	v_lshl_add_u64 v[18:19], v[140:141], 0, v[18:19]
	v_mov_b32_e32 v22, v206
	v_pk_mul_f32 v[12:13], v[12:13], v[22:23] op_sel_hi:[1,0]
	v_pk_mul_f32 v[14:15], v[14:15], v[22:23] op_sel_hi:[1,0]
	v_pk_mul_f32 v[10:11], v[10:11], v[22:23] op_sel_hi:[1,0]
	v_pk_mul_f32 v[24:25], v[8:9], v[22:23] op_sel_hi:[1,0]
	v_pk_mul_f32 v[28:29], v[0:1], v[22:23] op_sel_hi:[1,0]
	v_and_b32_e32 v1, 0x7fffffff, v13
	v_and_b32_e32 v0, 0x7fffffff, v12
	v_pk_mul_f32 v[6:7], v[6:7], v[22:23] op_sel_hi:[1,0]
	v_pk_mul_f32 v[4:5], v[4:5], v[22:23] op_sel_hi:[1,0]
	v_pk_mul_f32 v[26:27], v[2:3], v[22:23] op_sel_hi:[1,0]
	v_and_b32_e32 v23, 0x7fffffff, v15
	v_and_b32_e32 v22, 0x7fffffff, v14
	v_and_b32_e32 v31, 0x7fffffff, v25
	v_and_b32_e32 v30, 0x7fffffff, v24
	v_and_b32_e32 v37, 0x7fffffff, v11
	v_and_b32_e32 v36, 0x7fffffff, v10
	v_pk_fma_f32 v[0:1], v[0:1], s[76:77], 1.0 op_sel_hi:[1,0,0]
	v_pk_fma_f32 v[22:23], v[22:23], s[76:77], 1.0 op_sel_hi:[1,0,0]
	v_pk_fma_f32 v[30:31], v[30:31], s[76:77], 1.0 op_sel_hi:[1,0,0]
	v_pk_fma_f32 v[36:37], v[36:37], s[76:77], 1.0 op_sel_hi:[1,0,0]
	v_rcp_f32_e32 v0, v0
	v_rcp_f32_e32 v1, v1
	v_rcp_f32_e32 v22, v22
	v_rcp_f32_e32 v23, v23
	v_rcp_f32_e32 v30, v30
	v_rcp_f32_e32 v31, v31
	v_rcp_f32_e32 v36, v36
	v_rcp_f32_e32 v37, v37
	v_pk_mul_f32 v[8:9], v[12:13], v[12:13]
	v_pk_mul_f32 v[2:3], v[14:15], v[14:15]
	v_pk_mul_f32 v[32:33], v[10:11], v[10:11]
	v_pk_mul_f32 v[34:35], v[24:25], v[24:25]
	v_pk_mul_f32 v[8:9], v[8:9], s[52:53] op_sel_hi:[1,0]
	v_pk_fma_f32 v[44:45], v[0:1], s[78:79], v[20:21] op_sel_hi:[1,0,0]
	v_pk_mul_f32 v[2:3], v[2:3], s[52:53] op_sel_hi:[1,0]
	v_pk_mul_f32 v[34:35], v[34:35], s[52:53] op_sel_hi:[1,0]
	v_pk_mul_f32 v[32:33], v[32:33], s[52:53] op_sel_hi:[1,0]
	v_exp_f32_e32 v8, v8
	v_exp_f32_e32 v9, v9
	v_pk_fma_f32 v[46:47], v[22:23], s[78:79], v[20:21] op_sel_hi:[1,0,0]
	v_pk_fma_f32 v[48:49], v[30:31], s[78:79], v[20:21] op_sel_hi:[1,0,0]
	v_pk_fma_f32 v[50:51], v[36:37], s[78:79], v[20:21] op_sel_hi:[1,0,0]
	v_pk_fma_f32 v[44:45], v[0:1], v[44:45], s[96:97] op_sel_hi:[1,1,0]
	v_exp_f32_e32 v2, v2
	v_exp_f32_e32 v3, v3
	v_exp_f32_e32 v34, v34
	v_exp_f32_e32 v35, v35
	v_exp_f32_e32 v32, v32
	v_exp_f32_e32 v33, v33
	v_pk_fma_f32 v[46:47], v[22:23], v[46:47], s[96:97] op_sel_hi:[1,1,0]
	v_pk_fma_f32 v[48:49], v[30:31], v[48:49], s[96:97] op_sel_hi:[1,1,0]
	v_pk_fma_f32 v[50:51], v[36:37], v[50:51], s[96:97] op_sel_hi:[1,1,0]
	v_pk_fma_f32 v[44:45], v[0:1], v[44:45], s[48:49] op_sel_hi:[1,1,0]
	v_pk_fma_f32 v[46:47], v[22:23], v[46:47], s[48:49] op_sel_hi:[1,1,0]
	v_pk_fma_f32 v[48:49], v[30:31], v[48:49], s[48:49] op_sel_hi:[1,1,0]
	v_pk_fma_f32 v[50:51], v[36:37], v[50:51], s[48:49] op_sel_hi:[1,1,0]
	v_pk_fma_f32 v[44:45], v[0:1], v[44:45], s[50:51] op_sel_hi:[1,1,0]
	v_pk_fma_f32 v[46:47], v[22:23], v[46:47], s[50:51] op_sel_hi:[1,1,0]
	v_pk_fma_f32 v[48:49], v[30:31], v[48:49], s[50:51] op_sel_hi:[1,1,0]
	v_pk_fma_f32 v[50:51], v[36:37], v[50:51], s[50:51] op_sel_hi:[1,1,0]
	v_pk_mul_f32 v[0:1], v[0:1], v[44:45]
	v_pk_mul_f32 v[22:23], v[22:23], v[46:47]
	v_pk_mul_f32 v[30:31], v[30:31], v[48:49]
	v_pk_mul_f32 v[36:37], v[36:37], v[50:51]
	v_pk_mul_f32 v[0:1], v[8:9], v[0:1]
	v_and_b32_e32 v39, 0x7fffffff, v5
	v_and_b32_e32 v38, 0x7fffffff, v4
	v_pk_mul_f32 v[2:3], v[2:3], v[22:23]
	v_pk_mul_f32 v[8:9], v[34:35], v[30:31]
	v_pk_mul_f32 v[22:23], v[32:33], v[36:37]
	v_pk_mul_f32 v[30:31], v[12:13], v[0:1]
	v_pk_fma_f32 v[32:33], v[12:13], v[0:1], v[12:13] neg_lo:[1,0,0] neg_hi:[1,0,0]
	v_and_b32_e32 v1, 0x7fffffff, v7
	v_and_b32_e32 v0, 0x7fffffff, v6
	v_pk_fma_f32 v[38:39], v[38:39], s[76:77], 1.0 op_sel_hi:[1,0,0]
	v_pk_fma_f32 v[0:1], v[0:1], s[76:77], 1.0 op_sel_hi:[1,0,0]
	v_rcp_f32_e32 v38, v38
	v_rcp_f32_e32 v39, v39
	v_rcp_f32_e32 v0, v0
	v_rcp_f32_e32 v1, v1
	v_pk_mul_f32 v[40:41], v[6:7], v[6:7]
	v_pk_mul_f32 v[42:43], v[4:5], v[4:5]
	v_pk_fma_f32 v[52:53], v[38:39], s[78:79], v[20:21] op_sel_hi:[1,0,0]
	v_pk_mul_f32 v[42:43], v[42:43], s[52:53] op_sel_hi:[1,0]
	v_pk_mul_f32 v[44:45], v[24:25], v[8:9]
	v_pk_fma_f32 v[46:47], v[24:25], v[8:9], v[24:25] neg_lo:[1,0,0] neg_hi:[1,0,0]
	v_pk_fma_f32 v[8:9], v[0:1], s[78:79], v[20:21] op_sel_hi:[1,0,0]
	v_pk_mul_f32 v[40:41], v[40:41], s[52:53] op_sel_hi:[1,0]
	v_exp_f32_e32 v42, v42
	v_pk_fma_f32 v[52:53], v[38:39], v[52:53], s[96:97] op_sel_hi:[1,1,0]
	v_exp_f32_e32 v43, v43
	v_pk_fma_f32 v[8:9], v[0:1], v[8:9], s[96:97] op_sel_hi:[1,1,0]
	v_exp_f32_e32 v40, v40
	v_exp_f32_e32 v41, v41
	v_pk_fma_f32 v[52:53], v[38:39], v[52:53], s[48:49] op_sel_hi:[1,1,0]
	v_pk_fma_f32 v[8:9], v[0:1], v[8:9], s[48:49] op_sel_hi:[1,1,0]
	v_pk_fma_f32 v[52:53], v[38:39], v[52:53], s[50:51] op_sel_hi:[1,1,0]
	v_pk_fma_f32 v[8:9], v[0:1], v[8:9], s[50:51] op_sel_hi:[1,1,0]
	v_pk_mul_f32 v[38:39], v[38:39], v[52:53]
	v_pk_mul_f32 v[0:1], v[0:1], v[8:9]
	v_pk_mul_f32 v[34:35], v[14:15], v[2:3]
	v_pk_fma_f32 v[36:37], v[14:15], v[2:3], v[14:15] neg_lo:[1,0,0] neg_hi:[1,0,0]
	v_pk_mul_f32 v[2:3], v[42:43], v[38:39]
	v_pk_mul_f32 v[0:1], v[40:41], v[0:1]
	v_cmp_gt_f32_e32 vcc, 0, v12
	v_pk_mul_f32 v[38:39], v[4:5], v[2:3]
	v_pk_fma_f32 v[2:3], v[4:5], v[2:3], v[4:5] neg_lo:[1,0,0] neg_hi:[1,0,0]
	v_pk_mul_f32 v[40:41], v[6:7], v[0:1]
	v_pk_fma_f32 v[42:43], v[6:7], v[0:1], v[6:7] neg_lo:[1,0,0] neg_hi:[1,0,0]
	v_cndmask_b32_e32 v0, v32, v30, vcc
	v_cmp_gt_f32_e32 vcc, 0, v4
	v_pk_mul_f32 v[48:49], v[10:11], v[22:23]
; DI unsigned pk2(float a, float b) { f32x2 v = {a, b}; hbf16x2 r = __builtin_convertvector(v, hbf16x2); return __builtin_bit_cast(unsigned, r); }
; __device__ __forceinline__ f32x2 gelu_pk(f32x2 v) {
;     const f32x2 av = __builtin_elementwise_abs(v), d = av * 0.2316418882f + 1.0f;
;     f32x2 t; t.x = __builtin_amdgcn_rcpf(d.x); t.y = __builtin_amdgcn_rcpf(d.y);
;     f32x2 q = t * 0.5307027145f + (-0.7265760135f); q = q * t + 0.7107068705f; q = q * t + (-0.142248368f); q = q * t + 0.127414796f; q = q * t;
;     const f32x2 s = (v * v) * (-0.72134752044f);
;     f32x2 e; e.x = __builtin_amdgcn_exp2f(s.x); e.y = __builtin_amdgcn_exp2f(s.y);
;     const f32x2 m = v * (q * e), r = v - m;
;     f32x2 o; o.x = v.x < 0.f ? m.x : r.x; o.y = v.y < 0.f ? m.y : r.y; return o;
;     DI void operator()(const f32x4 (&acc)[2][2][4][2], const Unit& u, int wr, int wc, int fr, int fq) const {
;     ...
;                 for (int bj = 0; bj < 2; ++bj) { const f32x4 a0 = acc[ai][bj][m][0] * rs, a1 = acc[ai][bj][m][1] * rs;
;                     const f32x2 g0 = gelu_pk((f32x2){a0[0], a0[1]}), g1 = gelu_pk((f32x2){a0[2], a0[3]}), g2 = gelu_pk((f32x2){a1[0], a1[1]}), g3 = gelu_pk((f32x2){a1[2], a1[3]});
;                     s += ((g0.x + g0.y) + (g1.x + g1.y)) + ((g2.x + g2.y) + (g3.x + g3.y));
;                     q += ((g0.x * g0.x + g0.y * g0.y) + (g1.x * g1.x + g1.y * g1.y)) + ((g2.x * g2.x + g2.y * g2.y) + (g3.x * g3.x + g3.y * g3.y));
;                     u32x4 w; w.x = pk2(g0.x, g0.y); w.y = pk2(g1.x, g1.y); w.z = pk2(g2.x, g2.y); w.w = pk2(g3.x, g3.y);
;                     *(u32x4*)(base + (size_t)r * 2048 + colt + bj * HALF) = w; }
;                 if (isv) { s += __shfl_xor(s, 16); s += __shfl_xor(s, 32); q += __shfl_xor(q, 16); q += __shfl_xor(q, 32);
;                     if (fq == 0) *(f32x2*)(STATS + ((size_t)r * 32 + (pn - 8) * 4 + wc) * 2) = (f32x2){s, q}; }
	v_pk_fma_f32 v[22:23], v[10:11], v[22:23], v[10:11] neg_lo:[1,0,0] neg_hi:[1,0,0]
	v_cndmask_b32_e32 v1, v2, v38, vcc
	v_cmp_gt_f32_e32 vcc, 0, v13
	v_and_b32_e32 v32, 0x7fffffff, v26
	s_nop 0
	v_cndmask_b32_e32 v8, v33, v31, vcc
	v_cmp_gt_f32_e32 vcc, 0, v14
	v_and_b32_e32 v33, 0x7fffffff, v27
	v_pk_fma_f32 v[32:33], v[32:33], s[76:77], 1.0 op_sel_hi:[1,0,0]
	v_cndmask_b32_e32 v2, v36, v34, vcc
	v_cmp_gt_f32_e32 vcc, 0, v5
	v_rcp_f32_e32 v32, v32
	v_rcp_f32_e32 v33, v33
	v_cndmask_b32_e32 v3, v3, v39, vcc
	v_cmp_gt_f32_e32 vcc, 0, v15
	s_nop 1
	v_cndmask_b32_e32 v12, v37, v35, vcc
	v_cmp_gt_f32_e32 vcc, 0, v24
	v_and_b32_e32 v24, 0x7fffffff, v28
	s_nop 0
	v_cndmask_b32_e32 v4, v46, v44, vcc
	v_cmp_gt_f32_e32 vcc, 0, v6
	s_nop 1
	v_cndmask_b32_e32 v5, v42, v40, vcc
	v_cmp_gt_f32_e32 vcc, 0, v25
	v_and_b32_e32 v25, 0x7fffffff, v29
	v_pk_fma_f32 v[24:25], v[24:25], s[76:77], 1.0 op_sel_hi:[1,0,0]
	v_cndmask_b32_e32 v14, v47, v45, vcc
	v_cmp_gt_f32_e32 vcc, 0, v10
	v_rcp_f32_e32 v30, v24
	v_rcp_f32_e32 v31, v25
	v_cndmask_b32_e32 v6, v22, v48, vcc
	v_cmp_gt_f32_e32 vcc, 0, v7
	v_cvt_pk_bf16_f32 v22, v0, v8
	v_cvt_pk_bf16_f32 v24, v4, v14
	v_cndmask_b32_e32 v7, v43, v41, vcc
	v_cmp_gt_f32_e32 vcc, 0, v11
	s_nop 1
	v_cndmask_b32_e32 v10, v23, v49, vcc
	v_cvt_pk_bf16_f32 v23, v2, v12
	v_cvt_pk_bf16_f32 v25, v6, v10
	global_store_dwordx4 v[18:19], v[22:25], off
	v_cmp_gt_f32_e32 vcc, 0, v26
	s_nop 0
	v_pk_fma_f32 v[22:23], v[30:31], s[78:79], v[20:21] op_sel_hi:[1,0,0]
	v_pk_mul_f32 v[24:25], v[26:27], v[26:27]
	v_pk_fma_f32 v[22:23], v[30:31], v[22:23], s[96:97] op_sel_hi:[1,1,0]
	v_pk_fma_f32 v[20:21], v[32:33], s[78:79], v[20:21] op_sel_hi:[1,0,0]
	v_pk_fma_f32 v[22:23], v[30:31], v[22:23], s[48:49] op_sel_hi:[1,1,0]
	v_pk_fma_f32 v[20:21], v[32:33], v[20:21], s[96:97] op_sel_hi:[1,1,0]
	v_pk_fma_f32 v[22:23], v[30:31], v[22:23], s[50:51] op_sel_hi:[1,1,0]
	v_pk_fma_f32 v[20:21], v[32:33], v[20:21], s[48:49] op_sel_hi:[1,1,0]
	v_pk_mul_f32 v[22:23], v[30:31], v[22:23]
	v_pk_mul_f32 v[30:31], v[28:29], v[28:29]
	v_pk_fma_f32 v[20:21], v[32:33], v[20:21], s[50:51] op_sel_hi:[1,1,0]
	v_pk_mul_f32 v[30:31], v[30:31], s[52:53] op_sel_hi:[1,0]
	v_pk_mul_f32 v[20:21], v[32:33], v[20:21]
	v_exp_f32_e32 v30, v30
	v_exp_f32_e32 v31, v31
	s_nop 0
	v_pk_mul_f32 v[22:23], v[30:31], v[22:23]
	s_nop 0
	v_pk_mul_f32 v[30:31], v[28:29], v[22:23]
	v_pk_fma_f32 v[34:35], v[28:29], v[22:23], v[28:29] neg_lo:[1,0,0] neg_hi:[1,0,0]
	v_pk_mul_f32 v[22:23], v[24:25], s[52:53] op_sel_hi:[1,0]
	s_nop 0
	v_exp_f32_e32 v22, v22
	v_exp_f32_e32 v23, v23
	s_nop 0
	v_pk_mul_f32 v[20:21], v[22:23], v[20:21]
	s_nop 0
	v_pk_mul_f32 v[22:23], v[26:27], v[20:21]
	v_pk_fma_f32 v[24:25], v[26:27], v[20:21], v[26:27] neg_lo:[1,0,0] neg_hi:[1,0,0]
	s_nop 0
	v_cndmask_b32_e32 v21, v24, v22, vcc
	v_cmp_gt_f32_e32 vcc, 0, v28
	v_cvt_pk_bf16_f32 v24, v1, v3
	s_nop 0
	v_cndmask_b32_e32 v20, v34, v30, vcc
	v_cmp_gt_f32_e32 vcc, 0, v27
	s_nop 1
	v_cndmask_b32_e32 v23, v25, v23, vcc
	v_cmp_gt_f32_e32 vcc, 0, v29
	v_cvt_pk_bf16_f32 v25, v5, v7
	v_cvt_pk_bf16_f32 v27, v21, v23
	v_cndmask_b32_e32 v22, v35, v31, vcc
	v_cvt_pk_bf16_f32 v26, v20, v22
	s_and_b64 vcc, exec, s[4:5]
	global_store_dwordx4 v[18:19], v[24:27], off offset:256
	s_cbranch_vccnz .LBB0_256
	v_mov_b32_e32 v9, v1
	v_mov_b32_e32 v13, v3
	v_pk_mul_f32 v[24:25], v[8:9], v[8:9]
	v_pk_add_f32 v[38:39], v[0:1], v[8:9]
	v_pk_mul_f32 v[8:9], v[0:1], v[8:9]
	v_mov_b32_e32 v15, v5
	v_pk_mul_f32 v[18:19], v[0:1], v[0:1]
	v_pk_mul_f32 v[28:29], v[12:13], v[12:13]
	v_mov_b32_e32 v39, v9
	v_pk_add_f32 v[8:9], v[2:3], v[12:13]
	v_pk_mul_f32 v[12:13], v[2:3], v[12:13]
	v_mov_b32_e32 v11, v7
	v_pk_mul_f32 v[26:27], v[2:3], v[2:3]
	v_pk_mul_f32 v[32:33], v[14:15], v[14:15]
	v_mov_b32_e32 v9, v13
	v_pk_add_f32 v[12:13], v[4:5], v[14:15]
	v_pk_mul_f32 v[14:15], v[4:5], v[14:15]
	v_pk_mov_b32 v[0:1], v[0:1], v[18:19] op_sel:[1,0]
	v_pk_mov_b32 v[2:3], v[2:3], v[24:25] op_sel:[1,0]
	v_pk_mul_f32 v[30:31], v[4:5], v[4:5]
	v_pk_mul_f32 v[36:37], v[10:11], v[10:11]
	v_mov_b32_e32 v13, v15
	v_pk_add_f32 v[14:15], v[6:7], v[10:11]
	v_pk_mul_f32 v[10:11], v[6:7], v[10:11]
	v_pk_add_f32 v[0:1], v[0:1], v[2:3]
	v_pk_mov_b32 v[2:3], v[4:5], v[26:27] op_sel:[1,0]
	v_pk_mov_b32 v[4:5], v[6:7], v[28:29] op_sel:[1,0]
	v_mov_b32_e32 v15, v11
	v_pk_mul_f32 v[10:11], v[22:23], v[22:23]
	v_pk_add_f32 v[2:3], v[2:3], v[4:5]
	v_pk_mul_f32 v[34:35], v[6:7], v[6:7]
	v_pk_fma_f32 v[10:11], v[20:21], v[20:21], v[10:11]
	v_pk_add_f32 v[0:1], v[0:1], v[2:3]
	v_mov_b32_e32 v2, v20
	v_mov_b32_e32 v3, v30
	v_mov_b32_e32 v4, v22
	v_mov_b32_e32 v5, v32
	v_pk_add_f32 v[10:11], v[10:11], v[10:11] op_sel_hi:[0,1]
	v_cmp_lt_i32_e32 vcc, v248, v243
	v_pk_add_f32 v[2:3], v[2:3], v[4:5]
	v_pk_mov_b32 v[4:5], v[20:21], v[34:35] op_sel:[1,0]
	v_pk_mov_b32 v[6:7], v[22:23], v[36:37] op_sel:[1,0]
	v_cndmask_b32_e32 v10, v241, v248, vcc
	v_pk_add_f32 v[8:9], v[38:39], v[8:9]
	v_pk_add_f32 v[12:13], v[12:13], v[14:15]
	v_pk_add_f32 v[4:5], v[4:5], v[6:7]
	v_lshlrev_b32_e32 v31, 2, v10
	v_pk_add_f32 v[8:9], v[8:9], v[12:13]
	v_mov_b32_e32 v10, v153
	v_pk_add_f32 v[2:3], v[2:3], v[4:5]
	v_pk_add_f32 v[8:9], v[8:9], v[10:11]
	v_pk_add_f32 v[0:1], v[0:1], v[2:3]
	v_cmp_lt_i32_e32 vcc, v249, v243
	v_pk_add_f32 v[0:1], v[0:1], v[8:9]
	ds_bpermute_b32 v2, v31, v0
	ds_bpermute_b32 v3, v31, v1
	v_cndmask_b32_e32 v4, v241, v249, vcc
	v_lshlrev_b32_e32 v4, 2, v4
	s_waitcnt lgkmcnt(0)
	v_pk_add_f32 v[0:1], v[0:1], v[2:3]
	ds_bpermute_b32 v2, v4, v0
	ds_bpermute_b32 v3, v4, v1
	s_and_saveexec_b64 s[4:5], s[0:1]
	s_cbranch_execz .LBB0_255
	v_lshlrev_b64 v[4:5], 8, v[16:17]
	s_waitcnt lgkmcnt(0)
	v_pk_add_f32 v[0:1], v[0:1], v[2:3]
	v_lshl_add_u64 v[2:3], s[18:19], 0, v[4:5]
	v_lshl_add_u64 v[2:3], s[72:73], 3, v[2:3]
	global_store_dwordx2 v[2:3], v[0:1], off

; DI float bflo(unsigned w) { return __uint_as_float(w << 16); }
; DI float bfhi(unsigned w) { return __uint_as_float(w & 0xffff0000u); }
; DI u32x4 pk8(f32x4 a, f32x4 b) { u32x4 w; w.x = pk2(a[0], a[1]); w.y = pk2(a[2], a[3]); w.z = pk2(b[0], b[1]); w.w = pk2(b[2], b[3]); return w; }
;     DI void fused(f32x4 (&acc)[2][2][4][2], const Unit& u, int wr, int wc, int fr, int fq, LAS unsigned char* lds, int wid, int lane) const {
;     ...
; #pragma unroll
;         for (int ai = 0; ai < 2; ++ai)
; #pragma unroll
;             for (int m = 0; m < 4; ++m) {
;                 const int row = ai * HALF + wr * 64 + m * 16 + fr; const size_t goff = (size_t)(u.pm * BM + row) * DM + colb;
;                 const float r1 = R[row].x;
; #pragma unroll
;                 for (int bj = 0; bj < 2; ++bj) {
;                     f32x4 xn[2]; const u32x4 xw = *(const u32x4*)(XB + goff + bj * HALF);
; #pragma unroll
;                     for (int n = 0; n < 2; ++n) { const unsigned w0 = xw[2 * n], w1 = xw[2 * n + 1];
;                         const f32x4 x = {bflo(w0), bfhi(w0), bflo(w1), bfhi(w1)}; xn[n] = x + acc[ai][bj][m][n] * r1; }
;                     if (Yout) { float* y = Yout + goff + bj * HALF; *(f32x4*)y = xn[0]; *(f32x4*)(y + 4) = xn[1]; }
;                     else *(u32x4*)(XB + goff + bj * HALF) = pk8(xn[0], xn[1]);
;                 }
;             }
.LBB0_962:
	s_or_b64 exec, exec, s[4:5]
	s_waitcnt lgkmcnt(0)
	s_barrier
	global_load_dwordx4 v[180:183], v[148:149], off
	global_load_dwordx4 v[184:187], v[148:149], off offset:256
	global_load_dwordx4 v[188:191], v[132:133], off
	global_load_dwordx4 v[192:195], v[132:133], off offset:256
	global_load_dwordx4 v[196:199], v[128:129], off
	global_load_dwordx4 v[200:203], v[128:129], off offset:256
	global_load_dwordx4 v[204:207], v[112:113], off
	global_load_dwordx4 v[208:211], v[112:113], off offset:256
	v_lshl_add_u32 v2, v152, 3, 0
	v_add_u32_e32 v3, 0x4000, v2
	ds_read2_b32 v[0:1], v3 offset1:32
	v_add_u32_e32 v2, 0x4400, v2
	s_waitcnt vmcnt(7)
	v_mov_b32_e32 v16, v180
	v_mov_b32_e32 v17, v181
	v_mov_b32_e32 v18, v182
	v_mov_b32_e32 v19, v183
	v_lshlrev_b32_e32 v32, 16, v16
	v_and_b32_e32 v33, 0xffff0000, v16
	v_lshlrev_b32_e32 v16, 16, v17
	v_and_b32_e32 v17, 0xffff0000, v17
	s_waitcnt lgkmcnt(0)
	v_pk_fma_f32 v[34:35], v[150:151], v[0:1], v[16:17] op_sel_hi:[1,0,1]
	v_pk_fma_f32 v[16:17], v[164:165], v[0:1], v[32:33] op_sel_hi:[1,0,1]
	v_lshlrev_b32_e32 v32, 16, v18
	v_and_b32_e32 v33, 0xffff0000, v18
	v_lshlrev_b32_e32 v18, 16, v19
	v_and_b32_e32 v19, 0xffff0000, v19
	v_pk_fma_f32 v[40:41], v[140:141], v[0:1], v[18:19] op_sel_hi:[1,0,1]
	v_pk_fma_f32 v[18:19], v[142:143], v[0:1], v[32:33] op_sel_hi:[1,0,1]
	v_cvt_pk_bf16_f32 v16, v16, v17
	v_cvt_pk_bf16_f32 v17, v34, v35
	v_cvt_pk_bf16_f32 v18, v18, v19
	v_cvt_pk_bf16_f32 v19, v40, v41
	global_store_dwordx4 v[148:149], v[16:19], off
	global_load_dwordx4 v[180:183], v[84:85], off
	s_waitcnt vmcnt(8)
	v_mov_b32_e32 v16, v184
	v_mov_b32_e32 v17, v185
	v_mov_b32_e32 v18, v186
	v_mov_b32_e32 v19, v187
	v_lshlrev_b32_e32 v32, 16, v16
	v_and_b32_e32 v33, 0xffff0000, v16
	v_lshlrev_b32_e32 v16, 16, v17
	v_and_b32_e32 v17, 0xffff0000, v17
	v_pk_fma_f32 v[34:35], v[136:137], v[0:1], v[16:17] op_sel_hi:[1,0,1]
	v_pk_fma_f32 v[16:17], v[138:139], v[0:1], v[32:33] op_sel_hi:[1,0,1]
	v_lshlrev_b32_e32 v32, 16, v18
	v_and_b32_e32 v33, 0xffff0000, v18
	v_lshlrev_b32_e32 v18, 16, v19
	v_and_b32_e32 v19, 0xffff0000, v19
	v_pk_fma_f32 v[40:41], v[134:135], v[0:1], v[18:19] op_sel_hi:[1,0,1]
	v_pk_fma_f32 v[18:19], v[144:145], v[0:1], v[32:33] op_sel_hi:[1,0,1]
	v_cvt_pk_bf16_f32 v16, v16, v17
	v_cvt_pk_bf16_f32 v17, v34, v35
	v_cvt_pk_bf16_f32 v18, v18, v19
	v_cvt_pk_bf16_f32 v19, v40, v41
	global_store_dwordx4 v[148:149], v[16:19], off offset:256
	global_load_dwordx4 v[184:187], v[84:85], off offset:256
	v_mov_b32_e32 v0, v1
	s_waitcnt vmcnt(9)
	v_mov_b32_e32 v16, v188
	v_mov_b32_e32 v17, v189
	v_mov_b32_e32 v18, v190
	v_mov_b32_e32 v19, v191
	v_lshlrev_b32_e32 v32, 16, v16
	v_and_b32_e32 v33, 0xffff0000, v16
	v_lshlrev_b32_e32 v16, 16, v17
	v_and_b32_e32 v17, 0xffff0000, v17
	v_pk_fma_f32 v[34:35], v[146:147], v[0:1], v[16:17] op_sel_hi:[1,0,1]
	v_pk_fma_f32 v[16:17], v[166:167], v[0:1], v[32:33] op_sel_hi:[1,0,1]
	v_lshlrev_b32_e32 v32, 16, v18
	v_and_b32_e32 v33, 0xffff0000, v18
	v_lshlrev_b32_e32 v18, 16, v19
	v_and_b32_e32 v19, 0xffff0000, v19
	v_pk_fma_f32 v[40:41], v[124:125], v[0:1], v[18:19] op_sel_hi:[1,0,1]
	v_pk_fma_f32 v[18:19], v[126:127], v[0:1], v[32:33] op_sel_hi:[1,0,1]
	v_cvt_pk_bf16_f32 v16, v16, v17
	v_cvt_pk_bf16_f32 v17, v34, v35
	v_cvt_pk_bf16_f32 v18, v18, v19
	v_cvt_pk_bf16_f32 v19, v40, v41
	global_store_dwordx4 v[132:133], v[16:19], off
	global_load_dwordx4 v[188:191], v[76:77], off
	s_waitcnt vmcnt(10)
	v_mov_b32_e32 v16, v192
	v_mov_b32_e32 v17, v193
	v_mov_b32_e32 v18, v194
	v_mov_b32_e32 v19, v195
	v_lshlrev_b32_e32 v32, 16, v16
	v_and_b32_e32 v33, 0xffff0000, v16
	v_lshlrev_b32_e32 v16, 16, v17
	v_and_b32_e32 v17, 0xffff0000, v17
	v_pk_fma_f32 v[34:35], v[120:121], v[0:1], v[16:17] op_sel_hi:[1,0,1]
	v_pk_fma_f32 v[16:17], v[122:123], v[0:1], v[32:33] op_sel_hi:[1,0,1]
	v_lshlrev_b32_e32 v32, 16, v18
	v_and_b32_e32 v33, 0xffff0000, v18
	v_lshlrev_b32_e32 v18, 16, v19
	v_and_b32_e32 v19, 0xffff0000, v19
	v_pk_fma_f32 v[40:41], v[116:117], v[0:1], v[18:19] op_sel_hi:[1,0,1]
	v_pk_fma_f32 v[0:1], v[118:119], v[0:1], v[32:33] op_sel_hi:[1,0,1]
	v_cvt_pk_bf16_f32 v16, v16, v17
	v_cvt_pk_bf16_f32 v17, v34, v35
	v_cvt_pk_bf16_f32 v18, v0, v1
	v_cvt_pk_bf16_f32 v19, v40, v41
	global_store_dwordx4 v[132:133], v[16:19], off offset:256
	global_load_dwordx4 v[192:195], v[76:77], off offset:256
	ds_read2_b32 v[0:1], v3 offset0:64 offset1:96
	s_waitcnt vmcnt(11)
	v_mov_b32_e32 v16, v196
	v_mov_b32_e32 v17, v197
	v_mov_b32_e32 v18, v198
	v_mov_b32_e32 v19, v199
	v_lshlrev_b32_e32 v32, 16, v16
	v_and_b32_e32 v33, 0xffff0000, v16
	v_lshlrev_b32_e32 v16, 16, v17
	v_and_b32_e32 v17, 0xffff0000, v17
	s_waitcnt lgkmcnt(0)
	v_pk_fma_f32 v[34:35], v[130:131], v[0:1], v[16:17] op_sel_hi:[1,0,1]
	v_pk_fma_f32 v[16:17], v[168:169], v[0:1], v[32:33] op_sel_hi:[1,0,1]
	v_lshlrev_b32_e32 v32, 16, v18
	v_and_b32_e32 v33, 0xffff0000, v18
	v_lshlrev_b32_e32 v18, 16, v19
	v_and_b32_e32 v19, 0xffff0000, v19
	v_pk_fma_f32 v[40:41], v[108:109], v[0:1], v[18:19] op_sel_hi:[1,0,1]
	v_pk_fma_f32 v[18:19], v[110:111], v[0:1], v[32:33] op_sel_hi:[1,0,1]
	v_cvt_pk_bf16_f32 v16, v16, v17
	v_cvt_pk_bf16_f32 v17, v34, v35
	v_cvt_pk_bf16_f32 v18, v18, v19
	v_cvt_pk_bf16_f32 v19, v40, v41
	global_store_dwordx4 v[128:129], v[16:19], off
	global_load_dwordx4 v[196:199], v[64:65], off
	s_waitcnt vmcnt(12)
; DI float bflo(unsigned w) { return __uint_as_float(w << 16); }
; DI float bfhi(unsigned w) { return __uint_as_float(w & 0xffff0000u); }
; DI u32x4 pk8(f32x4 a, f32x4 b) { u32x4 w; w.x = pk2(a[0], a[1]); w.y = pk2(a[2], a[3]); w.z = pk2(b[0], b[1]); w.w = pk2(b[2], b[3]); return w; }
;     DI void fused(f32x4 (&acc)[2][2][4][2], const Unit& u, int wr, int wc, int fr, int fq, LAS unsigned char* lds, int wid, int lane) const {
;     ...
; #pragma unroll
;         for (int ai = 0; ai < 2; ++ai)
; #pragma unroll
;             for (int m = 0; m < 4; ++m) {
;                 const int row = ai * HALF + wr * 64 + m * 16 + fr; const size_t goff = (size_t)(u.pm * BM + row) * DM + colb;
;                 const float r1 = R[row].x;
; #pragma unroll
;                 for (int bj = 0; bj < 2; ++bj) {
;                     f32x4 xn[2]; const u32x4 xw = *(const u32x4*)(XB + goff + bj * HALF);
; #pragma unroll
;                     for (int n = 0; n < 2; ++n) { const unsigned w0 = xw[2 * n], w1 = xw[2 * n + 1];
;                         const f32x4 x = {bflo(w0), bfhi(w0), bflo(w1), bfhi(w1)}; xn[n] = x + acc[ai][bj][m][n] * r1; }
;                     if (Yout) { float* y = Yout + goff + bj * HALF; *(f32x4*)y = xn[0]; *(f32x4*)(y + 4) = xn[1]; }
;                     else *(u32x4*)(XB + goff + bj * HALF) = pk8(xn[0], xn[1]);
;                 }
;             }
	v_mov_b32_e32 v16, v200
	v_mov_b32_e32 v17, v201
	v_mov_b32_e32 v18, v202
	v_mov_b32_e32 v19, v203
	v_lshlrev_b32_e32 v32, 16, v16
	v_and_b32_e32 v33, 0xffff0000, v16
	v_lshlrev_b32_e32 v16, 16, v17
	v_and_b32_e32 v17, 0xffff0000, v17
	v_pk_fma_f32 v[34:35], v[104:105], v[0:1], v[16:17] op_sel_hi:[1,0,1]
	v_pk_fma_f32 v[16:17], v[106:107], v[0:1], v[32:33] op_sel_hi:[1,0,1]
	v_lshlrev_b32_e32 v32, 16, v18
	v_and_b32_e32 v33, 0xffff0000, v18
	v_lshlrev_b32_e32 v18, 16, v19
	v_and_b32_e32 v19, 0xffff0000, v19
	v_pk_fma_f32 v[40:41], v[100:101], v[0:1], v[18:19] op_sel_hi:[1,0,1]
	v_pk_fma_f32 v[18:19], v[102:103], v[0:1], v[32:33] op_sel_hi:[1,0,1]
	v_cvt_pk_bf16_f32 v16, v16, v17
	v_cvt_pk_bf16_f32 v17, v34, v35
	v_cvt_pk_bf16_f32 v18, v18, v19
	v_cvt_pk_bf16_f32 v19, v40, v41
	global_store_dwordx4 v[128:129], v[16:19], off offset:256
	global_load_dwordx4 v[200:203], v[64:65], off offset:256
	v_mov_b32_e32 v0, v1
	s_waitcnt vmcnt(13)
	v_mov_b32_e32 v16, v204
	v_mov_b32_e32 v17, v205
	v_mov_b32_e32 v18, v206
	v_mov_b32_e32 v19, v207
	v_lshlrev_b32_e32 v32, 16, v16
	v_and_b32_e32 v33, 0xffff0000, v16
	v_lshlrev_b32_e32 v16, 16, v17
	v_and_b32_e32 v17, 0xffff0000, v17
	v_pk_fma_f32 v[34:35], v[114:115], v[0:1], v[16:17] op_sel_hi:[1,0,1]
	v_pk_fma_f32 v[16:17], v[170:171], v[0:1], v[32:33] op_sel_hi:[1,0,1]
	v_lshlrev_b32_e32 v32, 16, v18
	v_and_b32_e32 v33, 0xffff0000, v18
	v_lshlrev_b32_e32 v18, 16, v19
	v_and_b32_e32 v19, 0xffff0000, v19
	v_pk_fma_f32 v[40:41], v[92:93], v[0:1], v[18:19] op_sel_hi:[1,0,1]
	v_pk_fma_f32 v[18:19], v[94:95], v[0:1], v[32:33] op_sel_hi:[1,0,1]
	v_cvt_pk_bf16_f32 v16, v16, v17
	v_cvt_pk_bf16_f32 v17, v34, v35
	v_cvt_pk_bf16_f32 v18, v18, v19
	v_cvt_pk_bf16_f32 v19, v40, v41
	global_store_dwordx4 v[112:113], v[16:19], off
	global_load_dwordx4 v[204:207], v[20:21], off
	s_waitcnt vmcnt(14)
	v_mov_b32_e32 v16, v208
	v_mov_b32_e32 v17, v209
	v_mov_b32_e32 v18, v210
	v_mov_b32_e32 v19, v211
	v_lshlrev_b32_e32 v32, 16, v16
	v_and_b32_e32 v33, 0xffff0000, v16
	v_lshlrev_b32_e32 v16, 16, v17
	v_and_b32_e32 v17, 0xffff0000, v17
	v_pk_fma_f32 v[34:35], v[88:89], v[0:1], v[16:17] op_sel_hi:[1,0,1]
	v_pk_fma_f32 v[16:17], v[90:91], v[0:1], v[32:33] op_sel_hi:[1,0,1]
	v_lshlrev_b32_e32 v32, 16, v18
	v_and_b32_e32 v33, 0xffff0000, v18
	v_lshlrev_b32_e32 v18, 16, v19
	v_and_b32_e32 v19, 0xffff0000, v19
	v_pk_fma_f32 v[40:41], v[86:87], v[0:1], v[18:19] op_sel_hi:[1,0,1]
	v_pk_fma_f32 v[0:1], v[96:97], v[0:1], v[32:33] op_sel_hi:[1,0,1]
	v_cvt_pk_bf16_f32 v16, v16, v17
	v_cvt_pk_bf16_f32 v17, v34, v35
	v_cvt_pk_bf16_f32 v18, v0, v1
	v_cvt_pk_bf16_f32 v19, v40, v41
	global_store_dwordx4 v[112:113], v[16:19], off offset:256
	global_load_dwordx4 v[208:211], v[20:21], off offset:256
	ds_read2_b32 v[0:1], v2 offset1:32
	s_waitcnt vmcnt(14)
	v_mov_b32_e32 v16, v180
	v_mov_b32_e32 v17, v181
	v_mov_b32_e32 v18, v182
	v_mov_b32_e32 v19, v183
	v_lshlrev_b32_e32 v32, 16, v16
	v_and_b32_e32 v33, 0xffff0000, v16
	v_lshlrev_b32_e32 v16, 16, v17
	v_and_b32_e32 v17, 0xffff0000, v17
	s_waitcnt lgkmcnt(0)
	v_pk_fma_f32 v[34:35], v[98:99], v[0:1], v[16:17] op_sel_hi:[1,0,1]
	v_pk_fma_f32 v[16:17], v[174:175], v[0:1], v[32:33] op_sel_hi:[1,0,1]
	v_lshlrev_b32_e32 v32, 16, v18
	v_and_b32_e32 v33, 0xffff0000, v18
	v_lshlrev_b32_e32 v18, 16, v19
	v_and_b32_e32 v19, 0xffff0000, v19
	v_pk_fma_f32 v[40:41], v[78:79], v[0:1], v[18:19] op_sel_hi:[1,0,1]
	v_pk_fma_f32 v[18:19], v[176:177], v[0:1], v[32:33] op_sel_hi:[1,0,1]
	v_cvt_pk_bf16_f32 v16, v16, v17
	v_cvt_pk_bf16_f32 v17, v34, v35
	v_cvt_pk_bf16_f32 v18, v18, v19
	v_cvt_pk_bf16_f32 v19, v40, v41
	global_store_dwordx4 v[84:85], v[16:19], off
	s_nop 0
	s_waitcnt vmcnt(13)
	v_mov_b32_e32 v16, v184
	v_mov_b32_e32 v17, v185
	v_mov_b32_e32 v18, v186
	v_mov_b32_e32 v19, v187
	v_lshlrev_b32_e32 v32, 16, v16
	v_and_b32_e32 v33, 0xffff0000, v16
	v_lshlrev_b32_e32 v16, 16, v17
	v_and_b32_e32 v17, 0xffff0000, v17
	v_pk_fma_f32 v[34:35], v[72:73], v[0:1], v[16:17] op_sel_hi:[1,0,1]
	v_pk_fma_f32 v[16:17], v[74:75], v[0:1], v[32:33] op_sel_hi:[1,0,1]
	v_lshlrev_b32_e32 v32, 16, v18
	v_and_b32_e32 v33, 0xffff0000, v18
	v_lshlrev_b32_e32 v18, 16, v19
	v_and_b32_e32 v19, 0xffff0000, v19
	v_pk_fma_f32 v[40:41], v[68:69], v[0:1], v[18:19] op_sel_hi:[1,0,1]
	v_pk_fma_f32 v[18:19], v[70:71], v[0:1], v[32:33] op_sel_hi:[1,0,1]
	v_cvt_pk_bf16_f32 v16, v16, v17
	v_cvt_pk_bf16_f32 v17, v34, v35
	v_cvt_pk_bf16_f32 v18, v18, v19
	v_cvt_pk_bf16_f32 v19, v40, v41
	global_store_dwordx4 v[84:85], v[16:19], off offset:256
	s_nop 0
	v_mov_b32_e32 v0, v1
	s_waitcnt vmcnt(12)
; DI float bflo(unsigned w) { return __uint_as_float(w << 16); }
; DI float bfhi(unsigned w) { return __uint_as_float(w & 0xffff0000u); }
; DI u32x4 pk8(f32x4 a, f32x4 b) { u32x4 w; w.x = pk2(a[0], a[1]); w.y = pk2(a[2], a[3]); w.z = pk2(b[0], b[1]); w.w = pk2(b[2], b[3]); return w; }
;     DI void fused(f32x4 (&acc)[2][2][4][2], const Unit& u, int wr, int wc, int fr, int fq, LAS unsigned char* lds, int wid, int lane) const {
;     ...
; #pragma unroll
;         for (int ai = 0; ai < 2; ++ai)
; #pragma unroll
;             for (int m = 0; m < 4; ++m) {
;                 const int row = ai * HALF + wr * 64 + m * 16 + fr; const size_t goff = (size_t)(u.pm * BM + row) * DM + colb;
;                 const float r1 = R[row].x;
; #pragma unroll
;                 for (int bj = 0; bj < 2; ++bj) {
;                     f32x4 xn[2]; const u32x4 xw = *(const u32x4*)(XB + goff + bj * HALF);
; #pragma unroll
;                     for (int n = 0; n < 2; ++n) { const unsigned w0 = xw[2 * n], w1 = xw[2 * n + 1];
;                         const f32x4 x = {bflo(w0), bfhi(w0), bflo(w1), bfhi(w1)}; xn[n] = x + acc[ai][bj][m][n] * r1; }
;                     if (Yout) { float* y = Yout + goff + bj * HALF; *(f32x4*)y = xn[0]; *(f32x4*)(y + 4) = xn[1]; }
;                     else *(u32x4*)(XB + goff + bj * HALF) = pk8(xn[0], xn[1]);
;                 }
;             }
	v_mov_b32_e32 v16, v188
	v_mov_b32_e32 v17, v189
	v_mov_b32_e32 v18, v190
	v_mov_b32_e32 v19, v191
	v_lshlrev_b32_e32 v32, 16, v16
	v_and_b32_e32 v33, 0xffff0000, v16
	v_lshlrev_b32_e32 v16, 16, v17
	v_and_b32_e32 v17, 0xffff0000, v17
	v_pk_fma_f32 v[34:35], v[80:81], v[0:1], v[16:17] op_sel_hi:[1,0,1]
	v_pk_fma_f32 v[16:17], v[82:83], v[0:1], v[32:33] op_sel_hi:[1,0,1]
	v_lshlrev_b32_e32 v32, 16, v18
	v_and_b32_e32 v33, 0xffff0000, v18
	v_lshlrev_b32_e32 v18, 16, v19
	v_and_b32_e32 v19, 0xffff0000, v19
	v_pk_fma_f32 v[40:41], v[60:61], v[0:1], v[18:19] op_sel_hi:[1,0,1]
	v_pk_fma_f32 v[18:19], v[62:63], v[0:1], v[32:33] op_sel_hi:[1,0,1]
	v_cvt_pk_bf16_f32 v16, v16, v17
	v_cvt_pk_bf16_f32 v17, v34, v35
	v_cvt_pk_bf16_f32 v18, v18, v19
	v_cvt_pk_bf16_f32 v19, v40, v41
	global_store_dwordx4 v[76:77], v[16:19], off
	s_nop 0
	s_waitcnt vmcnt(11)
	v_mov_b32_e32 v16, v192
	v_mov_b32_e32 v17, v193
	v_mov_b32_e32 v18, v194
	v_mov_b32_e32 v19, v195
	v_lshlrev_b32_e32 v32, 16, v16
	v_and_b32_e32 v33, 0xffff0000, v16
	v_lshlrev_b32_e32 v16, 16, v17
	v_and_b32_e32 v17, 0xffff0000, v17
	v_pk_fma_f32 v[34:35], v[56:57], v[0:1], v[16:17] op_sel_hi:[1,0,1]
	v_pk_fma_f32 v[16:17], v[58:59], v[0:1], v[32:33] op_sel_hi:[1,0,1]
	v_lshlrev_b32_e32 v32, 16, v18
	v_and_b32_e32 v33, 0xffff0000, v18
	v_lshlrev_b32_e32 v18, 16, v19
	v_and_b32_e32 v19, 0xffff0000, v19
	v_pk_fma_f32 v[40:41], v[52:53], v[0:1], v[18:19] op_sel_hi:[1,0,1]
	v_pk_fma_f32 v[0:1], v[54:55], v[0:1], v[32:33] op_sel_hi:[1,0,1]
	v_cvt_pk_bf16_f32 v16, v16, v17
	v_cvt_pk_bf16_f32 v17, v34, v35
	v_cvt_pk_bf16_f32 v18, v0, v1
	v_cvt_pk_bf16_f32 v19, v40, v41
	global_store_dwordx4 v[76:77], v[16:19], off offset:256
	s_nop 0
	ds_read2_b32 v[0:1], v2 offset0:64 offset1:96
	s_waitcnt vmcnt(10)
	v_mov_b32_e32 v16, v196
	v_mov_b32_e32 v17, v197
	v_mov_b32_e32 v18, v198
	v_mov_b32_e32 v19, v199
	v_lshlrev_b32_e32 v2, 16, v16
	v_and_b32_e32 v3, 0xffff0000, v16
	v_lshlrev_b32_e32 v16, 16, v17
	v_and_b32_e32 v17, 0xffff0000, v17
	s_waitcnt lgkmcnt(0)
	v_pk_fma_f32 v[32:33], v[66:67], v[0:1], v[16:17] op_sel_hi:[1,0,1]
	v_lshlrev_b32_e32 v16, 16, v18
	v_and_b32_e32 v17, 0xffff0000, v18
	v_lshlrev_b32_e32 v18, 16, v19
	v_and_b32_e32 v19, 0xffff0000, v19
	v_pk_fma_f32 v[2:3], v[178:179], v[0:1], v[2:3] op_sel_hi:[1,0,1]
	v_pk_fma_f32 v[28:29], v[28:29], v[0:1], v[18:19] op_sel_hi:[1,0,1]
	v_pk_fma_f32 v[18:19], v[30:31], v[0:1], v[16:17] op_sel_hi:[1,0,1]
	v_cvt_pk_bf16_f32 v16, v2, v3
	v_cvt_pk_bf16_f32 v17, v32, v33
	v_cvt_pk_bf16_f32 v18, v18, v19
	v_cvt_pk_bf16_f32 v19, v28, v29
	global_store_dwordx4 v[64:65], v[16:19], off
	s_nop 0
	s_waitcnt vmcnt(9)
	v_mov_b32_e32 v16, v200
	v_mov_b32_e32 v17, v201
	v_mov_b32_e32 v18, v202
	v_mov_b32_e32 v19, v203
	v_lshlrev_b32_e32 v2, 16, v16
	v_and_b32_e32 v3, 0xffff0000, v16
	v_lshlrev_b32_e32 v16, 16, v17
	v_and_b32_e32 v17, 0xffff0000, v17
	v_pk_fma_f32 v[24:25], v[24:25], v[0:1], v[16:17] op_sel_hi:[1,0,1]
	v_lshlrev_b32_e32 v16, 16, v18
	v_and_b32_e32 v17, 0xffff0000, v18
	v_lshlrev_b32_e32 v18, 16, v19
	v_and_b32_e32 v19, 0xffff0000, v19
	v_pk_fma_f32 v[2:3], v[26:27], v[0:1], v[2:3] op_sel_hi:[1,0,1]
	v_pk_fma_f32 v[22:23], v[22:23], v[0:1], v[18:19] op_sel_hi:[1,0,1]
	v_pk_fma_f32 v[18:19], v[36:37], v[0:1], v[16:17] op_sel_hi:[1,0,1]
	v_cvt_pk_bf16_f32 v16, v2, v3
	v_cvt_pk_bf16_f32 v17, v24, v25
	v_cvt_pk_bf16_f32 v18, v18, v19
	v_cvt_pk_bf16_f32 v19, v22, v23
	global_store_dwordx4 v[64:65], v[16:19], off offset:256
	s_nop 0
	s_waitcnt vmcnt(8)
	v_mov_b32_e32 v16, v204
	v_mov_b32_e32 v17, v205
	v_mov_b32_e32 v18, v206
	v_mov_b32_e32 v19, v207
	v_lshlrev_b32_e32 v2, 16, v16
	v_and_b32_e32 v3, 0xffff0000, v16
	v_mov_b32_e32 v16, v1
	v_lshlrev_b32_e32 v22, 16, v17
	v_and_b32_e32 v23, 0xffff0000, v17
	v_pk_fma_f32 v[0:1], v[48:49], v[16:17], v[2:3] op_sel_hi:[1,0,1]
	v_lshlrev_b32_e32 v2, 16, v18
	v_and_b32_e32 v3, 0xffff0000, v18
	v_lshlrev_b32_e32 v18, 16, v19
	v_and_b32_e32 v19, 0xffff0000, v19
	v_pk_fma_f32 v[22:23], v[38:39], v[16:17], v[22:23] op_sel_hi:[1,0,1]
	v_pk_fma_f32 v[12:13], v[12:13], v[16:17], v[18:19] op_sel_hi:[1,0,1]
	v_pk_fma_f32 v[2:3], v[14:15], v[16:17], v[2:3] op_sel_hi:[1,0,1]
	v_cvt_pk_bf16_f32 v0, v0, v1
	v_cvt_pk_bf16_f32 v1, v22, v23
	v_cvt_pk_bf16_f32 v2, v2, v3
	v_cvt_pk_bf16_f32 v3, v12, v13
	global_store_dwordx4 v[20:21], v[0:3], off
	s_nop 0
	s_waitcnt vmcnt(7)
	v_mov_b32_e32 v0, v208
	v_mov_b32_e32 v1, v209
	v_mov_b32_e32 v2, v210
	v_mov_b32_e32 v3, v211
	v_lshlrev_b32_e32 v12, 16, v0
	v_and_b32_e32 v13, 0xffff0000, v0
	v_lshlrev_b32_e32 v0, 16, v1
	v_and_b32_e32 v1, 0xffff0000, v1
	v_pk_fma_f32 v[10:11], v[10:11], v[16:17], v[0:1] op_sel_hi:[1,0,1]
	v_pk_fma_f32 v[0:1], v[8:9], v[16:17], v[12:13] op_sel_hi:[1,0,1]
	v_lshlrev_b32_e32 v8, 16, v2
	v_and_b32_e32 v9, 0xffff0000, v2
	v_lshlrev_b32_e32 v2, 16, v3
	v_and_b32_e32 v3, 0xffff0000, v3
	v_pk_fma_f32 v[6:7], v[6:7], v[16:17], v[2:3] op_sel_hi:[1,0,1]
	v_pk_fma_f32 v[2:3], v[4:5], v[16:17], v[8:9] op_sel_hi:[1,0,1]
	v_cvt_pk_bf16_f32 v0, v0, v1
	v_cvt_pk_bf16_f32 v1, v10, v11
	v_cvt_pk_bf16_f32 v2, v2, v3
	v_cvt_pk_bf16_f32 v3, v6, v7
	global_store_dwordx4 v[20:21], v[0:3], off offset:256

; #define PG8_STAGE(bufoff, gbase, voff) do { _Pragma("unroll") for (int _i = 0; _i < 2; ++_i) \
;         __builtin_amdgcn_global_load_lds((const unsigned*)((const char*)(gbase) + (voff)[_i]), (PG8_LAS unsigned*)(lds + (bufoff) + ldsw + _i * 8192), 16, 0, 0); } while (0)
; #define PG8_WAIT_V(n) asm volatile("s_waitcnt vmcnt(" #n ")" ::: "memory")
; #define PG8_BAR __builtin_amdgcn_s_barrier()
; template <class Epi, class Sched, bool ALIGN_EPI = false, bool SP2 = false>
; __device__ __forceinline__ void gemm_phase(PG8_LAS unsigned char* lds, const Gemm g, const Sched& S, const Epi& E) {
;     ...
;     for (int i = 0; i < 2; ++i) { int R, C; stage_rc(tid * 16 + i * 8192, R, C); const int Rb = Epi::PERM ? ((R & ~31) + perm32(R & 31)) : R;
;         voffA[i] = (unsigned)(R * K + C) * 2u; voffB[i] = (unsigned)(Rb * K + C) * 2u; }
;     const size_t kstep = (size_t)(BK * 2);
;     const size_t hstep = (size_t)HALF * K * 2;
;     const size_t tstep = 2 * hstep;
;     const unsigned ldsw = (unsigned)wid * 1024u;
;     const int aoff = lds_byte(wr * 64 + fr, fq * 8), boff = lds_byte(wc * 32 + fr, fq * 8);
;     ...
;         PG8_WAIT_V(2); PG8_BAR;
;         PG8_STAGE(PG8_SB(1, 0), cB + kstep, voffB); PG8_STAGE(PG8_SA(1, 0), cA + kstep, voffA); PG8_STAGE(PG8_SB(1, 1), cB + hstep + kstep, voffB);
;         PG8_WAIT_V(6); PG8_BAR;
.LBB0_1048:
	s_lshl_b32 s1, s1, 5
	s_and_b32 s41, s1, 0x60
	s_lshl_b32 s40, s4, 6
	s_lshl_b32 s18, s4, 13
	s_lshl_b32 s1, s41, 7
	s_add_u32 s4, s8, 0x26100000
	s_addc_u32 s5, s9, 0
	s_add_i32 m0, s36, 0x18000
	v_lshl_add_u64 v[6:7], v[6:7], 0, s[74:75]
	s_waitcnt vmcnt(2)
	s_barrier
	global_load_lds_dwordx4 v[6:7], off
	v_lshl_add_u64 v[4:5], v[4:5], 0, s[74:75]
	s_add_i32 m0, s36, 0x1a000
	s_add_i32 s42, s36, 0x8000
	s_add_i32 s43, s36, 0xa000
	global_load_lds_dwordx4 v[4:5], off
	v_lshl_add_u64 v[0:1], v[0:1], 0, s[74:75]
	s_mov_b32 m0, s42
	s_add_u32 s16, s28, 0x80080
	global_load_lds_dwordx4 v[0:1], off
	v_lshl_add_u64 v[0:1], v[2:3], 0, s[74:75]
	s_mov_b32 m0, s43
	s_addc_u32 s17, s29, 0
	global_load_lds_dwordx4 v[0:1], off
	s_add_i32 m0, s36, 0x1c000
	v_lshl_add_u64 v[0:1], s[16:17], 0, v[152:153]
	global_load_lds_dwordx4 v[0:1], off
	v_lshl_add_u64 v[0:1], s[16:17], 0, v[128:129]
	s_add_i32 m0, s36, 0x1e000
	v_bfe_u32 v143, v8, 4, 2
	global_load_lds_dwordx4 v[0:1], off
	v_and_b32_e32 v142, 15, v8
	v_lshlrev_b32_e32 v0, 4, v143
	v_lshlrev_b32_e32 v1, 2, v8
	v_lshl_or_b32 v0, v142, 6, v0
	v_and_b32_e32 v1, 32, v1
	v_bitop3_b32 v2, v0, s18, v1 bitop3:0xde
	v_bitop3_b32 v144, v0, s1, v1 bitop3:0xde
	v_lshlrev_b32_e32 v0, 15, v13
	v_and_b32_e32 v0, 0xffff0000, v0
	v_lshl_add_u32 v0, v12, 12, v0
	v_and_b32_e32 v1, 1, v13
	v_lshl_or_b32 v0, v1, 6, v0
	v_lshl_add_u32 v134, v14, 1, v0
	v_lshlrev_b32_e32 v0, 15, v9
	v_and_b32_e32 v0, 0xffff0000, v0
	s_waitcnt vmcnt(6)
	v_lshl_add_u32 v0, v10, 12, v0
	v_and_b32_e32 v1, 1, v9
	s_cmpk_lt_u32 s0, 0x100
	v_lshl_or_b32 v0, v1, 6, v0
	v_readlane_b32 s0, v253, 33
	s_cselect_b64 s[16:17], -1, 0
	v_mov_b32_e32 v135, v153
	v_lshl_add_u32 v136, v11, 1, v0
	v_mov_b32_e32 v137, v153
	s_mov_b32 s44, 0
	v_add_u32_e32 v145, 0, v2
	v_readlane_b32 s45, v253, 32
	s_mov_b32 s46, s0
	s_barrier
	v_readlane_b32 s1, v253, 34
	s_branch .LBB0_1051
	s_nop 0
	s_nop 0
	s_nop 0
	s_nop 0
	s_nop 0
	s_nop 0
	s_nop 0
	s_nop 0
	s_nop 0
	s_nop 0
	s_nop 0
	s_nop 0
	s_nop 0
	s_nop 0
	s_nop 0
	s_nop 0
	s_nop 0
	s_nop 0
	s_nop 0
	s_nop 0
	s_nop 0
	s_nop 0
	s_nop 0
	s_nop 0
	s_nop 0
	s_nop 0
	s_nop 0
	s_nop 0
	s_nop 0
	s_nop 0
	s_nop 0
	s_nop 0
	s_nop 0
	s_nop 0
	s_nop 0
	s_nop 0
	s_nop 0
	s_nop 0
	s_nop 0
	s_nop 0
	s_nop 0
	s_nop 0
	s_nop 0
	s_nop 0
	s_nop 0
	s_nop 0
	s_nop 0
	s_nop 0
	s_nop 0
	s_nop 0
	s_nop 0
	s_nop 0
	s_nop 0
	s_nop 0
	s_nop 0
	s_nop 0
	s_nop 0
	s_nop 0
	s_nop 0
	s_nop 0
	s_nop 0
